# additionally: f32->bf16 pair packing done with v_cvt_pk_bf16_f32 (already used by the baseline; same round-to-nearest-even) instead of the 6-instruction integer sequence at 146 sites
# speedup vs baseline: 1.0087x; 1.0087x over previous
; DI unsigned pk2(float lo, float hi) { return f2bf(lo) | (f2bf(hi) << 16); }
; #define BIDX() sgpr_opaque((int)__builtin_amdgcn_workgroup_id_x())
; DI const float* modp(const unsigned char* ws, int layer, int who, int idx) { return (const float*)(ws + WS_MOD) + ((size_t)(layer * 9 + who) * 6 + idx) * D; }
; DI void phase_norm(int layer, const float* g, int sidx, bf16_t* dst, bool first) {
;     ...
;     for (int m0 = BIDX() * 8 + wave; m0 < M; m0 += 2 * nw) {
;         const int m1 = m0 + nw; const bool has1 = m1 < M; const int m1c = has1 ? m1 : m0;
;         const float* z0 = zrow_src(zcs, zls, m0); const float* z1 = zrow_src(zcs, zls, m1c);
;         f32x4 v0[4], v1[4]; float ss0 = 0.f, ss1 = 0.f;
; #pragma unroll
;         for (int j = 0; j < 4; ++j) { v0[j] = *(const f32x4*)(z0 + 4 * lane + 256 * j); v1[j] = *(const f32x4*)(z1 + 4 * lane + 256 * j); }
; #pragma unroll
;         for (int j = 0; j < 4; ++j) { ss0 += v0[j][0] * v0[j][0] + v0[j][1] * v0[j][1] + v0[j][2] * v0[j][2] + v0[j][3] * v0[j][3]; ss1 += v1[j][0] * v1[j][0] + v1[j][1] * v1[j][1] + v1[j][2] * v1[j][2] + v1[j][3] * v1[j][3]; }
; #pragma unroll
;         for (int o = 1; o < 64; o <<= 1) { ss0 += __shfl_xor(ss0, o); ss1 += __shfl_xor(ss1, o); }
; #pragma unroll
;         for (int r = 0; r < 2; ++r) {
;             if (r == 1 && !has1) break;
;             const int m = r ? m1 : m0; const int b = m / T, t = m - b * T; const int who = t < LC ? 8 : b;
;             const float* sh = modp(ws, layer, who, sidx); const float* sc = modp(ws, layer, who, sidx + 1);
;             const float rstd = rsqrtf((r ? ss1 : ss0) * (1.f / D) + 1e-6f);
; #pragma unroll
;             for (int j = 0; j < 4; ++j) { const int c = 4 * lane + 256 * j;
;                 const f32x4 gg = *(const f32x4*)(g + c), s1 = *(const f32x4*)(sc + c), s0 = *(const f32x4*)(sh + c);
;                 f32x4 y = (r ? v1[j] : v0[j]) * rstd * gg; y = y * (s1 + 1.f) + s0;
;                 u32x2 w; w.x = pk2(y[0], y[1]); w.y = pk2(y[2], y[3]);
;                 *(u32x2*)(dst + (size_t)m * D + c) = w; }
.LBB0_51:
	s_mov_b32 s2, 0x78787879
	v_mul_hi_i32 v0, v30, s2
	v_lshrrev_b32_e32 v2, 31, v0
	v_ashrrev_i32_e32 v0, 11, v0
	v_add_u32_e32 v5, v0, v2
	s_movk_i32 s2, 0xef00
	v_mad_i32_i24 v0, v5, s2, v30
	s_movk_i32 s2, 0x100
	v_cmp_gt_i32_e64 s[4:5], s2, v0
	s_movk_i32 s2, 0xff
	v_cmp_lt_i32_e32 vcc, s2, v0
	v_mov_b64_e32 v[6:7], s[12:13]
	s_and_saveexec_b64 s[2:3], vcc
	s_xor_b64 s[2:3], exec, s[2:3]
	v_mul_i32_i24_e32 v0, 0xffffef00, v5
	v_lshl_add_u32 v0, v5, 12, v0
	s_movk_i32 s6, 0xff00
	v_add3_u32 v8, v30, v0, s6
	v_mov_b64_e32 v[6:7], s[14:15]
	s_andn2_saveexec_b64 s[2:3], s[2:3]
	v_lshl_add_u32 v8, v5, 8, v0
	s_or_b64 exec, exec, s[2:3]
	v_add_u32_e32 v46, s24, v30
	s_mov_b32 s2, 0x8800
	v_cmp_gt_i32_e32 vcc, s2, v46
	s_mov_b32 s2, 0x78787879
	s_nop 0
	v_cndmask_b32_e32 v2, v30, v46, vcc
	v_mul_hi_i32 v0, v2, s2
	v_lshrrev_b32_e32 v3, 31, v0
	v_ashrrev_i32_e32 v0, 11, v0
	v_add_u32_e32 v0, v0, v3
	s_movk_i32 s2, 0xef00
	v_mad_i32_i24 v9, v0, s2, v2
	s_movk_i32 s2, 0xff
	v_cmp_lt_i32_e64 s[6:7], s2, v9
	v_mov_b64_e32 v[2:3], s[12:13]
	s_and_saveexec_b64 s[2:3], s[6:7]
	s_xor_b64 s[2:3], exec, s[2:3]
	v_lshlrev_b32_e32 v0, 12, v0
	s_movk_i32 s6, 0xff00
	v_add3_u32 v4, v0, v9, s6
	v_mov_b64_e32 v[2:3], s[14:15]
	s_andn2_saveexec_b64 s[2:3], s[2:3]
	v_lshl_add_u32 v4, v0, 8, v9
	s_or_b64 exec, exec, s[2:3]
	v_ashrrev_i32_e32 v9, 31, v8
	v_lshlrev_b64 v[8:9], 12, v[8:9]
	v_lshl_add_u64 v[6:7], v[6:7], 0, v[8:9]
	v_lshlrev_b32_e32 v0, 2, v32
	v_lshl_add_u64 v[6:7], v[6:7], 0, v[0:1]
	global_load_dwordx4 v[56:59], v[6:7], off
	global_load_dwordx4 v[26:29], v[6:7], off offset:1024
	s_waitcnt lgkmcnt(0)
	global_load_dwordx4 v[14:17], v[6:7], off offset:2048
	s_nop 0
	global_load_dwordx4 v[6:9], v[6:7], off offset:3072
	v_cndmask_b32_e64 v5, v5, 8, s[4:5]
	v_add_u32_e32 v5, s25, v5
	v_mul_i32_i24_e32 v10, 6, v5
	v_ashrrev_i32_e32 v11, 31, v10
	v_lshlrev_b64 v[10:11], 12, v[10:11]
	v_lshl_add_u64 v[10:11], s[16:17], 0, v[10:11]
	s_mov_b64 s[2:3], 0x4000
	v_lshl_add_u64 v[48:49], v[10:11], 0, s[2:3]
	s_mov_b64 s[2:3], 0x3000
	v_lshl_add_u64 v[12:13], v[48:49], 0, v[0:1]
	v_lshl_add_u64 v[72:73], v[10:11], 0, s[2:3]
	global_load_dwordx4 v[60:63], v[12:13], off
	global_load_dwordx4 v[64:67], v[34:35], off
	v_lshl_add_u64 v[10:11], v[72:73], 0, v[0:1]
	global_load_dwordx4 v[68:71], v[10:11], off
	s_mov_b32 s2, 0x800000
	v_mov_b32_e32 v41, v1
	s_waitcnt vmcnt(0)
	v_mov_b32_e32 v12, v57
	v_mov_b32_e32 v13, v27
	v_mov_b32_e32 v10, v56
	v_mov_b32_e32 v11, v26
	v_mov_b32_e32 v24, v15
	v_mov_b32_e32 v25, v7
	v_pk_mul_f32 v[12:13], v[12:13], v[12:13]
	v_mov_b32_e32 v18, v58
	v_mov_b32_e32 v19, v28
	v_mov_b32_e32 v22, v14
	v_mov_b32_e32 v23, v6
	v_pk_mul_f32 v[24:25], v[24:25], v[24:25]
	v_pk_fma_f32 v[10:11], v[10:11], v[10:11], v[12:13]
	v_mov_b32_e32 v20, v59
	v_mov_b32_e32 v21, v29
	v_mov_b32_e32 v74, v16
	v_mov_b32_e32 v75, v8
	v_pk_fma_f32 v[12:13], v[22:23], v[22:23], v[24:25]
	v_pk_fma_f32 v[10:11], v[18:19], v[18:19], v[10:11]
	v_mov_b32_e32 v76, v17
	v_mov_b32_e32 v77, v9
	v_pk_fma_f32 v[12:13], v[74:75], v[74:75], v[12:13]
	v_pk_fma_f32 v[10:11], v[20:21], v[20:21], v[10:11]
	v_pk_fma_f32 v[12:13], v[76:77], v[76:77], v[12:13]
	v_add_f32_e32 v5, v10, v11
	v_add_f32_e32 v5, v5, v12
	v_add_f32_e32 v5, v5, v13
	ds_bpermute_b32 v10, v33, v5
	v_pk_add_f32 v[62:63], v[62:63], 1.0 op_sel_hi:[1,0]
	v_pk_add_f32 v[60:61], v[60:61], 1.0 op_sel_hi:[1,0]
	s_waitcnt lgkmcnt(0)
	v_add_f32_e32 v5, v5, v10
	ds_bpermute_b32 v10, v50, v5
	s_waitcnt lgkmcnt(0)
	v_add_f32_e32 v5, v5, v10
	ds_bpermute_b32 v10, v51, v5
	s_waitcnt lgkmcnt(0)
	v_add_f32_e32 v5, v5, v10
	ds_bpermute_b32 v10, v52, v5
	s_waitcnt lgkmcnt(0)
	v_add_f32_e32 v10, v5, v10
	ds_bpermute_b32 v11, v53, v10
	v_ashrrev_i32_e32 v5, 31, v4
	v_lshlrev_b64 v[4:5], 12, v[4:5]
	v_lshl_add_u64 v[2:3], v[2:3], 0, v[4:5]
	v_lshl_add_u64 v[2:3], v[2:3], 0, v[0:1]
	s_waitcnt lgkmcnt(0)
	v_add_f32_e32 v10, v10, v11
	ds_bpermute_b32 v11, v54, v10
	global_load_dwordx4 v[22:25], v[2:3], off
	global_load_dwordx4 v[18:21], v[2:3], off offset:1024
	s_waitcnt lgkmcnt(0)
	v_add_f32_e32 v4, v10, v11
	v_fmamk_f32 v4, v4, 0x3a800000, v183
	v_mul_f32_e32 v5, 0x4b800000, v4
	v_cmp_gt_f32_e64 s[4:5], s2, v4
	s_nop 1
	v_cndmask_b32_e64 v4, v4, v5, s[4:5]
	v_rsq_f32_e32 v31, v4
	global_load_dwordx4 v[10:13], v[2:3], off offset:2048
	s_nop 0
	global_load_dwordx4 v[2:5], v[2:3], off offset:3072
	v_mul_f32_e32 v43, 0x45800000, v31
	v_cndmask_b32_e64 v74, v31, v43, s[4:5]
	v_pk_mul_f32 v[58:59], v[58:59], v[74:75] op_sel_hi:[1,0]
	v_pk_mul_f32 v[56:57], v[56:57], v[74:75] op_sel_hi:[1,0]
	v_pk_mul_f32 v[58:59], v[66:67], v[58:59]
	v_pk_mul_f32 v[56:57], v[64:65], v[56:57]
	v_pk_fma_f32 v[58:59], v[62:63], v[58:59], v[70:71]
	v_pk_fma_f32 v[56:57], v[60:61], v[56:57], v[68:69]
	v_cvt_pk_bf16_f32 v56, v56, v57
	v_cvt_pk_bf16_f32 v57, v58, v59
	global_store_dwordx2 v[38:39], v[56:57], off
	v_lshl_add_u64 v[60:61], v[48:49], 0, v[40:41]
	global_load_dwordx4 v[56:59], v[34:35], off offset:1024
	v_lshl_add_u64 v[64:65], v[72:73], 0, v[40:41]
	global_load_dwordx4 v[60:63], v[60:61], off
	v_pk_mul_f32 v[28:29], v[28:29], v[74:75] op_sel_hi:[1,0]
	global_load_dwordx4 v[64:67], v[64:65], off
	v_pk_mul_f32 v[26:27], v[26:27], v[74:75] op_sel_hi:[1,0]
	v_mov_b32_e32 v43, v1
	v_pk_mul_f32 v[16:17], v[16:17], v[74:75] op_sel_hi:[1,0]
	v_pk_mul_f32 v[14:15], v[14:15], v[74:75] op_sel_hi:[1,0]
	v_pk_mul_f32 v[8:9], v[8:9], v[74:75] op_sel_hi:[1,0]
	v_pk_mul_f32 v[6:7], v[6:7], v[74:75] op_sel_hi:[1,0]
	s_waitcnt vmcnt(2)
	v_pk_mul_f32 v[26:27], v[56:57], v[26:27]
	v_pk_mul_f32 v[28:29], v[58:59], v[28:29]
	s_waitcnt vmcnt(1)
; DI unsigned pk2(float lo, float hi) { return f2bf(lo) | (f2bf(hi) << 16); }
; DI const float* modp(const unsigned char* ws, int layer, int who, int idx) { return (const float*)(ws + WS_MOD) + ((size_t)(layer * 9 + who) * 6 + idx) * D; }
; DI void phase_norm(int layer, const float* g, int sidx, bf16_t* dst, bool first) {
;     ...
;         for (int o = 1; o < 64; o <<= 1) { ss0 += __shfl_xor(ss0, o); ss1 += __shfl_xor(ss1, o); }
; #pragma unroll
;         for (int r = 0; r < 2; ++r) {
;             if (r == 1 && !has1) break;
;             const int m = r ? m1 : m0; const int b = m / T, t = m - b * T; const int who = t < LC ? 8 : b;
;             const float* sh = modp(ws, layer, who, sidx); const float* sc = modp(ws, layer, who, sidx + 1);
;             const float rstd = rsqrtf((r ? ss1 : ss0) * (1.f / D) + 1e-6f);
; #pragma unroll
;             for (int j = 0; j < 4; ++j) { const int c = 4 * lane + 256 * j;
;                 const f32x4 gg = *(const f32x4*)(g + c), s1 = *(const f32x4*)(sc + c), s0 = *(const f32x4*)(sh + c);
;                 f32x4 y = (r ? v1[j] : v0[j]) * rstd * gg; y = y * (s1 + 1.f) + s0;
;                 u32x2 w; w.x = pk2(y[0], y[1]); w.y = pk2(y[2], y[3]);
;                 *(u32x2*)(dst + (size_t)m * D + c) = w; }
	v_pk_add_f32 v[56:57], v[62:63], 1.0 op_sel_hi:[1,0]
	v_pk_add_f32 v[58:59], v[60:61], 1.0 op_sel_hi:[1,0]
	s_waitcnt vmcnt(0)
	v_pk_fma_f32 v[28:29], v[56:57], v[28:29], v[66:67]
	v_pk_fma_f32 v[26:27], v[58:59], v[26:27], v[64:65]
	v_cvt_pk_bf16_f32 v26, v26, v27
	v_cvt_pk_bf16_f32 v27, v28, v29
	global_store_dwordx2 v[38:39], v[26:27], off offset:512
	v_lshl_add_u64 v[56:57], v[48:49], 0, v[42:43]
	global_load_dwordx4 v[26:29], v[34:35], off offset:2048
	v_lshl_add_u64 v[60:61], v[72:73], 0, v[42:43]
	global_load_dwordx4 v[56:59], v[56:57], off
	v_mov_b32_e32 v45, v1
	global_load_dwordx4 v[60:63], v[60:61], off
	s_waitcnt vmcnt(2)
	v_pk_mul_f32 v[14:15], v[26:27], v[14:15]
	v_pk_mul_f32 v[16:17], v[28:29], v[16:17]
	s_waitcnt vmcnt(1)
	v_pk_add_f32 v[26:27], v[58:59], 1.0 op_sel_hi:[1,0]
	v_pk_add_f32 v[28:29], v[56:57], 1.0 op_sel_hi:[1,0]
	s_waitcnt vmcnt(0)
	v_pk_fma_f32 v[16:17], v[26:27], v[16:17], v[62:63]
	v_pk_fma_f32 v[14:15], v[28:29], v[14:15], v[60:61]
	v_cvt_pk_bf16_f32 v14, v14, v15
	v_cvt_pk_bf16_f32 v15, v16, v17
	global_store_dwordx2 v[38:39], v[14:15], off offset:1024
	v_lshl_add_u64 v[14:15], v[48:49], 0, v[44:45]
	global_load_dwordx4 v[26:29], v[34:35], off offset:3072
	global_load_dwordx4 v[56:59], v[14:15], off
	v_lshl_add_u64 v[14:15], v[72:73], 0, v[44:45]
	global_load_dwordx4 v[60:63], v[14:15], off
	v_mul_f32_e32 v14, v23, v23
	v_mul_f32_e32 v15, v19, v19
	v_mul_f32_e32 v16, v11, v11
	v_fmac_f32_e32 v14, v22, v22
	v_fmac_f32_e32 v15, v18, v18
	v_mul_f32_e32 v17, v3, v3
	v_fmac_f32_e32 v16, v10, v10
	v_fmac_f32_e32 v14, v24, v24
	v_fmac_f32_e32 v15, v20, v20
	v_fmac_f32_e32 v17, v2, v2
	v_fmac_f32_e32 v16, v12, v12
	v_fmac_f32_e32 v14, v25, v25
	v_fmac_f32_e32 v15, v21, v21
	v_fmac_f32_e32 v17, v4, v4
	v_fmac_f32_e32 v16, v13, v13
	v_add_f32_e32 v14, v14, v15
	v_fmac_f32_e32 v17, v5, v5
	v_add_f32_e32 v14, v14, v16
	v_add_f32_e32 v14, v14, v17
	ds_bpermute_b32 v15, v33, v14
	s_waitcnt lgkmcnt(0)
	v_add_f32_e32 v14, v14, v15
	ds_bpermute_b32 v15, v50, v14
	s_waitcnt lgkmcnt(0)
	v_add_f32_e32 v14, v14, v15
	ds_bpermute_b32 v15, v51, v14
	s_waitcnt lgkmcnt(0)
	v_add_f32_e32 v14, v14, v15
	ds_bpermute_b32 v15, v52, v14
	s_waitcnt lgkmcnt(0)
	v_add_f32_e32 v14, v14, v15
	ds_bpermute_b32 v15, v53, v14
	s_waitcnt lgkmcnt(0)
	v_add_f32_e32 v14, v14, v15
	ds_bpermute_b32 v15, v54, v14
	s_waitcnt vmcnt(2)
	v_pk_mul_f32 v[6:7], v[6:7], v[26:27]
	v_pk_mul_f32 v[8:9], v[8:9], v[28:29]
	s_waitcnt vmcnt(1)
	v_pk_add_f32 v[16:17], v[58:59], 1.0 op_sel_hi:[1,0]
	v_pk_add_f32 v[26:27], v[56:57], 1.0 op_sel_hi:[1,0]
	s_waitcnt vmcnt(0)
	v_pk_fma_f32 v[8:9], v[8:9], v[16:17], v[62:63]
	v_pk_fma_f32 v[6:7], v[6:7], v[26:27], v[60:61]
	v_cvt_pk_bf16_f32 v6, v6, v7
	v_cvt_pk_bf16_f32 v7, v8, v9
	global_store_dwordx2 v[38:39], v[6:7], off offset:1536
	s_and_saveexec_b64 s[4:5], vcc
	s_cbranch_execz .LBB0_50
; DI unsigned pk2(float lo, float hi) { return f2bf(lo) | (f2bf(hi) << 16); }
; DI const float* modp(const unsigned char* ws, int layer, int who, int idx) { return (const float*)(ws + WS_MOD) + ((size_t)(layer * 9 + who) * 6 + idx) * D; }
; DI void phase_norm(int layer, const float* g, int sidx, bf16_t* dst, bool first) {
;     ...
;         for (int r = 0; r < 2; ++r) {
;             if (r == 1 && !has1) break;
;             const int m = r ? m1 : m0; const int b = m / T, t = m - b * T; const int who = t < LC ? 8 : b;
;             const float* sh = modp(ws, layer, who, sidx); const float* sc = modp(ws, layer, who, sidx + 1);
;             const float rstd = rsqrtf((r ? ss1 : ss0) * (1.f / D) + 1e-6f);
; #pragma unroll
;             for (int j = 0; j < 4; ++j) { const int c = 4 * lane + 256 * j;
;                 const f32x4 gg = *(const f32x4*)(g + c), s1 = *(const f32x4*)(sc + c), s0 = *(const f32x4*)(sh + c);
;                 f32x4 y = (r ? v1[j] : v0[j]) * rstd * gg; y = y * (s1 + 1.f) + s0;
;                 u32x2 w; w.x = pk2(y[0], y[1]); w.y = pk2(y[2], y[3]);
;                 *(u32x2*)(dst + (size_t)m * D + c) = w; }
	s_mov_b32 s2, 0x78787879
	v_mul_hi_i32 v6, v46, s2
	v_lshrrev_b32_e32 v7, 31, v6
	v_ashrrev_i32_e32 v6, 11, v6
	v_add_u32_e32 v6, v6, v7
	v_mul_i32_i24_e32 v7, 0xffffef00, v6
	v_add3_u32 v7, s24, v7, v30
	s_movk_i32 s2, 0xff
	v_cmp_lt_i32_e32 vcc, s2, v7
	s_mov_b64 s[2:3], 0x3000
	v_ashrrev_i32_e32 v47, 31, v46
	v_cndmask_b32_e32 v6, 8, v6, vcc
	v_add_u32_e32 v6, s25, v6
	v_mul_i32_i24_e32 v6, 6, v6
	v_ashrrev_i32_e32 v7, 31, v6
	v_lshlrev_b64 v[6:7], 12, v[6:7]
	v_lshl_add_u64 v[6:7], s[16:17], 0, v[6:7]
	v_lshl_add_u64 v[48:49], v[6:7], 0, s[2:3]
	s_mov_b64 s[2:3], 0x4000
	v_lshl_add_u64 v[60:61], v[6:7], 0, s[2:3]
	v_lshl_add_u64 v[16:17], v[60:61], 0, v[0:1]
	global_load_dwordx4 v[6:9], v[34:35], off
	global_load_dwordx4 v[26:29], v[16:17], off
	v_lshl_add_u64 v[16:17], v[48:49], 0, v[0:1]
	global_load_dwordx4 v[56:59], v[16:17], off
	s_waitcnt lgkmcnt(0)
	v_add_f32_e32 v0, v14, v15
	v_fmamk_f32 v0, v0, 0x3a800000, v183
	s_mov_b32 s2, 0x800000
	v_mul_f32_e32 v14, 0x4b800000, v0
	v_cmp_gt_f32_e32 vcc, s2, v0
	s_nop 1
	v_cndmask_b32_e32 v0, v0, v14, vcc
	v_rsq_f32_e32 v0, v0
	v_lshlrev_b64 v[14:15], 11, v[46:47]
	v_lshl_add_u64 v[46:47], v[36:37], 0, v[14:15]
	v_mul_f32_e32 v14, 0x45800000, v0
	v_cndmask_b32_e32 v0, v0, v14, vcc
	v_pk_mul_f32 v[14:15], v[24:25], v[0:1] op_sel_hi:[1,0]
	v_pk_mul_f32 v[16:17], v[22:23], v[0:1] op_sel_hi:[1,0]
	v_lshl_add_u64 v[22:23], v[48:49], 0, v[40:41]
	v_pk_mul_f32 v[20:21], v[20:21], v[0:1] op_sel_hi:[1,0]
	v_pk_mul_f32 v[18:19], v[18:19], v[0:1] op_sel_hi:[1,0]
	v_pk_mul_f32 v[12:13], v[12:13], v[0:1] op_sel_hi:[1,0]
	v_pk_mul_f32 v[10:11], v[10:11], v[0:1] op_sel_hi:[1,0]
	v_pk_mul_f32 v[4:5], v[4:5], v[0:1] op_sel_hi:[1,0]
	v_pk_mul_f32 v[2:3], v[2:3], v[0:1] op_sel_hi:[1,0]
	s_waitcnt vmcnt(2)
	v_pk_mul_f32 v[6:7], v[16:17], v[6:7]
	v_pk_mul_f32 v[8:9], v[14:15], v[8:9]
	s_waitcnt vmcnt(1)
	v_pk_add_f32 v[14:15], v[28:29], 1.0 op_sel_hi:[1,0]
	v_pk_add_f32 v[16:17], v[26:27], 1.0 op_sel_hi:[1,0]
	s_waitcnt vmcnt(0)
	v_pk_fma_f32 v[8:9], v[8:9], v[14:15], v[58:59]
	v_pk_fma_f32 v[6:7], v[6:7], v[16:17], v[56:57]
	v_cvt_pk_bf16_f32 v6, v6, v7
	v_cvt_pk_bf16_f32 v7, v8, v9
	global_store_dwordx2 v[46:47], v[6:7], off
	v_lshl_add_u64 v[14:15], v[60:61], 0, v[40:41]
	global_load_dwordx4 v[6:9], v[34:35], off offset:1024
	s_waitcnt vmcnt(0)
	v_pk_mul_f32 v[6:7], v[18:19], v[6:7]
	global_load_dwordx4 v[14:17], v[14:15], off
	v_pk_mul_f32 v[8:9], v[20:21], v[8:9]
	global_load_dwordx4 v[22:25], v[22:23], off
	v_lshl_add_u64 v[18:19], v[48:49], 0, v[42:43]
	s_waitcnt vmcnt(1)
	v_pk_add_f32 v[16:17], v[16:17], 1.0 op_sel_hi:[1,0]
	v_pk_add_f32 v[14:15], v[14:15], 1.0 op_sel_hi:[1,0]
	s_waitcnt vmcnt(0)
	v_pk_fma_f32 v[8:9], v[8:9], v[16:17], v[24:25]
	v_pk_fma_f32 v[6:7], v[6:7], v[14:15], v[22:23]
	v_cvt_pk_bf16_f32 v6, v6, v7
	v_cvt_pk_bf16_f32 v7, v8, v9
	global_store_dwordx2 v[46:47], v[6:7], off offset:512
	v_lshl_add_u64 v[14:15], v[60:61], 0, v[42:43]
	global_load_dwordx4 v[6:9], v[34:35], off offset:2048
	s_waitcnt vmcnt(0)
	v_pk_mul_f32 v[6:7], v[10:11], v[6:7]
	global_load_dwordx4 v[14:17], v[14:15], off
	v_pk_mul_f32 v[8:9], v[12:13], v[8:9]
	global_load_dwordx4 v[18:21], v[18:19], off
	s_waitcnt vmcnt(1)
	v_pk_add_f32 v[10:11], v[16:17], 1.0 op_sel_hi:[1,0]
	v_pk_add_f32 v[12:13], v[14:15], 1.0 op_sel_hi:[1,0]
	s_waitcnt vmcnt(0)
	v_pk_fma_f32 v[8:9], v[8:9], v[10:11], v[20:21]
	v_pk_fma_f32 v[6:7], v[6:7], v[12:13], v[18:19]
	v_cvt_pk_bf16_f32 v6, v6, v7
	v_cvt_pk_bf16_f32 v7, v8, v9
	global_store_dwordx2 v[46:47], v[6:7], off offset:1024
	v_lshl_add_u64 v[10:11], v[60:61], 0, v[44:45]
	global_load_dwordx4 v[6:9], v[34:35], off offset:3072
	v_lshl_add_u64 v[14:15], v[48:49], 0, v[44:45]
	global_load_dwordx4 v[10:13], v[10:11], off
	s_waitcnt vmcnt(1)
	v_pk_mul_f32 v[2:3], v[2:3], v[6:7]
	global_load_dwordx4 v[14:17], v[14:15], off
	v_pk_mul_f32 v[4:5], v[4:5], v[8:9]
	s_waitcnt vmcnt(1)
	v_pk_add_f32 v[6:7], v[12:13], 1.0 op_sel_hi:[1,0]
	v_pk_add_f32 v[8:9], v[10:11], 1.0 op_sel_hi:[1,0]
	s_waitcnt vmcnt(0)
	v_pk_fma_f32 v[4:5], v[4:5], v[6:7], v[16:17]
	v_pk_fma_f32 v[2:3], v[2:3], v[8:9], v[14:15]
	v_bfe_u32 v0, v2, 16, 1
	v_bfe_u32 v6, v3, 16, 1
	v_add3_u32 v0, v2, v0, s31
	v_add3_u32 v2, v3, v6, s31
	v_lshrrev_b32_e32 v0, 16, v0
	v_and_or_b32 v2, v2, s0, v0
	v_cvt_pk_bf16_f32 v3, v4, v5
	global_store_dwordx2 v[46:47], v[2:3], off offset:1536
	s_branch .LBB0_50

; #define LAS __attribute__((address_space(3)))
; DI unsigned pk2(float lo, float hi) { return f2bf(lo) | (f2bf(hi) << 16); }
; DI int tok_of(int d, int i) { if (i < LC) return d ? (LC - 1 - i) : i; return d ? (LC + SL - 1 - (i - LC)) : i; }
; DI void rwkv_scan_item(int j, int item, LAS unsigned char* lds) {
;     ...
;             const int cp = c - 1;
;             if (cp >= 0 && cp < NC) {
;                 const int r0 = (wave - 6) * 16; const LAS float* yb = ybuf + (cp & 1) * 2048;
; #pragma unroll
;                 for (int i = 0; i < 4; ++i) { const int row = r0 + i * 4 + fq; const size_t mr = (size_t)b * T + tok_of(d, cp * 32 + row);
;                     const f32x4 y4 = *(const LAS f32x4*)(yb + row * 64 + fr * 4); u32x2 w; w.x = pk2(y4[0], y4[1]); w.y = pk2(y4[2], y4[3]);
;                     *(u32x2*)(Y + mr * D + head * 64 + fr * 4) = w; }
;             }
.LBB0_110:
	s_and_b64 vcc, exec, s[6:7]
	s_mov_b64 s[2:3], -1
	s_cbranch_vccz .LBB0_127
	s_and_b64 vcc, exec, s[10:11]
	s_cbranch_vccz .LBB0_115
	s_cmp_lt_i32 s24, 1
	s_cbranch_scc1 .LBB0_114
	s_add_i32 s3, s24, -1
	s_lshl_b32 s2, s3, 5
	s_lshl_b32 s3, s3, 13
	s_and_b32 s3, s3, 0x2000
	v_add_u32_e32 v0, s3, v81
	v_add_u32_e32 v20, v0, v85
	ds_read_b128 v[20:23], v20
	v_add_u32_e32 v2, s2, v80
	s_movk_i32 s3, 0xff
	v_cmp_lt_i32_e32 vcc, s3, v2
	s_waitcnt lgkmcnt(0)
	v_cndmask_b32_e32 v3, v253, v196, vcc
	v_sub_u32_e32 v3, v3, v2
	v_cndmask_b32_e64 v2, v3, v2, s[40:41]
	v_ashrrev_i32_e32 v3, 31, v2
	v_cvt_pk_bf16_f32 v20, v20, v21
	v_lshl_add_u64 v[2:3], s[12:13], 0, v[2:3]
	v_lshlrev_b64 v[2:3], 11, v[2:3]
	v_cvt_pk_bf16_f32 v21, v22, v23
	v_lshl_add_u64 v[2:3], v[44:45], 0, v[2:3]
	global_store_dwordx2 v[2:3], v[20:21], off
	v_add_u32_e32 v20, v0, v87
	ds_read_b128 v[20:23], v20
	v_add_u32_e32 v2, s2, v86
	v_cmp_lt_i32_e32 vcc, s3, v2
	s_waitcnt lgkmcnt(0)
	v_cndmask_b32_e32 v3, v253, v196, vcc
	v_sub_u32_e32 v3, v3, v2
	v_cndmask_b32_e64 v2, v3, v2, s[40:41]
	v_ashrrev_i32_e32 v3, 31, v2
	v_cvt_pk_bf16_f32 v20, v20, v21
	v_lshl_add_u64 v[2:3], s[12:13], 0, v[2:3]
	v_lshlrev_b64 v[2:3], 11, v[2:3]
	v_cvt_pk_bf16_f32 v21, v22, v23
	v_lshl_add_u64 v[2:3], v[44:45], 0, v[2:3]
	global_store_dwordx2 v[2:3], v[20:21], off
	v_add_u32_e32 v20, v0, v89
	ds_read_b128 v[20:23], v20
	v_add_u32_e32 v2, s2, v88
	v_cmp_lt_i32_e32 vcc, s3, v2
	v_add_u32_e32 v0, v0, v91
	s_waitcnt lgkmcnt(0)
	v_cndmask_b32_e32 v3, v253, v196, vcc
	v_sub_u32_e32 v3, v3, v2
	v_cndmask_b32_e64 v2, v3, v2, s[40:41]
	v_ashrrev_i32_e32 v3, 31, v2
	v_cvt_pk_bf16_f32 v20, v20, v21
	v_lshl_add_u64 v[2:3], s[12:13], 0, v[2:3]
	v_lshlrev_b64 v[2:3], 11, v[2:3]
	v_cvt_pk_bf16_f32 v21, v22, v23
	v_lshl_add_u64 v[2:3], v[44:45], 0, v[2:3]
	global_store_dwordx2 v[2:3], v[20:21], off
	ds_read_b128 v[20:23], v0
	v_add_u32_e32 v2, s2, v90
	v_cmp_lt_i32_e32 vcc, s3, v2
	s_waitcnt lgkmcnt(0)
	v_cndmask_b32_e32 v3, v253, v196, vcc
	v_sub_u32_e32 v3, v3, v2
	v_cndmask_b32_e64 v2, v3, v2, s[40:41]
	v_ashrrev_i32_e32 v3, 31, v2
	v_cvt_pk_bf16_f32 v20, v20, v21
	v_lshl_add_u64 v[2:3], s[12:13], 0, v[2:3]
	v_lshlrev_b64 v[2:3], 11, v[2:3]
	v_cvt_pk_bf16_f32 v21, v22, v23
	v_lshl_add_u64 v[2:3], v[44:45], 0, v[2:3]
	global_store_dwordx2 v[2:3], v[20:21], off

; #define LAS __attribute__((address_space(3)))
; DI unsigned pk2(float lo, float hi) { return f2bf(lo) | (f2bf(hi) << 16); }
; DI void phase_rw_mix(int layer, int j, int q, LAS unsigned char* lds) {
;     ...
;         for (int k = 0; k < 9; ++k) { const int r = rh + 2 * k; if (r >= 17) break;
;             const int t = t0 + r;
;             const f32x4 u = *(const LAS f32x4*)(hs + (r + 1) * 1024 + 4 * c4);
;             f32x4 pv = *(const LAS f32x4*)(hs + r * 1024 + 4 * c4), nx = *(const LAS f32x4*)(hs + (r + 2) * 1024 + 4 * c4);
;             if (t == 0 || t == LC) pv = (f32x4){0.f, 0.f, 0.f, 0.f};
;             if (t == LC - 1 || t == T - 1) nx = (f32x4){0.f, 0.f, 0.f, 0.f};
;             const f32x4 dp = pv - u, dn = nx - u;
; #pragma unroll
;             for (int i = 0; i < 6; ++i) { const f32x4 x = u + mu0[i] * dp + mu1[i] * dn; u32x2 w; w.x = pk2(x[0], x[1]); w.y = pk2(x[2], x[3]);
;                 *(u32x2*)(X + (size_t)i * QROWS * D + (size_t)(lr0 + r) * D + 4 * c4) = w; } }
.LBB0_465:
	v_cmp_gt_i32_e32 vcc, 17, v79
	s_or_b64 s[16:17], s[16:17], exec
	s_and_saveexec_b64 s[18:19], vcc
	s_cbranch_execz .LBB0_464
	v_add_u32_e32 v81, s2, v88
	ds_read_b128 v[90:93], v81 offset:4096
	ds_read_b128 v[94:97], v81
	ds_read_b128 v[98:101], v81 offset:8192
	v_add_u32_e32 v83, s22, v79
	v_and_b32_e32 v81, 0xfffffeff, v83
	v_cmp_ne_u32_e32 vcc, 0, v81
	v_and_b32_e32 v83, 0xffffefff, v83
	s_movk_i32 s3, 0xff
	s_waitcnt lgkmcnt(1)
	v_cndmask_b32_e32 v81, 0, v94, vcc
	v_cndmask_b32_e32 v89, 0, v95, vcc
	v_cndmask_b32_e32 v94, 0, v96, vcc
	v_cndmask_b32_e32 v95, 0, v97, vcc
	v_cmp_ne_u32_e32 vcc, s3, v83
	v_sub_f32_e32 v97, v89, v91
	v_sub_f32_e32 v96, v81, v90
	s_waitcnt lgkmcnt(0)
	v_cndmask_b32_e32 v98, 0, v98, vcc
	v_cndmask_b32_e32 v99, 0, v99, vcc
	v_sub_f32_e32 v99, v99, v91
	v_sub_f32_e32 v98, v98, v90
	v_pk_fma_f32 v[104:105], v[2:3], v[96:97], v[90:91]
	v_cndmask_b32_e32 v83, 0, v100, vcc
	v_pk_fma_f32 v[104:105], v[6:7], v[98:99], v[104:105]
	v_cndmask_b32_e32 v100, 0, v101, vcc
	v_sub_f32_e32 v95, v95, v93
	v_sub_f32_e32 v94, v94, v92
	v_sub_f32_e32 v101, v100, v93
	v_sub_f32_e32 v100, v83, v92
	v_pk_fma_f32 v[106:107], v[4:5], v[94:95], v[92:93]
	v_pk_fma_f32 v[106:107], v[8:9], v[100:101], v[106:107]
	v_add_u32_e32 v102, s21, v79
	v_cvt_pk_bf16_f32 v104, v104, v105
	v_ashrrev_i32_e32 v103, 31, v102
	v_lshlrev_b64 v[102:103], 11, v[102:103]
	v_lshl_add_u64 v[102:103], v[50:51], 0, v[102:103]
	v_cvt_pk_bf16_f32 v105, v106, v107
	global_store_dwordx2 v[102:103], v[104:105], off
	v_pk_fma_f32 v[104:105], v[10:11], v[96:97], v[90:91]
	v_pk_fma_f32 v[106:107], v[12:13], v[94:95], v[92:93]
	v_pk_fma_f32 v[104:105], v[14:15], v[98:99], v[104:105]
	v_pk_fma_f32 v[106:107], v[16:17], v[100:101], v[106:107]
	v_cvt_pk_bf16_f32 v104, v104, v105
	v_bfe_u32 v81, v106, 16, 1
	v_add3_u32 v81, v106, v81, s31
	v_bfe_u32 v83, v107, 16, 1
	s_mov_b32 s3, 0x1100000
	v_lshrrev_b32_e32 v81, 16, v81
	v_add3_u32 v83, v107, v83, s31
	v_add_co_u32_e32 v106, vcc, s3, v102
	v_and_or_b32 v105, v83, s0, v81
	s_nop 0
	v_addc_co_u32_e32 v107, vcc, 0, v103, vcc
	global_store_dwordx2 v[106:107], v[104:105], off
	v_pk_fma_f32 v[104:105], v[18:19], v[96:97], v[90:91]
	v_pk_fma_f32 v[106:107], v[20:21], v[94:95], v[92:93]
	v_pk_fma_f32 v[104:105], v[22:23], v[98:99], v[104:105]
	v_pk_fma_f32 v[106:107], v[24:25], v[100:101], v[106:107]
	v_cvt_pk_bf16_f32 v104, v104, v105
	v_bfe_u32 v81, v106, 16, 1
	v_add3_u32 v81, v106, v81, s31
	v_bfe_u32 v83, v107, 16, 1
	s_mov_b32 s3, 0x2200000
	v_lshrrev_b32_e32 v81, 16, v81
	v_add3_u32 v83, v107, v83, s31
	v_add_co_u32_e32 v106, vcc, s3, v102
	v_and_or_b32 v105, v83, s0, v81
	s_nop 0
	v_addc_co_u32_e32 v107, vcc, 0, v103, vcc
	global_store_dwordx2 v[106:107], v[104:105], off
	v_pk_fma_f32 v[104:105], v[26:27], v[96:97], v[90:91]
	v_pk_fma_f32 v[106:107], v[28:29], v[94:95], v[92:93]
	v_pk_fma_f32 v[104:105], v[30:31], v[98:99], v[104:105]
	v_pk_fma_f32 v[106:107], v[32:33], v[100:101], v[106:107]
	v_cvt_pk_bf16_f32 v104, v104, v105
	v_bfe_u32 v81, v106, 16, 1
	v_add3_u32 v81, v106, v81, s31
	v_bfe_u32 v83, v107, 16, 1
	s_mov_b32 s3, 0x3300000
	v_lshrrev_b32_e32 v81, 16, v81
	v_add3_u32 v83, v107, v83, s31
	v_add_co_u32_e32 v106, vcc, s3, v102
	v_and_or_b32 v105, v83, s0, v81
	s_nop 0
	v_addc_co_u32_e32 v107, vcc, 0, v103, vcc
	global_store_dwordx2 v[106:107], v[104:105], off
	v_pk_fma_f32 v[104:105], v[34:35], v[96:97], v[90:91]
	v_pk_fma_f32 v[106:107], v[36:37], v[94:95], v[92:93]
	v_pk_fma_f32 v[104:105], v[38:39], v[98:99], v[104:105]
	v_pk_fma_f32 v[106:107], v[40:41], v[100:101], v[106:107]
	v_cvt_pk_bf16_f32 v104, v104, v105
	v_pk_fma_f32 v[90:91], v[42:43], v[96:97], v[90:91]
	v_pk_fma_f32 v[90:91], v[46:47], v[98:99], v[90:91]
	v_cvt_pk_bf16_f32 v105, v106, v107
	v_pk_fma_f32 v[92:93], v[44:45], v[94:95], v[92:93]
	s_mov_b32 s3, 0x4400000
	v_pk_fma_f32 v[92:93], v[48:49], v[100:101], v[92:93]
	s_addk_i32 s2, 0x2000
	v_add_co_u32_e32 v106, vcc, s3, v102
	v_cvt_pk_bf16_f32 v90, v90, v91
	v_bfe_u32 v81, v92, 16, 1
	s_cmp_eq_u32 s2, 0x12000
	v_addc_co_u32_e32 v107, vcc, 0, v103, vcc
	v_add3_u32 v81, v92, v81, s31
	v_bfe_u32 v83, v93, 16, 1
	s_cselect_b64 s[24:25], -1, 0
	v_lshrrev_b32_e32 v81, 16, v81
	v_add3_u32 v83, v93, v83, s31
	v_add_co_u32_e32 v92, vcc, 0x5500000, v102
	s_andn2_b64 s[16:17], s[16:17], exec
	s_and_b64 s[24:25], s[24:25], exec
	v_and_or_b32 v91, v83, s0, v81
	v_addc_co_u32_e32 v93, vcc, 0, v103, vcc
	v_add_u32_e32 v79, 2, v79
	s_or_b64 s[16:17], s[16:17], s[24:25]
	global_store_dwordx2 v[106:107], v[104:105], off
	global_store_dwordx2 v[92:93], v[90:91], off
	s_branch .LBB0_464

; DI unsigned pk2(float lo, float hi) { return f2bf(lo) | (f2bf(hi) << 16); }
; DI float sigmoidf_(float x) { return 1.f / (1.f + __expf(-x)); }
; DI float red16(float x) { x += dppmov<0xB1>(x); x += dppmov<0x4E>(x); x += dppmov<0x141>(x); x += dppmov<0x140>(x); return x; }
; #define BIDX() sgpr_opaque((int)__builtin_amdgcn_workgroup_id_x())
; DI void phase_ml_combine(int j) {
;     ...
;     for (int m0 = BIDX() * 8 + wave; m0 < M; m0 += 2 * nw) {
;         const int m1 = (m0 + nw < M) ? m0 + nw : m0; const bool has1 = m0 + nw < M;
;         u32x4 a[2], c[2], o[2];
; #pragma unroll
;         for (int r = 0; r < 2; ++r) { const size_t m = r ? m1 : m0; a[r] = *(const u32x4*)(H0 + m * 512 + col); c[r] = *(const u32x4*)(H1 + m * 512 + col); o[r] = *(const u32x4*)(Pb + m * PW + 2048 + col); }
; #pragma unroll
;         for (int r = 0; r < 2; ++r) {
;             if (r == 1 && !has1) break;
;             const size_t m = r ? m1 : m0;
;             const unsigned av[4] = {a[r].x, a[r].y, a[r].z, a[r].w}, cv[4] = {c[r].x, c[r].y, c[r].z, c[r].w}, ov[4] = {o[r].x, o[r].y, o[r].z, o[r].w};
;             float s[8]; float ss = 0.f;
; #pragma unroll
;             for (int e = 0; e < 4; ++e) { s[2 * e] = bflo(av[e]) + bflo(cv[e]); s[2 * e + 1] = bfhi(av[e]) + bfhi(cv[e]); ss += s[2 * e] * s[2 * e] + s[2 * e + 1] * s[2 * e + 1]; }
;             ss = red16(ss); const float rstd = rsqrtf(ss * (1.f / 128.f) + 1e-6f);
;             unsigned w[4];
; #pragma unroll
;             for (int e = 0; e < 4; ++e) { const float y0 = s[2 * e] * rstd * ogv[2 * e] * sigmoidf_(bflo(ov[e])); const float y1 = s[2 * e + 1] * rstd * ogv[2 * e + 1] * sigmoidf_(bfhi(ov[e])); w[e] = pk2(y0, y1); }
.LBB0_508:
	v_ashrrev_i32_e32 v39, 31, v38
	s_waitcnt vmcnt(1)
	v_lshlrev_b64 v[10:11], 10, v[38:39]
	v_lshl_add_u64 v[12:13], v[30:31], 0, v[10:11]
	v_lshl_add_u64 v[10:11], v[32:33], 0, v[10:11]
	global_load_dwordx4 v[18:21], v[12:13], off
	global_load_dwordx4 v[22:25], v[10:11], off
	v_mov_b64_e32 v[10:11], s[8:9]
	v_add_u32_e32 v44, s2, v38
	s_mov_b32 s3, 0x8800
	v_mad_i64_i32 v[10:11], s[12:13], v38, s78, v[10:11]
	v_cmp_gt_i32_e64 s[4:5], s3, v44
	v_lshl_add_u64 v[10:11], v[10:11], 0, v[0:1]
	s_movk_i32 s3, 0x1000
	v_add_co_u32_e32 v10, vcc, s3, v10
	v_cndmask_b32_e64 v36, v38, v44, s[4:5]
	s_nop 0
	v_addc_co_u32_e32 v11, vcc, 0, v11, vcc
	global_load_dwordx4 v[26:29], v[10:11], off
	v_ashrrev_i32_e32 v37, 31, v36
	v_lshlrev_b64 v[10:11], 10, v[36:37]
	v_lshl_add_u64 v[12:13], v[30:31], 0, v[10:11]
	v_lshl_add_u64 v[10:11], v[32:33], 0, v[10:11]
	global_load_dwordx4 v[14:17], v[12:13], off
	s_mov_b32 s3, 0x800000
	global_load_dwordx4 v[10:13], v[10:11], off
	s_waitcnt vmcnt(4)
	v_lshlrev_b32_e32 v49, 16, v21
	s_waitcnt vmcnt(3)
	v_lshlrev_b32_e32 v43, 16, v23
	v_lshlrev_b32_e32 v42, 16, v22
	v_and_b32_e32 v23, 0xffff0000, v23
	v_and_b32_e32 v22, 0xffff0000, v22
	v_lshlrev_b32_e32 v48, 16, v20
	v_lshlrev_b32_e32 v51, 16, v25
	v_lshlrev_b32_e32 v50, 16, v24
	v_pk_add_f32 v[48:49], v[48:49], v[50:51]
	v_and_b32_e32 v21, 0xffff0000, v21
	v_and_b32_e32 v20, 0xffff0000, v20
	v_and_b32_e32 v25, 0xffff0000, v25
	v_and_b32_e32 v24, 0xffff0000, v24
	v_pk_add_f32 v[20:21], v[20:21], v[24:25]
	v_pk_mul_f32 v[24:25], v[48:49], v[48:49]
	s_waitcnt vmcnt(2)
	v_lshlrev_b32_e32 v37, 16, v26
	v_and_b32_e32 v26, 0xffff0000, v26
	v_mul_f32_e32 v26, 0xbfb8aa3b, v26
	v_exp_f32_e32 v46, v26
	v_lshlrev_b32_e32 v26, 16, v27
	v_mul_f32_e32 v26, 0xbfb8aa3b, v26
	v_mul_f32_e32 v37, 0xbfb8aa3b, v37
	v_exp_f32_e32 v41, v26
	v_and_b32_e32 v26, 0xffff0000, v27
	v_exp_f32_e32 v40, v37
	v_mul_f32_e32 v26, 0xbfb8aa3b, v26
	v_exp_f32_e32 v47, v26
	v_lshlrev_b32_e32 v27, 16, v19
	v_lshlrev_b32_e32 v26, 16, v18
	v_pk_add_f32 v[26:27], v[26:27], v[42:43]
	v_and_b32_e32 v19, 0xffff0000, v19
	v_and_b32_e32 v18, 0xffff0000, v18
	v_pk_add_f32 v[18:19], v[18:19], v[22:23]
	v_pk_mul_f32 v[22:23], v[26:27], v[26:27]
	v_pk_fma_f32 v[24:25], v[20:21], v[20:21], v[24:25]
	v_pk_fma_f32 v[42:43], v[18:19], v[18:19], v[22:23]
	v_pk_add_f32 v[22:23], v[40:41], 1.0 op_sel_hi:[1,0]
	s_nop 0
	v_div_scale_f32 v37, s[12:13], v23, v23, 1.0
	v_rcp_f32_e32 v39, v37
	s_nop 0
	v_fma_f32 v40, -v37, v39, 1.0
	v_fmac_f32_e32 v39, v40, v39
	v_div_scale_f32 v40, vcc, 1.0, v23, 1.0
	v_mul_f32_e32 v41, v40, v39
	v_fma_f32 v45, -v37, v41, v40
	v_fmac_f32_e32 v41, v45, v39
	v_fma_f32 v37, -v37, v41, v40
	v_div_fmas_f32 v37, v37, v39, v41
	v_div_fixup_f32 v23, v37, v23, 1.0
	v_div_scale_f32 v37, s[12:13], v22, v22, 1.0
	v_rcp_f32_e32 v39, v37
	s_nop 0
	v_fma_f32 v40, -v37, v39, 1.0
	v_fmac_f32_e32 v39, v40, v39
	v_div_scale_f32 v40, vcc, 1.0, v22, 1.0
	v_mul_f32_e32 v41, v40, v39
	v_fma_f32 v45, -v37, v41, v40
	v_fmac_f32_e32 v41, v45, v39
	v_fma_f32 v37, -v37, v41, v40
	v_div_fmas_f32 v37, v37, v39, v41
	v_pk_add_f32 v[40:41], v[46:47], 1.0 op_sel_hi:[1,0]
	v_div_fixup_f32 v22, v37, v22, 1.0
	v_div_scale_f32 v37, s[12:13], v41, v41, 1.0
	v_rcp_f32_e32 v39, v37
	s_nop 0
	v_fma_f32 v45, -v37, v39, 1.0
	v_fmac_f32_e32 v39, v45, v39
	v_div_scale_f32 v45, vcc, 1.0, v41, 1.0
	v_mul_f32_e32 v46, v45, v39
	v_fma_f32 v47, -v37, v46, v45
	v_fmac_f32_e32 v46, v47, v39
	v_fma_f32 v37, -v37, v46, v45
	v_div_fmas_f32 v37, v37, v39, v46
	v_div_fixup_f32 v41, v37, v41, 1.0
	v_div_scale_f32 v37, s[12:13], v40, v40, 1.0
	v_rcp_f32_e32 v39, v37
	s_nop 0
	v_fma_f32 v45, -v37, v39, 1.0
	v_fmac_f32_e32 v39, v45, v39
	v_div_scale_f32 v45, vcc, 1.0, v40, 1.0
	v_mul_f32_e32 v46, v45, v39
	v_fma_f32 v47, -v37, v46, v45
	v_fmac_f32_e32 v46, v47, v39
	v_fma_f32 v37, -v37, v46, v45
	v_div_fmas_f32 v37, v37, v39, v46
	v_div_fixup_f32 v40, v37, v40, 1.0
	v_lshlrev_b32_e32 v37, 16, v28
	v_mul_f32_e32 v37, 0xbfb8aa3b, v37
	v_exp_f32_e32 v46, v37
	v_lshlrev_b32_e32 v37, 16, v29
	v_mul_f32_e32 v37, 0xbfb8aa3b, v37
	v_exp_f32_e32 v47, v37
	v_add_f32_e32 v37, v42, v43
	v_add_f32_e32 v24, v24, v37
	v_add_f32_e32 v24, v25, v24
	v_and_b32_e32 v28, 0xffff0000, v28
	v_and_b32_e32 v29, 0xffff0000, v29
	v_add_f32_dpp v24, v24, v24 quad_perm:[1,0,3,2] row_mask:0xf bank_mask:0xf bound_ctrl:1
	v_mul_f32_e32 v28, 0xbfb8aa3b, v28
	v_mul_f32_e32 v29, 0xbfb8aa3b, v29
	v_add_f32_dpp v24, v24, v24 quad_perm:[2,3,0,1] row_mask:0xf bank_mask:0xf bound_ctrl:1
	v_exp_f32_e32 v28, v28
	v_exp_f32_e32 v29, v29
	v_add_f32_dpp v24, v24, v24 row_half_mirror row_mask:0xf bank_mask:0xf bound_ctrl:1
	s_nop 1
	v_add_f32_dpp v24, v24, v24 row_mirror row_mask:0xf bank_mask:0xf bound_ctrl:1
	v_fmamk_f32 v24, v24, 0x3c000000, v183
	v_cmp_gt_f32_e32 vcc, s3, v24
	v_mul_f32_e32 v25, 0x4b800000, v24
	s_nop 0
	v_cndmask_b32_e32 v24, v24, v25, vcc
	v_rsq_f32_e32 v24, v24
	s_nop 0
	v_mul_f32_e32 v25, 0x45800000, v24
	v_cndmask_b32_e32 v24, v24, v25, vcc
	v_pk_mul_f32 v[18:19], v[18:19], v[24:25] op_sel_hi:[1,0]
	v_pk_mul_f32 v[26:27], v[26:27], v[24:25] op_sel_hi:[1,0]
	v_pk_mul_f32 v[18:19], v[8:9], v[18:19]
	v_pk_mul_f32 v[26:27], v[6:7], v[26:27]
	v_pk_mul_f32 v[18:19], v[40:41], v[18:19]
	v_pk_add_f32 v[40:41], v[46:47], 1.0 op_sel_hi:[1,0]
	v_pk_mul_f32 v[22:23], v[22:23], v[26:27]
	v_pk_mul_f32 v[26:27], v[48:49], v[24:25] op_sel_hi:[1,0]
	v_div_scale_f32 v25, s[12:13], v41, v41, 1.0
	v_rcp_f32_e32 v37, v25
	v_pk_mul_f32 v[26:27], v[2:3], v[26:27]
	v_fma_f32 v39, -v25, v37, 1.0
	v_fmac_f32_e32 v37, v39, v37
	v_div_scale_f32 v39, vcc, 1.0, v41, 1.0
	v_mul_f32_e32 v42, v39, v37
; DI unsigned pk2(float lo, float hi) { return f2bf(lo) | (f2bf(hi) << 16); }
; DI float sigmoidf_(float x) { return 1.f / (1.f + __expf(-x)); }
; DI float red16(float x) { x += dppmov<0xB1>(x); x += dppmov<0x4E>(x); x += dppmov<0x141>(x); x += dppmov<0x140>(x); return x; }
; DI void phase_ml_combine(int j) {
;     ...
;             for (int e = 0; e < 4; ++e) { s[2 * e] = bflo(av[e]) + bflo(cv[e]); s[2 * e + 1] = bfhi(av[e]) + bfhi(cv[e]); ss += s[2 * e] * s[2 * e] + s[2 * e + 1] * s[2 * e + 1]; }
;             ss = red16(ss); const float rstd = rsqrtf(ss * (1.f / 128.f) + 1e-6f);
;             unsigned w[4];
; #pragma unroll
;             for (int e = 0; e < 4; ++e) { const float y0 = s[2 * e] * rstd * ogv[2 * e] * sigmoidf_(bflo(ov[e])); const float y1 = s[2 * e + 1] * rstd * ogv[2 * e + 1] * sigmoidf_(bfhi(ov[e])); w[e] = pk2(y0, y1); }
;             u32x4 wv; wv.x = w[0]; wv.y = w[1]; wv.z = w[2]; wv.w = w[3];
;             *(u32x4*)(Pb + m * PW + col) = wv;
	v_fma_f32 v43, -v25, v42, v39
	v_fmac_f32_e32 v42, v43, v37
	v_fma_f32 v25, -v25, v42, v39
	v_div_fmas_f32 v25, v25, v37, v42
	v_div_fixup_f32 v41, v25, v41, 1.0
	v_div_scale_f32 v25, s[12:13], v40, v40, 1.0
	v_rcp_f32_e32 v37, v25
	s_nop 0
	v_fma_f32 v39, -v25, v37, 1.0
	v_fmac_f32_e32 v37, v39, v37
	v_div_scale_f32 v39, vcc, 1.0, v40, 1.0
	v_mul_f32_e32 v42, v39, v37
	v_fma_f32 v43, -v25, v42, v39
	v_fmac_f32_e32 v42, v43, v37
	v_fma_f32 v25, -v25, v42, v39
	v_div_fmas_f32 v25, v25, v37, v42
	v_div_fixup_f32 v40, v25, v40, 1.0
	v_pk_mul_f32 v[20:21], v[20:21], v[24:25] op_sel_hi:[1,0]
	v_pk_add_f32 v[24:25], v[28:29], 1.0 op_sel_hi:[1,0]
	v_pk_mul_f32 v[26:27], v[40:41], v[26:27]
	v_div_scale_f32 v28, s[12:13], v25, v25, 1.0
	v_rcp_f32_e32 v29, v28
	v_pk_mul_f32 v[20:21], v[4:5], v[20:21]
	v_fma_f32 v37, -v28, v29, 1.0
	v_fmac_f32_e32 v29, v37, v29
	v_div_scale_f32 v37, vcc, 1.0, v25, 1.0
	v_mul_f32_e32 v39, v37, v29
	v_fma_f32 v40, -v28, v39, v37
	v_fmac_f32_e32 v39, v40, v29
	v_fma_f32 v28, -v28, v39, v37
	v_div_fmas_f32 v28, v28, v29, v39
	v_div_fixup_f32 v25, v28, v25, 1.0
	v_div_scale_f32 v28, s[12:13], v24, v24, 1.0
	v_rcp_f32_e32 v29, v28
	s_nop 0
	v_fma_f32 v37, -v28, v29, 1.0
	v_fmac_f32_e32 v29, v37, v29
	v_div_scale_f32 v37, vcc, 1.0, v24, 1.0
	v_mul_f32_e32 v39, v37, v29
	v_fma_f32 v40, -v28, v39, v37
	v_fmac_f32_e32 v39, v40, v29
	v_fma_f32 v28, -v28, v39, v37
	v_div_fmas_f32 v28, v28, v29, v39
	v_div_fixup_f32 v24, v28, v24, 1.0
	v_pk_mul_f32 v[20:21], v[24:25], v[20:21]
	v_bfe_u32 v24, v21, 16, 1
	v_add3_u32 v21, v21, v24, s31
	v_bfe_u32 v29, v27, 16, 1
	v_add3_u32 v27, v27, v29, s31
	v_lshrrev_b32_e32 v25, 16, v27
	v_and_or_b32 v21, v21, s0, v25
	v_cvt_pk_bf16_f32 v20, v26, v20
	v_cvt_pk_bf16_f32 v19, v23, v19
	v_cvt_pk_bf16_f32 v18, v22, v18
	v_mad_i64_i32 v[22:23], s[12:13], v38, s78, v[34:35]
	global_store_dwordx4 v[22:23], v[18:21], off
	s_and_saveexec_b64 s[12:13], s[4:5]
	s_cbranch_execz .LBB0_507
	v_mov_b64_e32 v[18:19], s[8:9]
	v_mad_i64_i32 v[18:19], s[4:5], v36, s78, v[18:19]
	v_lshl_add_u64 v[18:19], v[18:19], 0, v[0:1]
	v_add_co_u32_e32 v18, vcc, 0x1000, v18
	s_waitcnt vmcnt(1)
	v_lshlrev_b32_e32 v25, 16, v11
	v_addc_co_u32_e32 v19, vcc, 0, v19, vcc
	global_load_dwordx4 v[26:29], v[18:19], off
	v_lshlrev_b32_e32 v19, 16, v15
	v_lshlrev_b32_e32 v24, 16, v10
	v_and_b32_e32 v15, 0xffff0000, v15
	v_and_b32_e32 v11, 0xffff0000, v11
	v_and_b32_e32 v10, 0xffff0000, v10
	v_lshlrev_b32_e32 v39, 16, v13
	v_lshlrev_b32_e32 v38, 16, v12
	v_and_b32_e32 v13, 0xffff0000, v13
	v_and_b32_e32 v12, 0xffff0000, v12
	s_waitcnt vmcnt(0)
; DI unsigned pk2(float lo, float hi) { return f2bf(lo) | (f2bf(hi) << 16); }
; DI float sigmoidf_(float x) { return 1.f / (1.f + __expf(-x)); }
; DI float red16(float x) { x += dppmov<0xB1>(x); x += dppmov<0x4E>(x); x += dppmov<0x141>(x); x += dppmov<0x140>(x); return x; }
; DI void phase_ml_combine(int j) {
;     ...
;         for (int r = 0; r < 2; ++r) {
;             if (r == 1 && !has1) break;
;             const size_t m = r ? m1 : m0;
;             const unsigned av[4] = {a[r].x, a[r].y, a[r].z, a[r].w}, cv[4] = {c[r].x, c[r].y, c[r].z, c[r].w}, ov[4] = {o[r].x, o[r].y, o[r].z, o[r].w};
;             float s[8]; float ss = 0.f;
; #pragma unroll
;             for (int e = 0; e < 4; ++e) { s[2 * e] = bflo(av[e]) + bflo(cv[e]); s[2 * e + 1] = bfhi(av[e]) + bfhi(cv[e]); ss += s[2 * e] * s[2 * e] + s[2 * e + 1] * s[2 * e + 1]; }
;             ss = red16(ss); const float rstd = rsqrtf(ss * (1.f / 128.f) + 1e-6f);
;             unsigned w[4];
; #pragma unroll
;             for (int e = 0; e < 4; ++e) { const float y0 = s[2 * e] * rstd * ogv[2 * e] * sigmoidf_(bflo(ov[e])); const float y1 = s[2 * e + 1] * rstd * ogv[2 * e + 1] * sigmoidf_(bfhi(ov[e])); w[e] = pk2(y0, y1); }
;             u32x4 wv; wv.x = w[0]; wv.y = w[1]; wv.z = w[2]; wv.w = w[3];
;             *(u32x4*)(Pb + m * PW + col) = wv;
	v_lshlrev_b32_e32 v18, 16, v26
	v_mul_f32_e32 v18, 0xbfb8aa3b, v18
	v_exp_f32_e32 v20, v18
	v_and_b32_e32 v18, 0xffff0000, v26
	v_mul_f32_e32 v18, 0xbfb8aa3b, v18
	v_exp_f32_e32 v22, v18
	v_lshlrev_b32_e32 v18, 16, v27
	v_mul_f32_e32 v18, 0xbfb8aa3b, v18
	v_exp_f32_e32 v21, v18
	v_and_b32_e32 v18, 0xffff0000, v27
	v_mul_f32_e32 v18, 0xbfb8aa3b, v18
	v_exp_f32_e32 v23, v18
	v_lshlrev_b32_e32 v18, 16, v14
	v_pk_add_f32 v[18:19], v[18:19], v[24:25]
	v_and_b32_e32 v14, 0xffff0000, v14
	v_pk_add_f32 v[14:15], v[14:15], v[10:11]
	v_pk_mul_f32 v[10:11], v[18:19], v[18:19]
	s_nop 0
	v_pk_fma_f32 v[26:27], v[14:15], v[14:15], v[10:11]
	v_pk_add_f32 v[10:11], v[20:21], 1.0 op_sel_hi:[1,0]
	v_add_f32_e32 v26, v26, v27
	v_div_scale_f32 v20, s[4:5], v11, v11, 1.0
	v_rcp_f32_e32 v21, v20
	s_nop 0
	v_fma_f32 v24, -v20, v21, 1.0
	v_fmac_f32_e32 v21, v24, v21
	v_div_scale_f32 v24, vcc, 1.0, v11, 1.0
	v_mul_f32_e32 v25, v24, v21
	v_fma_f32 v37, -v20, v25, v24
	v_fmac_f32_e32 v25, v37, v21
	v_fma_f32 v20, -v20, v25, v24
	v_div_fmas_f32 v20, v20, v21, v25
	v_div_fixup_f32 v21, v20, v11, 1.0
	v_div_scale_f32 v11, s[4:5], v10, v10, 1.0
	v_rcp_f32_e32 v20, v11
	s_nop 0
	v_fma_f32 v24, -v11, v20, 1.0
	v_fmac_f32_e32 v20, v24, v20
	v_div_scale_f32 v24, vcc, 1.0, v10, 1.0
	v_mul_f32_e32 v25, v24, v20
	v_fma_f32 v37, -v11, v25, v24
	v_fmac_f32_e32 v25, v37, v20
	v_fma_f32 v11, -v11, v25, v24
	v_div_fmas_f32 v11, v11, v20, v25
	v_div_fixup_f32 v20, v11, v10, 1.0
	v_pk_add_f32 v[10:11], v[22:23], 1.0 op_sel_hi:[1,0]
	s_nop 0
	v_div_scale_f32 v22, s[4:5], v11, v11, 1.0
	v_rcp_f32_e32 v23, v22
	s_nop 0
	v_fma_f32 v24, -v22, v23, 1.0
	v_fmac_f32_e32 v23, v24, v23
	v_div_scale_f32 v24, vcc, 1.0, v11, 1.0
	v_mul_f32_e32 v25, v24, v23
	v_fma_f32 v37, -v22, v25, v24
	v_fmac_f32_e32 v25, v37, v23
	v_fma_f32 v22, -v22, v25, v24
	v_div_fmas_f32 v22, v22, v23, v25
	v_div_fixup_f32 v25, v22, v11, 1.0
	v_div_scale_f32 v11, s[4:5], v10, v10, 1.0
	v_rcp_f32_e32 v22, v11
	s_nop 0
	v_fma_f32 v23, -v11, v22, 1.0
	v_fmac_f32_e32 v22, v23, v22
	v_div_scale_f32 v23, vcc, 1.0, v10, 1.0
	v_mul_f32_e32 v24, v23, v22
	v_fma_f32 v37, -v11, v24, v23
	v_fmac_f32_e32 v24, v37, v22
	v_fma_f32 v11, -v11, v24, v23
	v_div_fmas_f32 v11, v11, v22, v24
	v_div_fixup_f32 v24, v11, v10, 1.0
	v_lshlrev_b32_e32 v10, 16, v28
	v_lshlrev_b32_e32 v11, 16, v29
	v_mul_f32_e32 v10, 0xbfb8aa3b, v10
	v_mul_f32_e32 v11, 0xbfb8aa3b, v11
	v_exp_f32_e32 v22, v10
	v_and_b32_e32 v10, 0xffff0000, v28
	v_exp_f32_e32 v23, v11
	v_and_b32_e32 v11, 0xffff0000, v29
	v_lshlrev_b32_e32 v29, 16, v17
	v_lshlrev_b32_e32 v28, 16, v16
	v_pk_add_f32 v[28:29], v[28:29], v[38:39]
	v_and_b32_e32 v17, 0xffff0000, v17
	v_and_b32_e32 v16, 0xffff0000, v16
	v_pk_add_f32 v[12:13], v[16:17], v[12:13]
	v_pk_mul_f32 v[16:17], v[28:29], v[28:29]
	v_pk_add_f32 v[22:23], v[22:23], 1.0 op_sel_hi:[1,0]
	v_pk_fma_f32 v[16:17], v[12:13], v[12:13], v[16:17]
	v_mul_f32_e32 v10, 0xbfb8aa3b, v10
	v_add_f32_e32 v16, v16, v26
	v_add_f32_e32 v16, v17, v16
	v_mul_f32_e32 v11, 0xbfb8aa3b, v11
	v_exp_f32_e32 v10, v10
	v_add_f32_dpp v16, v16, v16 quad_perm:[1,0,3,2] row_mask:0xf bank_mask:0xf bound_ctrl:1
	v_exp_f32_e32 v11, v11
	s_nop 0
	v_add_f32_dpp v16, v16, v16 quad_perm:[2,3,0,1] row_mask:0xf bank_mask:0xf bound_ctrl:1
	v_pk_add_f32 v[10:11], v[10:11], 1.0 op_sel_hi:[1,0]
	s_nop 0
	v_add_f32_dpp v16, v16, v16 row_half_mirror row_mask:0xf bank_mask:0xf bound_ctrl:1
	s_nop 1
	v_add_f32_dpp v16, v16, v16 row_mirror row_mask:0xf bank_mask:0xf bound_ctrl:1
	v_fmamk_f32 v16, v16, 0x3c000000, v183
	v_cmp_gt_f32_e32 vcc, s3, v16
	v_mul_f32_e32 v17, 0x4b800000, v16
	s_nop 0
	v_cndmask_b32_e32 v16, v16, v17, vcc
	v_rsq_f32_e32 v16, v16
	s_nop 0
	v_mul_f32_e32 v17, 0x45800000, v16
	v_cndmask_b32_e32 v16, v16, v17, vcc
	v_pk_mul_f32 v[18:19], v[18:19], v[16:17] op_sel_hi:[1,0]
	v_pk_mul_f32 v[14:15], v[14:15], v[16:17] op_sel_hi:[1,0]
	v_pk_mul_f32 v[18:19], v[6:7], v[18:19]
	v_pk_mul_f32 v[14:15], v[8:9], v[14:15]
	v_pk_mul_f32 v[18:19], v[20:21], v[18:19]
	v_pk_mul_f32 v[20:21], v[28:29], v[16:17] op_sel_hi:[1,0]
	v_div_scale_f32 v17, s[4:5], v23, v23, 1.0
	v_pk_mul_f32 v[14:15], v[24:25], v[14:15]
	v_rcp_f32_e32 v24, v17
	v_pk_mul_f32 v[20:21], v[2:3], v[20:21]
	v_fma_f32 v25, -v17, v24, 1.0
	v_fmac_f32_e32 v24, v25, v24
	v_div_scale_f32 v25, vcc, 1.0, v23, 1.0
	v_mul_f32_e32 v26, v25, v24
	v_fma_f32 v27, -v17, v26, v25
	v_fmac_f32_e32 v26, v27, v24
	v_fma_f32 v17, -v17, v26, v25
	v_div_fmas_f32 v17, v17, v24, v26
	v_div_fixup_f32 v23, v17, v23, 1.0
	v_div_scale_f32 v17, s[4:5], v22, v22, 1.0
	v_rcp_f32_e32 v24, v17
	s_nop 0
	v_fma_f32 v25, -v17, v24, 1.0
	v_fmac_f32_e32 v24, v25, v24
	v_div_scale_f32 v25, vcc, 1.0, v22, 1.0
	v_mul_f32_e32 v26, v25, v24
	v_fma_f32 v27, -v17, v26, v25
	v_fmac_f32_e32 v26, v27, v24
	v_fma_f32 v17, -v17, v26, v25
	v_div_fmas_f32 v17, v17, v24, v26
	v_pk_mul_f32 v[12:13], v[12:13], v[16:17] op_sel_hi:[1,0]
	v_div_scale_f32 v16, s[4:5], v11, v11, 1.0
	v_div_fixup_f32 v22, v17, v22, 1.0
	v_rcp_f32_e32 v17, v16
	v_pk_mul_f32 v[20:21], v[22:23], v[20:21]
	v_pk_mul_f32 v[12:13], v[4:5], v[12:13]
	v_fma_f32 v22, -v16, v17, 1.0
	v_fmac_f32_e32 v17, v22, v17
	v_div_scale_f32 v22, vcc, 1.0, v11, 1.0
	v_mul_f32_e32 v23, v22, v17
	v_fma_f32 v24, -v16, v23, v22
	v_fmac_f32_e32 v23, v24, v17
	v_fma_f32 v16, -v16, v23, v22
	v_div_fmas_f32 v16, v16, v17, v23
	v_div_fixup_f32 v11, v16, v11, 1.0
	v_div_scale_f32 v16, s[4:5], v10, v10, 1.0
	v_rcp_f32_e32 v17, v16
	s_nop 0
	v_fma_f32 v22, -v16, v17, 1.0
	v_fmac_f32_e32 v17, v22, v17
	v_div_scale_f32 v22, vcc, 1.0, v10, 1.0
	v_mul_f32_e32 v23, v22, v17
	v_fma_f32 v24, -v16, v23, v22
	v_fmac_f32_e32 v23, v24, v17
	v_fma_f32 v16, -v16, v23, v22
	v_div_fmas_f32 v16, v16, v17, v23
	v_div_fixup_f32 v10, v16, v10, 1.0
	v_pk_mul_f32 v[10:11], v[10:11], v[12:13]
	v_bfe_u32 v16, v15, 16, 1
	v_bfe_u32 v12, v11, 16, 1
	v_bfe_u32 v13, v10, 16, 1
	v_bfe_u32 v17, v14, 16, 1
	v_add3_u32 v14, v14, v17, s31
	v_add3_u32 v15, v15, v16, s31
	v_add3_u32 v10, v10, v13, s31
	v_add3_u32 v11, v11, v12, s31
	v_bfe_u32 v12, v18, 16, 1
	v_bfe_u32 v13, v19, 16, 1
	v_bfe_u32 v16, v20, 16, 1
	v_bfe_u32 v17, v21, 16, 1
	v_add3_u32 v17, v21, v17, s31
	v_add3_u32 v16, v20, v16, s31
	v_add3_u32 v13, v19, v13, s31
	v_add3_u32 v12, v18, v12, s31
	v_lshrrev_b32_e32 v18, 16, v12
	v_lshrrev_b32_e32 v19, 16, v13
	v_lshrrev_b32_e32 v12, 16, v16
	v_lshrrev_b32_e32 v13, 16, v17
	v_and_or_b32 v13, v11, s0, v13
	v_and_or_b32 v12, v10, s0, v12
	v_and_or_b32 v11, v15, s0, v19
	v_and_or_b32 v10, v14, s0, v18
	v_mad_i64_i32 v[14:15], s[4:5], v36, s78, v[34:35]
	global_store_dwordx4 v[14:15], v[10:13], off
	s_branch .LBB0_507

; #define LAS __attribute__((address_space(3)))
; DI unsigned pk2(float lo, float hi) { return f2bf(lo) | (f2bf(hi) << 16); }
; DI int tok_of(int d, int i) { if (i < LC) return d ? (LC - 1 - i) : i; return d ? (LC + SL - 1 - (i - LC)) : i; }
; DI void mlstm_item(int j, int item, LAS unsigned char* lds) {
;     ...
;             *(LAS u32x2*)(KPs + trow * 136 + nt * 16 + fq * 4) = w2; }
;         __syncthreads();
;         f32x4 num[3], num2[3];
; #pragma unroll
;         for (int i = 0; i < 3; ++i) { num[i] = (f32x4){0.f, 0.f, 0.f, 0.f}; num2[i] = (f32x4){0.f, 0.f, 0.f, 0.f}; }
;         mm16<3, 4>(KPs + wave * 16 * 136, 136, VTs, 136, num, fr, fq);
;         mm16<3, 4>(Qs + wave * 16 * 136, 136, Cs, 136, num2, fr, fq);
;         {
;             const float rs = __shfl(num[2][0], fr), qn = __shfl(num2[2][0], fr);
;             const float iw = __expf(mst - at), mt = bcs[trow] + at;
;             const float den = fmaxf(fabsf(rs + iw * qn), __expf(-mt)); const float inv = 1.f / den;
;             const int mrow = b * T + tok_of(d, i0 + trow);
; #pragma unroll
;             for (int nt = 0; nt < 2; ++nt) { const f32x4 o = (num[nt] + num2[nt] * iw) * inv;
;                 u32x2 w2; w2.x = pk2(o[0], o[1]); w2.y = pk2(o[2], o[3]);
;                 *(u32x2*)(HB + (size_t)mrow * 512 + head * 128 + vq * 32 + nt * 16 + fq * 4) = w2; }
;         }
; #pragma unroll
;         for (int i = 0; i < 3; ++i) Ct[i] *= carry;
.LBB0_524:
	s_or_b64 exec, exec, s[2:3]
	v_cvt_pk_bf16_f32 v52, v59, v58
	v_cvt_pk_bf16_f32 v53, v51, v50
	v_add_u32_e32 v70, v106, v88
	ds_write_b64 v106, v[52:53] offset:224
	s_waitcnt lgkmcnt(0)
	s_barrier
	ds_read_b128 v[50:53], v70
	ds_read_b128 v[54:57], v135
	ds_read_b128 v[58:61], v135 offset:4352
	ds_read_b128 v[62:65], v135 offset:8704
	s_waitcnt lgkmcnt(2)
	v_mfma_f32_16x16x32_bf16 v[54:57], v[54:57], v[50:53], 0
	v_mul_f32_e64 v40, v40, v96
	v_mul_f32_e64 v41, v41, v96
	v_pk_mul_f32 v[38:39], v[38:39], v[96:97] op_sel_hi:[1,0]
	v_pk_mul_f32 v[44:45], v[44:45], v[96:97] op_sel_hi:[1,0]
	s_waitcnt lgkmcnt(1)
	v_mfma_f32_16x16x32_bf16 v[58:61], v[58:61], v[50:53], 0
	v_mul_f32_e64 v42, v42, v96
	v_mul_f32_e64 v43, v43, v96
	v_pk_mul_f32 v[48:49], v[48:49], v[96:97] op_sel_hi:[1,0]
	v_pk_mul_f32 v[46:47], v[46:47], v[96:97] op_sel_hi:[1,0]
	s_waitcnt lgkmcnt(0)
	v_mfma_f32_16x16x32_bf16 v[50:53], v[62:65], v[50:53], 0
	ds_read_b128 v[62:65], v70 offset:64
	ds_read_b128 v[66:69], v135 offset:64
	v_add_u32_e32 v131, 0xffffff80, v131
	v_add_u32_e32 v133, 0xffffff80, v133
	s_waitcnt lgkmcnt(0)
	v_mfma_f32_16x16x32_bf16 v[54:57], v[66:69], v[62:65], v[54:57]
	ds_read_b128 v[66:69], v135 offset:4416
	s_waitcnt lgkmcnt(0)
	v_mfma_f32_16x16x32_bf16 v[58:61], v[66:69], v[62:65], v[58:61]
	ds_read_b128 v[66:69], v135 offset:8768
	s_waitcnt lgkmcnt(0)
	v_mfma_f32_16x16x32_bf16 v[50:53], v[66:69], v[62:65], v[50:53]
	ds_read_b128 v[62:65], v70 offset:128
	ds_read_b128 v[66:69], v135 offset:128
	s_waitcnt lgkmcnt(0)
	v_mfma_f32_16x16x32_bf16 v[54:57], v[66:69], v[62:65], v[54:57]
	ds_read_b128 v[66:69], v135 offset:4480
	s_waitcnt lgkmcnt(0)
	v_mfma_f32_16x16x32_bf16 v[58:61], v[66:69], v[62:65], v[58:61]
	ds_read_b128 v[66:69], v135 offset:8832
	s_waitcnt lgkmcnt(0)
	v_mfma_f32_16x16x32_bf16 v[62:65], v[66:69], v[62:65], v[50:53]
	ds_read_b128 v[66:69], v70 offset:192
	s_nop 1
	ds_read_b128 v[50:53], v135 offset:192
	s_waitcnt lgkmcnt(0)
	v_mfma_f32_16x16x32_bf16 v[54:57], v[50:53], v[66:69], v[54:57]
	ds_read_b128 v[50:53], v135 offset:4544
	s_waitcnt lgkmcnt(0)
	v_mfma_f32_16x16x32_bf16 v[50:53], v[50:53], v[66:69], v[58:61]
	s_nop 2
	ds_read_b128 v[58:61], v135 offset:8896
	s_waitcnt lgkmcnt(0)
	v_mfma_f32_16x16x32_bf16 v[58:61], v[58:61], v[66:69], v[62:65]
	s_nop 7
	ds_read_b128 v[60:63], v102
	ds_read_b128 v[64:67], v136
	ds_read_b128 v[68:71], v136 offset:4352
	ds_read_b128 v[72:75], v136 offset:8704
	s_waitcnt lgkmcnt(2)
	v_mfma_f32_16x16x32_bf16 v[64:67], v[64:67], v[60:63], 0
	ds_bpermute_b32 v59, v107, v58
	v_sub_f32_e32 v58, v145, v95
	v_mul_f32_e32 v58, 0x3fb8aa3b, v58
	s_waitcnt lgkmcnt(2)
	v_mfma_f32_16x16x32_bf16 v[68:71], v[68:71], v[60:63], 0
	v_exp_f32_e32 v58, v58
	v_mov_b32_e32 v145, v146
	s_waitcnt lgkmcnt(1)
	v_mfma_f32_16x16x32_bf16 v[60:63], v[72:75], v[60:63], 0
	ds_read_b128 v[72:75], v102 offset:64
	ds_read_b128 v[76:79], v136 offset:64
	s_waitcnt lgkmcnt(0)
	v_mfma_f32_16x16x32_bf16 v[64:67], v[76:79], v[72:75], v[64:67]
	ds_read_b128 v[76:79], v136 offset:4416
	s_waitcnt lgkmcnt(0)
	v_mfma_f32_16x16x32_bf16 v[68:71], v[76:79], v[72:75], v[68:71]
	ds_read_b128 v[76:79], v136 offset:8768
	s_waitcnt lgkmcnt(0)
	v_mfma_f32_16x16x32_bf16 v[60:63], v[76:79], v[72:75], v[60:63]
	ds_read_b128 v[72:75], v102 offset:128
	ds_read_b128 v[76:79], v136 offset:128
	s_waitcnt lgkmcnt(0)
	v_mfma_f32_16x16x32_bf16 v[64:67], v[76:79], v[72:75], v[64:67]
	ds_read_b128 v[76:79], v136 offset:4480
	s_waitcnt lgkmcnt(0)
	v_mfma_f32_16x16x32_bf16 v[68:71], v[76:79], v[72:75], v[68:71]
	ds_read_b128 v[76:79], v136 offset:8832
	s_waitcnt lgkmcnt(0)
	v_mfma_f32_16x16x32_bf16 v[60:63], v[76:79], v[72:75], v[60:63]
	ds_read_b128 v[72:75], v102 offset:192
	ds_read_b128 v[76:79], v136 offset:192
	s_waitcnt lgkmcnt(0)
	v_mfma_f32_16x16x32_bf16 v[64:67], v[76:79], v[72:75], v[64:67]
	ds_read_b128 v[76:79], v136 offset:4544
	s_waitcnt lgkmcnt(0)
	v_mfma_f32_16x16x32_bf16 v[68:71], v[76:79], v[72:75], v[68:71]
	ds_read_b128 v[76:79], v136 offset:8896
	s_waitcnt lgkmcnt(0)
	v_mfma_f32_16x16x32_bf16 v[60:63], v[76:79], v[72:75], v[60:63]
	s_nop 7
	ds_read_b32 v61, v108
	ds_bpermute_b32 v60, v107, v60
	s_waitcnt lgkmcnt(1)
	v_add_f32_e32 v61, v95, v61
	s_waitcnt lgkmcnt(0)
; DI unsigned f2bf(float f) { unsigned u = __builtin_bit_cast(unsigned, f); return (u + 0x7fffu + ((u >> 16) & 1u)) >> 16; }
; DI unsigned pk2(float lo, float hi) { return f2bf(lo) | (f2bf(hi) << 16); }
; DI int tok_of(int d, int i) { if (i < LC) return d ? (LC - 1 - i) : i; return d ? (LC + SL - 1 - (i - LC)) : i; }
; DI void mlstm_item(int j, int item, LAS unsigned char* lds) {
;     ...
;             const float rs = __shfl(num[2][0], fr), qn = __shfl(num2[2][0], fr);
;             const float iw = __expf(mst - at), mt = bcs[trow] + at;
;             const float den = fmaxf(fabsf(rs + iw * qn), __expf(-mt)); const float inv = 1.f / den;
;             const int mrow = b * T + tok_of(d, i0 + trow);
; #pragma unroll
;             for (int nt = 0; nt < 2; ++nt) { const f32x4 o = (num[nt] + num2[nt] * iw) * inv;
;                 u32x2 w2; w2.x = pk2(o[0], o[1]); w2.y = pk2(o[2], o[3]);
;                 *(u32x2*)(HB + (size_t)mrow * 512 + head * 128 + vq * 32 + nt * 16 + fq * 4) = w2; }
;         }
; #pragma unroll
;         for (int i = 0; i < 3; ++i) Ct[i] *= carry;
;         mm16<3, 4>(KTs + wave * 16 * 136, 136, VWs, 136, Ct, fr, fq);
;         __syncthreads();
; #pragma unroll
;         for (int nt = 0; nt < 3; ++nt)
; #pragma unroll
;             for (int e = 0; e < 4; ++e) Cs[(nt * 16 + fq * 4 + e) * 136 + wave * 16 + fr] = (bf16_t)f2bf(Ct[nt][e]);
	v_fmac_f32_e32 v59, v58, v60
	v_mul_f32_e32 v60, 0xbfb8aa3b, v61
	v_exp_f32_e32 v60, v60
	s_nop 0
	v_max_f32_e64 v59, |v59|, v60
	v_div_scale_f32 v60, s[2:3], v59, v59, 1.0
	v_rcp_f32_e32 v61, v60
	s_movk_i32 s2, 0xff
	v_fma_f32 v62, -v60, v61, 1.0
	v_fmac_f32_e32 v61, v62, v61
	v_div_scale_f32 v62, vcc, 1.0, v59, 1.0
	v_mul_f32_e32 v63, v62, v61
	v_fma_f32 v72, -v60, v63, v62
	v_fmac_f32_e32 v63, v72, v61
	v_fma_f32 v60, -v60, v63, v62
	v_div_fmas_f32 v60, v60, v61, v63
	v_div_fixup_f32 v60, v60, v59, 1.0
	v_add_u32_e32 v59, s35, v103
	v_cmp_lt_i32_e32 vcc, s2, v59
	s_addk_i32 s35, 0x80
	s_cmpk_lg_i32 s35, 0x1100
	v_cndmask_b32_e32 v61, v253, v196, vcc
	v_add_u32_e32 v61, v61, v132
	v_cndmask_b32_e64 v59, v61, v59, s[42:43]
	v_pk_fma_f32 v[54:55], v[58:59], v[64:65], v[54:55] op_sel_hi:[0,1,1]
	v_pk_mul_f32 v[54:55], v[54:55], v[60:61] op_sel_hi:[1,0]
	v_add_u32_e32 v62, s34, v59
	v_pk_fma_f32 v[56:57], v[58:59], v[66:67], v[56:57] op_sel_hi:[0,1,1]
	v_bfe_u32 v59, v54, 16, 1
	v_add3_u32 v54, v54, v59, s31
	v_bfe_u32 v59, v55, 16, 1
	v_pk_mul_f32 v[56:57], v[56:57], v[60:61] op_sel_hi:[1,0]
	v_lshrrev_b32_e32 v54, 16, v54
	v_add3_u32 v55, v55, v59, s31
	v_and_or_b32 v54, v55, s0, v54
	v_ashrrev_i32_e32 v63, 31, v62
	v_lshlrev_b64 v[62:63], 10, v[62:63]
	v_pk_fma_f32 v[50:51], v[58:59], v[68:69], v[50:51] op_sel_hi:[0,1,1]
	v_lshl_add_u64 v[62:63], v[90:91], 0, v[62:63]
	v_cvt_pk_bf16_f32 v55, v56, v57
	v_pk_mul_f32 v[50:51], v[50:51], v[60:61] op_sel_hi:[1,0]
	global_store_dwordx2 v[62:63], v[54:55], off
	v_pk_fma_f32 v[52:53], v[58:59], v[70:71], v[52:53] op_sel_hi:[0,1,1]
	v_pk_mul_f32 v[52:53], v[52:53], v[60:61] op_sel_hi:[1,0]
	v_cvt_pk_bf16_f32 v50, v50, v51
	v_cvt_pk_bf16_f32 v51, v52, v53
	global_store_dwordx2 v[62:63], v[50:51], off offset:32
	ds_read_b128 v[50:53], v89
	ds_read_b128 v[54:57], v137
	s_waitcnt lgkmcnt(0)
	v_mfma_f32_16x16x32_bf16 v[38:41], v[54:57], v[50:53], v[38:41]
	ds_read_b128 v[54:57], v137 offset:4352
	v_add_u32_e32 v132, 0xffffff80, v132
	s_waitcnt lgkmcnt(0)
	v_mfma_f32_16x16x32_bf16 v[42:45], v[54:57], v[50:53], v[42:45]
	ds_read_b128 v[54:57], v137 offset:8704
	s_waitcnt lgkmcnt(0)
	v_mfma_f32_16x16x32_bf16 v[46:49], v[54:57], v[50:53], v[46:49]
	ds_read_b128 v[50:53], v89 offset:64
	ds_read_b128 v[54:57], v137 offset:64
	s_waitcnt lgkmcnt(0)
	v_mfma_f32_16x16x32_bf16 v[38:41], v[54:57], v[50:53], v[38:41]
	ds_read_b128 v[54:57], v137 offset:4416
	s_waitcnt lgkmcnt(0)
	v_mfma_f32_16x16x32_bf16 v[42:45], v[54:57], v[50:53], v[42:45]
	ds_read_b128 v[54:57], v137 offset:8768
	s_waitcnt lgkmcnt(0)
	v_mfma_f32_16x16x32_bf16 v[46:49], v[54:57], v[50:53], v[46:49]
	ds_read_b128 v[50:53], v89 offset:128
	ds_read_b128 v[54:57], v137 offset:128
	s_waitcnt lgkmcnt(0)
	v_mfma_f32_16x16x32_bf16 v[38:41], v[54:57], v[50:53], v[38:41]
	ds_read_b128 v[54:57], v137 offset:4480
	s_waitcnt lgkmcnt(0)
	v_mfma_f32_16x16x32_bf16 v[42:45], v[54:57], v[50:53], v[42:45]
	ds_read_b128 v[54:57], v137 offset:8832
	s_waitcnt lgkmcnt(0)
	v_mfma_f32_16x16x32_bf16 v[46:49], v[54:57], v[50:53], v[46:49]
	ds_read_b128 v[50:53], v89 offset:192
	ds_read_b128 v[54:57], v137 offset:192
	s_waitcnt lgkmcnt(0)
	v_mfma_f32_16x16x32_bf16 v[38:41], v[54:57], v[50:53], v[38:41]
	ds_read_b128 v[54:57], v137 offset:4544
	s_waitcnt lgkmcnt(0)
	v_mfma_f32_16x16x32_bf16 v[42:45], v[54:57], v[50:53], v[42:45]
	ds_read_b128 v[54:57], v137 offset:8896
	s_waitcnt lgkmcnt(0)
	s_barrier
	v_mfma_f32_16x16x32_bf16 v[46:49], v[54:57], v[50:53], v[46:49]
	s_nop 0
	v_bfe_u32 v50, v38, 16, 1
	v_add3_u32 v50, v38, v50, s31
	ds_write_b16_d16_hi v139, v50
	v_bfe_u32 v50, v39, 16, 1
	v_add3_u32 v50, v39, v50, s31
	ds_write_b16_d16_hi v139, v50 offset:272
	v_bfe_u32 v50, v40, 16, 1
	v_add3_u32 v50, v40, v50, s31
	ds_write_b16_d16_hi v139, v50 offset:544
	v_bfe_u32 v50, v41, 16, 1
	v_add3_u32 v50, v41, v50, s31
	ds_write_b16_d16_hi v139, v50 offset:816
	v_bfe_u32 v50, v42, 16, 1
	v_add3_u32 v50, v42, v50, s31
	ds_write_b16_d16_hi v144, v50
	v_bfe_u32 v50, v43, 16, 1
	v_add3_u32 v50, v43, v50, s31
	ds_write_b16_d16_hi v139, v50 offset:4624
	v_bfe_u32 v50, v44, 16, 1
	v_add3_u32 v50, v44, v50, s31
	ds_write_b16_d16_hi v139, v50 offset:4896
	v_bfe_u32 v50, v45, 16, 1
	v_add3_u32 v50, v45, v50, s31
	ds_write_b16_d16_hi v139, v50 offset:5168
	v_bfe_u32 v50, v46, 16, 1
	v_add3_u32 v50, v46, v50, s31
	ds_write_b16_d16_hi v144, v50 offset:4352
	v_bfe_u32 v50, v47, 16, 1
	v_add3_u32 v50, v47, v50, s31
	ds_write_b16_d16_hi v139, v50 offset:8976
	v_bfe_u32 v50, v48, 16, 1
	v_add3_u32 v50, v48, v50, s31
	ds_write_b16_d16_hi v139, v50 offset:9248
	v_bfe_u32 v50, v49, 16, 1
	v_add3_u32 v50, v49, v50, s31
	ds_write_b16_d16_hi v139, v50 offset:9520
	s_cbranch_scc0 .LBB0_515

; #define LAS __attribute__((address_space(3)))
; DI unsigned pk2(float lo, float hi) { return f2bf(lo) | (f2bf(hi) << 16); }
; DI void mlstm_item(int j, int item, LAS unsigned char* lds) {
;     ...
;         for (int nt = 0; nt < 8; ++nt) { const f32x4 g4 = *(const LAS f32x4*)(gs + nt * 16 + fq * 4); float o[4];
; #pragma unroll
;             for (int e = 0; e < 4; ++e) { const int sc = nt * 16 + fq * 4 + e; const float w = __expf(fminf(g4[e] - at, 0.f)); o[e] = (sc <= trow) ? s[nt][e] * scale * w : 0.f; }
;             u32x2 w2; w2.x = pk2(o[0], o[1]); w2.y = pk2(o[2], o[3]);
;             *(LAS u32x2*)(KPs + trow * 136 + nt * 16 + fq * 4) = w2; }
.LBB0_545:
	s_or_b64 exec, exec, s[2:3]
	v_cvt_pk_bf16_f32 v80, v148, v147
	v_cvt_pk_bf16_f32 v81, v79, v78
	ds_write_b64 v106, v[80:81]
	ds_read_b128 v[78:81], v105 offset:64
	s_waitcnt lgkmcnt(2)
	v_mov_b32_e32 v82, 0
	v_mov_b32_e32 v83, 0
	s_and_saveexec_b64 s[2:3], s[64:65]
	s_cbranch_execz .LBB0_547
	s_waitcnt lgkmcnt(0)
	v_sub_f32_e32 v78, v78, v95
	v_min_f32_e32 v78, 0, v78
	v_mul_f32_e32 v78, 0x3fb8aa3b, v78
	v_exp_f32_e32 v78, v78
	v_mul_f32_e32 v74, 0x3db504f3, v74
	v_mul_f32_e32 v83, v74, v78

; #define LAS __attribute__((address_space(3)))
; DI unsigned pk2(float lo, float hi) { return f2bf(lo) | (f2bf(hi) << 16); }
; DI void mlstm_item(int j, int item, LAS unsigned char* lds) {
;     ...
;         for (int nt = 0; nt < 8; ++nt) { const f32x4 g4 = *(const LAS f32x4*)(gs + nt * 16 + fq * 4); float o[4];
; #pragma unroll
;             for (int e = 0; e < 4; ++e) { const int sc = nt * 16 + fq * 4 + e; const float w = __expf(fminf(g4[e] - at, 0.f)); o[e] = (sc <= trow) ? s[nt][e] * scale * w : 0.f; }
;             u32x2 w2; w2.x = pk2(o[0], o[1]); w2.y = pk2(o[2], o[3]);
;             *(LAS u32x2*)(KPs + trow * 136 + nt * 16 + fq * 4) = w2; }
.LBB0_553:
	s_or_b64 exec, exec, s[2:3]
	v_cvt_pk_bf16_f32 v76, v83, v82
	v_cvt_pk_bf16_f32 v77, v75, v74
	ds_write_b64 v106, v[76:77] offset:32
	ds_read_b128 v[74:77], v105 offset:128
	s_waitcnt lgkmcnt(2)
	v_mov_b32_e32 v78, 0
	v_mov_b32_e32 v79, 0
	s_and_saveexec_b64 s[2:3], s[72:73]
	s_cbranch_execz .LBB0_555
	s_waitcnt lgkmcnt(0)
	v_sub_f32_e32 v74, v74, v95
	v_min_f32_e32 v74, 0, v74
	v_mul_f32_e32 v74, 0x3fb8aa3b, v74
	v_exp_f32_e32 v74, v74
	v_mul_f32_e32 v70, 0x3db504f3, v70
	v_mul_f32_e32 v79, v70, v74

; #define LAS __attribute__((address_space(3)))
; DI unsigned pk2(float lo, float hi) { return f2bf(lo) | (f2bf(hi) << 16); }
; DI void mlstm_item(int j, int item, LAS unsigned char* lds) {
;     ...
;         for (int nt = 0; nt < 8; ++nt) { const f32x4 g4 = *(const LAS f32x4*)(gs + nt * 16 + fq * 4); float o[4];
; #pragma unroll
;             for (int e = 0; e < 4; ++e) { const int sc = nt * 16 + fq * 4 + e; const float w = __expf(fminf(g4[e] - at, 0.f)); o[e] = (sc <= trow) ? s[nt][e] * scale * w : 0.f; }
;             u32x2 w2; w2.x = pk2(o[0], o[1]); w2.y = pk2(o[2], o[3]);
;             *(LAS u32x2*)(KPs + trow * 136 + nt * 16 + fq * 4) = w2; }
.LBB0_561:
	s_or_b64 exec, exec, s[2:3]
	v_cvt_pk_bf16_f32 v72, v79, v78
	v_cvt_pk_bf16_f32 v73, v71, v70
	ds_write_b64 v106, v[72:73] offset:64
	ds_read_b128 v[70:73], v105 offset:192
	s_waitcnt lgkmcnt(2)
	v_mov_b32_e32 v74, 0
	v_mov_b32_e32 v75, 0
	s_and_saveexec_b64 s[2:3], s[80:81]
	s_cbranch_execz .LBB0_563
	s_waitcnt lgkmcnt(0)
	v_sub_f32_e32 v70, v70, v95
	v_min_f32_e32 v70, 0, v70
	v_mul_f32_e32 v70, 0x3fb8aa3b, v70
	v_exp_f32_e32 v70, v70
	v_mul_f32_e32 v66, 0x3db504f3, v66
	v_mul_f32_e32 v75, v66, v70

; #define LAS __attribute__((address_space(3)))
; DI unsigned pk2(float lo, float hi) { return f2bf(lo) | (f2bf(hi) << 16); }
; DI void mlstm_item(int j, int item, LAS unsigned char* lds) {
;     ...
;         for (int nt = 0; nt < 8; ++nt) { const f32x4 g4 = *(const LAS f32x4*)(gs + nt * 16 + fq * 4); float o[4];
; #pragma unroll
;             for (int e = 0; e < 4; ++e) { const int sc = nt * 16 + fq * 4 + e; const float w = __expf(fminf(g4[e] - at, 0.f)); o[e] = (sc <= trow) ? s[nt][e] * scale * w : 0.f; }
;             u32x2 w2; w2.x = pk2(o[0], o[1]); w2.y = pk2(o[2], o[3]);
;             *(LAS u32x2*)(KPs + trow * 136 + nt * 16 + fq * 4) = w2; }
.LBB0_569:
	s_or_b64 exec, exec, s[2:3]
	v_cvt_pk_bf16_f32 v68, v75, v74
	v_cvt_pk_bf16_f32 v69, v67, v66
	ds_write_b64 v106, v[68:69] offset:96
	ds_read_b128 v[66:69], v105 offset:256
	s_waitcnt lgkmcnt(2)
	v_mov_b32_e32 v70, 0
	v_mov_b32_e32 v71, 0
	s_and_saveexec_b64 s[2:3], s[88:89]
	s_cbranch_execz .LBB0_571
	s_waitcnt lgkmcnt(0)
	v_sub_f32_e32 v66, v66, v95
	v_min_f32_e32 v66, 0, v66
	v_mul_f32_e32 v66, 0x3fb8aa3b, v66
	v_exp_f32_e32 v66, v66
	v_mul_f32_e32 v62, 0x3db504f3, v62
	v_mul_f32_e32 v71, v62, v66

; #define LAS __attribute__((address_space(3)))
; DI unsigned pk2(float lo, float hi) { return f2bf(lo) | (f2bf(hi) << 16); }
; DI void mlstm_item(int j, int item, LAS unsigned char* lds) {
;     ...
;         for (int nt = 0; nt < 8; ++nt) { const f32x4 g4 = *(const LAS f32x4*)(gs + nt * 16 + fq * 4); float o[4];
; #pragma unroll
;             for (int e = 0; e < 4; ++e) { const int sc = nt * 16 + fq * 4 + e; const float w = __expf(fminf(g4[e] - at, 0.f)); o[e] = (sc <= trow) ? s[nt][e] * scale * w : 0.f; }
;             u32x2 w2; w2.x = pk2(o[0], o[1]); w2.y = pk2(o[2], o[3]);
;             *(LAS u32x2*)(KPs + trow * 136 + nt * 16 + fq * 4) = w2; }
.LBB0_577:
	s_or_b64 exec, exec, s[2:3]
	v_cvt_pk_bf16_f32 v64, v71, v70
	v_cvt_pk_bf16_f32 v65, v63, v62
	ds_write_b64 v106, v[64:65] offset:128
	ds_read_b128 v[62:65], v105 offset:320
	s_waitcnt lgkmcnt(2)
	v_mov_b32_e32 v66, 0
	v_mov_b32_e32 v67, 0
	s_and_saveexec_b64 s[2:3], s[96:97]
	s_cbranch_execz .LBB0_579
	s_waitcnt lgkmcnt(0)
	v_sub_f32_e32 v62, v62, v95
	v_min_f32_e32 v62, 0, v62
	v_mul_f32_e32 v62, 0x3fb8aa3b, v62
	v_exp_f32_e32 v62, v62
	v_mul_f32_e32 v58, 0x3db504f3, v58
	v_mul_f32_e32 v67, v58, v62

; #define LAS __attribute__((address_space(3)))
; DI unsigned pk2(float lo, float hi) { return f2bf(lo) | (f2bf(hi) << 16); }
; DI void mlstm_item(int j, int item, LAS unsigned char* lds) {
;     ...
;         for (int nt = 0; nt < 8; ++nt) { const f32x4 g4 = *(const LAS f32x4*)(gs + nt * 16 + fq * 4); float o[4];
; #pragma unroll
;             for (int e = 0; e < 4; ++e) { const int sc = nt * 16 + fq * 4 + e; const float w = __expf(fminf(g4[e] - at, 0.f)); o[e] = (sc <= trow) ? s[nt][e] * scale * w : 0.f; }
;             u32x2 w2; w2.x = pk2(o[0], o[1]); w2.y = pk2(o[2], o[3]);
;             *(LAS u32x2*)(KPs + trow * 136 + nt * 16 + fq * 4) = w2; }
.LBB0_585:
	s_or_b64 exec, exec, s[2:3]
	v_cvt_pk_bf16_f32 v60, v67, v66
	v_cvt_pk_bf16_f32 v61, v59, v58
	ds_write_b64 v106, v[60:61] offset:160
	ds_read_b128 v[58:61], v105 offset:384
	s_waitcnt lgkmcnt(2)
	v_mov_b32_e32 v62, 0
	v_mov_b32_e32 v63, 0
	s_and_saveexec_b64 s[2:3], s[10:11]
	s_cbranch_execz .LBB0_587
	s_waitcnt lgkmcnt(0)
	v_sub_f32_e32 v58, v58, v95
	v_min_f32_e32 v58, 0, v58
	v_mul_f32_e32 v58, 0x3fb8aa3b, v58
	v_exp_f32_e32 v58, v58
	v_mul_f32_e32 v54, 0x3db504f3, v54
	v_mul_f32_e32 v63, v54, v58

; #define LAS __attribute__((address_space(3)))
; DI unsigned pk2(float lo, float hi) { return f2bf(lo) | (f2bf(hi) << 16); }
; DI void mlstm_item(int j, int item, LAS unsigned char* lds) {
;     ...
;         for (int nt = 0; nt < 8; ++nt) { const f32x4 g4 = *(const LAS f32x4*)(gs + nt * 16 + fq * 4); float o[4];
; #pragma unroll
;             for (int e = 0; e < 4; ++e) { const int sc = nt * 16 + fq * 4 + e; const float w = __expf(fminf(g4[e] - at, 0.f)); o[e] = (sc <= trow) ? s[nt][e] * scale * w : 0.f; }
;             u32x2 w2; w2.x = pk2(o[0], o[1]); w2.y = pk2(o[2], o[3]);
;             *(LAS u32x2*)(KPs + trow * 136 + nt * 16 + fq * 4) = w2; }
.LBB0_593:
	s_or_b64 exec, exec, s[2:3]
	v_cvt_pk_bf16_f32 v56, v63, v62
	v_cvt_pk_bf16_f32 v57, v55, v54
	ds_write_b64 v106, v[56:57] offset:192
	ds_read_b128 v[54:57], v105 offset:448
	s_waitcnt lgkmcnt(2)
	v_mov_b32_e32 v58, 0
	v_mov_b32_e32 v59, 0
	s_and_saveexec_b64 s[2:3], s[18:19]
	s_cbranch_execz .LBB0_595
	s_waitcnt lgkmcnt(0)
	v_sub_f32_e32 v54, v54, v95
	v_min_f32_e32 v54, 0, v54
	v_mul_f32_e32 v54, 0x3fb8aa3b, v54
	v_exp_f32_e32 v54, v54
	v_mul_f32_e32 v50, 0x3db504f3, v50
	v_mul_f32_e32 v59, v50, v54

; DI unsigned pk2(float lo, float hi) { return f2bf(lo) | (f2bf(hi) << 16); }
; DI void attn_tile(int j, int tile, LAS unsigned char* lds) {
;     ...
;     { const size_t mrow = (size_t)b * T + tq0 + wave * 16 + fr;
; #pragma unroll
;       for (int g = 0; g < 4; ++g) { const float inv = 1.f / lr[g];
; #pragma unroll
;           for (int nt = 0; nt < 4; ++nt) { const f32x4 o = O[g][nt] * inv; u32x2 w2; w2.x = pk2(o[0], o[1]); w2.y = pk2(o[2], o[3]);
;               *(u32x2*)(Pb + mrow * PW + 512 + (kvh * 4 + g) * 64 + nt * 16 + fq * 4) = w2; } } }
;     __syncthreads();
.LBB0_603:
	s_ashr_i32 s19, s18, 31
	s_add_u32 s2, s12, s7
	s_addc_u32 s3, s13, 0
	s_waitcnt vmcnt(0)
	v_or_b32_e32 v68, s2, v198
	v_mov_b32_e32 v69, s3
	v_lshl_add_u64 v[68:69], v[68:69], 0, s[18:19]
	v_mov_b64_e32 v[70:71], s[10:11]
	v_div_scale_f32 v72, s[2:3], v105, v105, 1.0
	v_mad_u64_u32 v[70:71], s[2:3], v68, s78, v[70:71]
	v_rcp_f32_e32 v73, v72
	v_mov_b32_e32 v0, v71
	v_mad_u64_u32 v[68:69], s[2:3], v69, s78, v[0:1]
	v_mov_b32_e32 v71, v68
	v_lshlrev_b32_e32 v0, 1, v199
	v_lshl_add_u64 v[68:69], v[70:71], 0, v[0:1]
	v_fma_f32 v0, -v72, v73, 1.0
	v_fmac_f32_e32 v73, v0, v73
	v_div_scale_f32 v0, vcc, 1.0, v105, 1.0
	v_mul_f32_e32 v70, v0, v73
	v_fma_f32 v71, -v72, v70, v0
	v_fmac_f32_e32 v70, v71, v73
	v_fma_f32 v0, -v72, v70, v0
	v_div_fmas_f32 v0, v0, v73, v70
	v_div_fixup_f32 v0, v0, v105, 1.0
	v_pk_mul_f32 v[64:65], v[64:65], v[0:1] op_sel_hi:[1,0]
	v_pk_mul_f32 v[66:67], v[66:67], v[0:1] op_sel_hi:[1,0]
	v_cvt_pk_bf16_f32 v64, v64, v65
	s_mov_b32 s7, s81
	v_lshl_add_u64 v[68:69], v[68:69], 0, s[6:7]
	v_cvt_pk_bf16_f32 v65, v66, v67
	v_pk_mul_f32 v[60:61], v[60:61], v[0:1] op_sel_hi:[1,0]
	global_store_dwordx2 v[68:69], v[64:65], off offset:1024
	v_pk_mul_f32 v[62:63], v[62:63], v[0:1] op_sel_hi:[1,0]
	v_cvt_pk_bf16_f32 v60, v60, v61
	v_cvt_pk_bf16_f32 v61, v62, v63
	v_pk_mul_f32 v[56:57], v[56:57], v[0:1] op_sel_hi:[1,0]
	global_store_dwordx2 v[68:69], v[60:61], off offset:1056
	v_pk_mul_f32 v[52:53], v[52:53], v[0:1] op_sel_hi:[1,0]
	v_pk_mul_f32 v[58:59], v[58:59], v[0:1] op_sel_hi:[1,0]
	v_pk_mul_f32 v[54:55], v[54:55], v[0:1] op_sel_hi:[1,0]
	v_cvt_pk_bf16_f32 v56, v56, v57
	v_cvt_pk_bf16_f32 v52, v52, v53
	v_bfe_u32 v0, v54, 16, 1
	v_cvt_pk_bf16_f32 v57, v58, v59
	v_add3_u32 v0, v54, v0, s31
	v_div_scale_f32 v54, s[2:3], v104, v104, 1.0
	global_store_dwordx2 v[68:69], v[56:57], off offset:1088
	v_rcp_f32_e32 v56, v54
	v_bfe_u32 v53, v55, 16, 1
	v_lshrrev_b32_e32 v0, 16, v0
	v_add3_u32 v53, v55, v53, s31
	v_and_or_b32 v53, v53, s0, v0
	v_fma_f32 v0, -v54, v56, 1.0
	v_fmac_f32_e32 v56, v0, v56
	v_div_scale_f32 v0, vcc, 1.0, v104, 1.0
	global_store_dwordx2 v[68:69], v[52:53], off offset:1120
	v_mul_f32_e32 v52, v0, v56
	v_fma_f32 v53, -v54, v52, v0
	v_fmac_f32_e32 v52, v53, v56
	v_fma_f32 v0, -v54, v52, v0
	v_div_fmas_f32 v0, v0, v56, v52
	v_div_fixup_f32 v0, v0, v104, 1.0
	v_pk_mul_f32 v[48:49], v[48:49], v[0:1] op_sel_hi:[1,0]
	v_pk_mul_f32 v[50:51], v[50:51], v[0:1] op_sel_hi:[1,0]
	v_cvt_pk_bf16_f32 v48, v48, v49
	v_cvt_pk_bf16_f32 v49, v50, v51
	v_pk_mul_f32 v[44:45], v[44:45], v[0:1] op_sel_hi:[1,0]
	global_store_dwordx2 v[68:69], v[48:49], off offset:1152
	v_pk_mul_f32 v[46:47], v[46:47], v[0:1] op_sel_hi:[1,0]
	v_cvt_pk_bf16_f32 v44, v44, v45
	v_cvt_pk_bf16_f32 v45, v46, v47
	v_pk_mul_f32 v[40:41], v[40:41], v[0:1] op_sel_hi:[1,0]
	global_store_dwordx2 v[68:69], v[44:45], off offset:1184
	v_pk_mul_f32 v[36:37], v[36:37], v[0:1] op_sel_hi:[1,0]
	v_pk_mul_f32 v[42:43], v[42:43], v[0:1] op_sel_hi:[1,0]
	v_pk_mul_f32 v[38:39], v[38:39], v[0:1] op_sel_hi:[1,0]
	v_cvt_pk_bf16_f32 v40, v40, v41
	v_cvt_pk_bf16_f32 v36, v36, v37
	v_bfe_u32 v0, v38, 16, 1
	v_cvt_pk_bf16_f32 v41, v42, v43
	v_add3_u32 v0, v38, v0, s31
	v_div_scale_f32 v38, s[2:3], v3, v3, 1.0
	global_store_dwordx2 v[68:69], v[40:41], off offset:1216
	v_rcp_f32_e32 v40, v38
	v_bfe_u32 v37, v39, 16, 1
	v_lshrrev_b32_e32 v0, 16, v0
	v_add3_u32 v37, v39, v37, s31
	v_and_or_b32 v37, v37, s0, v0
	v_fma_f32 v0, -v38, v40, 1.0
	v_fmac_f32_e32 v40, v0, v40
	v_div_scale_f32 v0, vcc, 1.0, v3, 1.0
	global_store_dwordx2 v[68:69], v[36:37], off offset:1248
	v_mul_f32_e32 v36, v0, v40
	v_fma_f32 v37, -v38, v36, v0
	v_fmac_f32_e32 v36, v37, v40
	v_fma_f32 v0, -v38, v36, v0
	v_div_fmas_f32 v0, v0, v40, v36
	v_div_fixup_f32 v0, v0, v3, 1.0
	v_pk_mul_f32 v[16:17], v[0:1], v[16:17] op_sel_hi:[0,1]
	v_pk_mul_f32 v[18:19], v[0:1], v[18:19] op_sel_hi:[0,1]
	v_cvt_pk_bf16_f32 v16, v16, v17
	v_pk_mul_f32 v[12:13], v[0:1], v[12:13] op_sel_hi:[0,1]
	v_cvt_pk_bf16_f32 v17, v18, v19
	v_pk_mul_f32 v[14:15], v[0:1], v[14:15] op_sel_hi:[0,1]
	v_cvt_pk_bf16_f32 v12, v12, v13
	v_pk_mul_f32 v[8:9], v[0:1], v[8:9] op_sel_hi:[0,1]
	v_cvt_pk_bf16_f32 v13, v14, v15
	v_pk_mul_f32 v[10:11], v[0:1], v[10:11] op_sel_hi:[0,1]
	v_cvt_pk_bf16_f32 v8, v8, v9
	v_pk_mul_f32 v[4:5], v[0:1], v[4:5] op_sel_hi:[0,1]
	v_pk_mul_f32 v[6:7], v[0:1], v[6:7] op_sel_hi:[0,1]
	v_cvt_pk_bf16_f32 v9, v10, v11
	v_cvt_pk_bf16_f32 v4, v4, v5
	v_bfe_u32 v0, v6, 16, 1
	v_add3_u32 v0, v6, v0, s31
	v_div_scale_f32 v6, s[2:3], v2, v2, 1.0
	global_store_dwordx2 v[68:69], v[8:9], off offset:1344
	v_rcp_f32_e32 v8, v6
	v_bfe_u32 v3, v7, 16, 1
	v_lshrrev_b32_e32 v0, 16, v0
	v_add3_u32 v3, v7, v3, s31
	v_and_or_b32 v5, v3, s0, v0
	v_fma_f32 v0, -v6, v8, 1.0
	v_fmac_f32_e32 v8, v0, v8
	v_div_scale_f32 v0, vcc, 1.0, v2, 1.0
	v_mul_f32_e32 v3, v0, v8
	global_store_dwordx2 v[68:69], v[4:5], off offset:1376
	v_fma_f32 v4, -v6, v3, v0
	v_fmac_f32_e32 v3, v4, v8
	v_fma_f32 v0, -v6, v3, v0
	v_div_fmas_f32 v0, v0, v8, v3
	v_div_fixup_f32 v0, v0, v2, 1.0
	v_pk_mul_f32 v[4:5], v[0:1], v[28:29] op_sel_hi:[0,1]
	v_pk_mul_f32 v[2:3], v[0:1], v[30:31] op_sel_hi:[0,1]
	v_cvt_pk_bf16_f32 v4, v4, v5
	v_cvt_pk_bf16_f32 v5, v2, v3
	global_store_dwordx2 v[68:69], v[4:5], off offset:1408
	v_pk_mul_f32 v[4:5], v[0:1], v[24:25] op_sel_hi:[0,1]
	v_pk_mul_f32 v[2:3], v[0:1], v[26:27] op_sel_hi:[0,1]
	v_cvt_pk_bf16_f32 v4, v4, v5
	v_cvt_pk_bf16_f32 v5, v2, v3
	global_store_dwordx2 v[68:69], v[4:5], off offset:1440
	v_pk_mul_f32 v[4:5], v[0:1], v[20:21] op_sel_hi:[0,1]
	v_pk_mul_f32 v[2:3], v[0:1], v[22:23] op_sel_hi:[0,1]
	v_cvt_pk_bf16_f32 v4, v4, v5
	v_cvt_pk_bf16_f32 v5, v2, v3
	global_store_dwordx2 v[68:69], v[4:5], off offset:1472
	v_pk_mul_f32 v[4:5], v[0:1], v[32:33] op_sel_hi:[0,1]
	v_pk_mul_f32 v[2:3], v[0:1], v[34:35] op_sel_hi:[0,1]
	v_cvt_pk_bf16_f32 v4, v4, v5
	v_readlane_b32 s2, v255, 29
	s_add_i32 s28, s28, s2
	v_cvt_pk_bf16_f32 v5, v2, v3
	s_cmpk_gt_i32 s28, 0x21f
	global_store_dwordx2 v[68:69], v[16:17], off offset:1280
	global_store_dwordx2 v[68:69], v[12:13], off offset:1312
	global_store_dwordx2 v[68:69], v[4:5], off offset:1504
	s_waitcnt lgkmcnt(0)
	s_barrier
	s_cbranch_scc1 .LBB0_616

; DI unsigned pk2(float lo, float hi) { return f2bf(lo) | (f2bf(hi) << 16); }
; #define BIDX() sgpr_opaque((int)__builtin_amdgcn_workgroup_id_x())
; DI const float* modp(const unsigned char* ws, int layer, int who, int idx) { return (const float*)(ws + WS_MOD) + ((size_t)(layer * 9 + who) * 6 + idx) * D; }
; DI void phase_norm(int layer, const float* g, int sidx, bf16_t* dst, bool first) {
;     ...
;     for (int m0 = BIDX() * 8 + wave; m0 < M; m0 += 2 * nw) {
;         const int m1 = m0 + nw; const bool has1 = m1 < M; const int m1c = has1 ? m1 : m0;
;         const float* z0 = zrow_src(zcs, zls, m0); const float* z1 = zrow_src(zcs, zls, m1c);
;         f32x4 v0[4], v1[4]; float ss0 = 0.f, ss1 = 0.f;
; #pragma unroll
;         for (int j = 0; j < 4; ++j) { v0[j] = *(const f32x4*)(z0 + 4 * lane + 256 * j); v1[j] = *(const f32x4*)(z1 + 4 * lane + 256 * j); }
; #pragma unroll
;         for (int j = 0; j < 4; ++j) { ss0 += v0[j][0] * v0[j][0] + v0[j][1] * v0[j][1] + v0[j][2] * v0[j][2] + v0[j][3] * v0[j][3]; ss1 += v1[j][0] * v1[j][0] + v1[j][1] * v1[j][1] + v1[j][2] * v1[j][2] + v1[j][3] * v1[j][3]; }
; #pragma unroll
;         for (int o = 1; o < 64; o <<= 1) { ss0 += __shfl_xor(ss0, o); ss1 += __shfl_xor(ss1, o); }
; #pragma unroll
;         for (int r = 0; r < 2; ++r) {
;             if (r == 1 && !has1) break;
;             const int m = r ? m1 : m0; const int b = m / T, t = m - b * T; const int who = t < LC ? 8 : b;
;             const float* sh = modp(ws, layer, who, sidx); const float* sc = modp(ws, layer, who, sidx + 1);
;             const float rstd = rsqrtf((r ? ss1 : ss0) * (1.f / D) + 1e-6f);
; #pragma unroll
;             for (int j = 0; j < 4; ++j) { const int c = 4 * lane + 256 * j;
;                 const f32x4 gg = *(const f32x4*)(g + c), s1 = *(const f32x4*)(sc + c), s0 = *(const f32x4*)(sh + c);
;                 f32x4 y = (r ? v1[j] : v0[j]) * rstd * gg; y = y * (s1 + 1.f) + s0;
;                 u32x2 w; w.x = pk2(y[0], y[1]); w.y = pk2(y[2], y[3]);
;                 *(u32x2*)(dst + (size_t)m * D + c) = w; }
.LBB0_759:
	s_mov_b32 s2, 0x78787879
	v_mul_hi_i32 v0, v30, s2
	v_lshrrev_b32_e32 v2, 31, v0
	v_ashrrev_i32_e32 v0, 11, v0
	v_add_u32_e32 v3, v0, v2
	s_movk_i32 s2, 0xef00
	v_mad_i32_i24 v0, v3, s2, v30
	s_movk_i32 s2, 0x100
	v_cmp_gt_i32_e64 s[4:5], s2, v0
	s_movk_i32 s2, 0xff
	v_cmp_lt_i32_e32 vcc, s2, v0
	s_and_saveexec_b64 s[2:3], vcc
	s_xor_b64 s[2:3], exec, s[2:3]
	v_mul_i32_i24_e32 v0, 0xffffef00, v3
	v_lshl_add_u32 v0, v3, 12, v0
	s_movk_i32 s6, 0xff00
	v_add3_u32 v6, v30, v0, s6
	s_or_saveexec_b64 s[2:3], s[2:3]
	s_waitcnt lgkmcnt(0)
	v_mov_b64_e32 v[8:9], s[12:13]
	s_xor_b64 exec, exec, s[2:3]
	v_lshl_add_u32 v6, v3, 8, v0
	v_mov_b64_e32 v[8:9], s[8:9]
	s_or_b64 exec, exec, s[2:3]
	v_add_u32_e32 v46, s22, v30
	s_mov_b32 s2, 0x8800
	v_cmp_gt_i32_e32 vcc, s2, v46
	s_mov_b32 s2, 0x78787879
	s_nop 0
	v_cndmask_b32_e32 v2, v30, v46, vcc
	v_mul_hi_i32 v0, v2, s2
	v_lshrrev_b32_e32 v4, 31, v0
	v_ashrrev_i32_e32 v0, 11, v0
	v_add_u32_e32 v0, v0, v4
	s_movk_i32 s2, 0xef00
	v_mad_i32_i24 v7, v0, s2, v2
	s_movk_i32 s2, 0xff
	v_cmp_lt_i32_e64 s[6:7], s2, v7
	s_and_saveexec_b64 s[2:3], s[6:7]
	s_xor_b64 s[2:3], exec, s[2:3]
	v_lshlrev_b32_e32 v0, 12, v0
	s_movk_i32 s6, 0xff00
	v_add3_u32 v2, v0, v7, s6
	s_or_saveexec_b64 s[2:3], s[2:3]
	v_mov_b64_e32 v[4:5], s[12:13]
	s_xor_b64 exec, exec, s[2:3]
	v_lshl_add_u32 v2, v0, 8, v7
	v_mov_b64_e32 v[4:5], s[8:9]
	s_or_b64 exec, exec, s[2:3]
	v_ashrrev_i32_e32 v7, 31, v6
	v_lshlrev_b64 v[6:7], 12, v[6:7]
	v_lshl_add_u64 v[6:7], v[8:9], 0, v[6:7]
	v_lshlrev_b32_e32 v0, 2, v32
	v_lshl_add_u64 v[6:7], v[6:7], 0, v[0:1]
	global_load_dwordx4 v[54:57], v[6:7], off
	global_load_dwordx4 v[26:29], v[6:7], off offset:1024
	global_load_dwordx4 v[14:17], v[6:7], off offset:2048
	s_nop 0
	global_load_dwordx4 v[6:9], v[6:7], off offset:3072
	v_cndmask_b32_e64 v3, v3, 8, s[4:5]
	v_add_u32_e32 v3, s23, v3
	v_mul_i32_i24_e32 v10, 6, v3
	v_ashrrev_i32_e32 v11, 31, v10
	v_lshlrev_b64 v[10:11], 12, v[10:11]
	v_lshl_add_u64 v[10:11], s[14:15], 0, v[10:11]
	s_mov_b64 s[2:3], 0x1000
	v_lshl_add_u64 v[70:71], v[10:11], 0, s[2:3]
	v_lshl_add_u64 v[12:13], v[70:71], 0, v[0:1]
	global_load_dwordx4 v[58:61], v[12:13], off
	global_load_dwordx4 v[62:65], v[34:35], off
	v_lshl_add_u64 v[72:73], v[10:11], 0, v[0:1]
	global_load_dwordx4 v[66:69], v[72:73], off
	s_mov_b32 s2, 0x800000
	v_mov_b32_e32 v41, v1
	s_waitcnt vmcnt(6)
	v_mov_b32_e32 v12, v55
	s_waitcnt vmcnt(5)
	v_mov_b32_e32 v13, v27
	v_mov_b32_e32 v10, v54
	v_mov_b32_e32 v11, v26
	s_waitcnt vmcnt(4)
	v_mov_b32_e32 v24, v15
	s_waitcnt vmcnt(3)
	v_mov_b32_e32 v25, v7
	v_pk_mul_f32 v[12:13], v[12:13], v[12:13]
	v_mov_b32_e32 v18, v56
	v_mov_b32_e32 v19, v28
	v_mov_b32_e32 v22, v14
	v_mov_b32_e32 v23, v6
	v_pk_mul_f32 v[24:25], v[24:25], v[24:25]
	v_pk_fma_f32 v[10:11], v[10:11], v[10:11], v[12:13]
	v_mov_b32_e32 v20, v57
	v_mov_b32_e32 v21, v29
	v_mov_b32_e32 v74, v16
	v_mov_b32_e32 v75, v8
	v_pk_fma_f32 v[12:13], v[22:23], v[22:23], v[24:25]
	v_pk_fma_f32 v[10:11], v[18:19], v[18:19], v[10:11]
	v_mov_b32_e32 v76, v17
	v_mov_b32_e32 v77, v9
	v_pk_fma_f32 v[12:13], v[74:75], v[74:75], v[12:13]
	v_pk_fma_f32 v[10:11], v[20:21], v[20:21], v[10:11]
	v_pk_fma_f32 v[12:13], v[76:77], v[76:77], v[12:13]
	v_add_f32_e32 v3, v10, v11
	v_add_f32_e32 v3, v3, v12
	v_add_f32_e32 v3, v3, v13
	ds_bpermute_b32 v10, v33, v3
	s_waitcnt vmcnt(2)
	v_pk_add_f32 v[60:61], v[60:61], 1.0 op_sel_hi:[1,0]
	v_pk_add_f32 v[58:59], v[58:59], 1.0 op_sel_hi:[1,0]
	s_waitcnt lgkmcnt(0)
	v_add_f32_e32 v3, v3, v10
	ds_bpermute_b32 v10, v48, v3
	s_waitcnt lgkmcnt(0)
	v_add_f32_e32 v3, v3, v10
	ds_bpermute_b32 v10, v49, v3
	s_waitcnt lgkmcnt(0)
	v_add_f32_e32 v3, v3, v10
	ds_bpermute_b32 v10, v50, v3
	s_waitcnt lgkmcnt(0)
	v_add_f32_e32 v10, v3, v10
	ds_bpermute_b32 v11, v51, v10
	v_ashrrev_i32_e32 v3, 31, v2
	v_lshlrev_b64 v[2:3], 12, v[2:3]
	v_lshl_add_u64 v[2:3], v[4:5], 0, v[2:3]
	v_lshl_add_u64 v[2:3], v[2:3], 0, v[0:1]
	s_waitcnt lgkmcnt(0)
	v_add_f32_e32 v10, v10, v11
	ds_bpermute_b32 v11, v52, v10
	global_load_dwordx4 v[22:25], v[2:3], off
	global_load_dwordx4 v[18:21], v[2:3], off offset:1024
	s_waitcnt lgkmcnt(0)
	v_add_f32_e32 v4, v10, v11
	v_fmamk_f32 v4, v4, 0x3a800000, v183
	v_mul_f32_e32 v5, 0x4b800000, v4
	v_cmp_gt_f32_e64 s[4:5], s2, v4
	s_nop 1
	v_cndmask_b32_e64 v4, v4, v5, s[4:5]
	v_rsq_f32_e32 v31, v4
	global_load_dwordx4 v[10:13], v[2:3], off offset:2048
	s_nop 0
	global_load_dwordx4 v[2:5], v[2:3], off offset:3072
	v_mul_f32_e32 v43, 0x45800000, v31
	v_cndmask_b32_e64 v74, v31, v43, s[4:5]
	v_pk_mul_f32 v[56:57], v[56:57], v[74:75] op_sel_hi:[1,0]
	v_pk_mul_f32 v[54:55], v[54:55], v[74:75] op_sel_hi:[1,0]
	s_waitcnt vmcnt(5)
	v_pk_mul_f32 v[56:57], v[64:65], v[56:57]
	v_pk_mul_f32 v[54:55], v[62:63], v[54:55]
	s_waitcnt vmcnt(4)
	v_pk_fma_f32 v[56:57], v[60:61], v[56:57], v[68:69]
	v_pk_fma_f32 v[54:55], v[58:59], v[54:55], v[66:67]
	v_cvt_pk_bf16_f32 v54, v54, v55
	v_cvt_pk_bf16_f32 v55, v56, v57
	global_store_dwordx2 v[38:39], v[54:55], off
	global_load_dwordx4 v[54:57], v[34:35], off offset:1024
	v_lshl_add_u64 v[58:59], v[70:71], 0, v[40:41]
	global_load_dwordx4 v[58:61], v[58:59], off
	s_nop 0
	global_load_dwordx4 v[62:65], v[72:73], off offset:1024
	v_pk_mul_f32 v[28:29], v[28:29], v[74:75] op_sel_hi:[1,0]
	v_pk_mul_f32 v[26:27], v[26:27], v[74:75] op_sel_hi:[1,0]
	v_mov_b32_e32 v43, v1
	v_pk_mul_f32 v[16:17], v[16:17], v[74:75] op_sel_hi:[1,0]
	v_pk_mul_f32 v[14:15], v[14:15], v[74:75] op_sel_hi:[1,0]
	v_pk_mul_f32 v[8:9], v[8:9], v[74:75] op_sel_hi:[1,0]
	v_pk_mul_f32 v[6:7], v[6:7], v[74:75] op_sel_hi:[1,0]
	s_waitcnt vmcnt(2)
; DI unsigned pk2(float lo, float hi) { return f2bf(lo) | (f2bf(hi) << 16); }
; DI const float* modp(const unsigned char* ws, int layer, int who, int idx) { return (const float*)(ws + WS_MOD) + ((size_t)(layer * 9 + who) * 6 + idx) * D; }
; DI void phase_norm(int layer, const float* g, int sidx, bf16_t* dst, bool first) {
;     ...
;         for (int o = 1; o < 64; o <<= 1) { ss0 += __shfl_xor(ss0, o); ss1 += __shfl_xor(ss1, o); }
; #pragma unroll
;         for (int r = 0; r < 2; ++r) {
;             if (r == 1 && !has1) break;
;             const int m = r ? m1 : m0; const int b = m / T, t = m - b * T; const int who = t < LC ? 8 : b;
;             const float* sh = modp(ws, layer, who, sidx); const float* sc = modp(ws, layer, who, sidx + 1);
;             const float rstd = rsqrtf((r ? ss1 : ss0) * (1.f / D) + 1e-6f);
; #pragma unroll
;             for (int j = 0; j < 4; ++j) { const int c = 4 * lane + 256 * j;
;                 const f32x4 gg = *(const f32x4*)(g + c), s1 = *(const f32x4*)(sc + c), s0 = *(const f32x4*)(sh + c);
;                 f32x4 y = (r ? v1[j] : v0[j]) * rstd * gg; y = y * (s1 + 1.f) + s0;
;                 u32x2 w; w.x = pk2(y[0], y[1]); w.y = pk2(y[2], y[3]);
;                 *(u32x2*)(dst + (size_t)m * D + c) = w; }
	v_pk_mul_f32 v[26:27], v[54:55], v[26:27]
	v_pk_mul_f32 v[28:29], v[56:57], v[28:29]
	s_waitcnt vmcnt(1)
	v_pk_add_f32 v[54:55], v[60:61], 1.0 op_sel_hi:[1,0]
	v_pk_add_f32 v[56:57], v[58:59], 1.0 op_sel_hi:[1,0]
	s_waitcnt vmcnt(0)
	v_pk_fma_f32 v[28:29], v[54:55], v[28:29], v[64:65]
	v_pk_fma_f32 v[26:27], v[56:57], v[26:27], v[62:63]
	v_cvt_pk_bf16_f32 v26, v26, v27
	v_cvt_pk_bf16_f32 v27, v28, v29
	global_store_dwordx2 v[38:39], v[26:27], off offset:512
	global_load_dwordx4 v[26:29], v[34:35], off offset:2048
	v_lshl_add_u64 v[54:55], v[70:71], 0, v[42:43]
	global_load_dwordx4 v[54:57], v[54:55], off
	s_nop 0
	global_load_dwordx4 v[58:61], v[72:73], off offset:2048
	v_mov_b32_e32 v45, v1
	s_waitcnt vmcnt(2)
	v_pk_mul_f32 v[14:15], v[26:27], v[14:15]
	v_pk_mul_f32 v[16:17], v[28:29], v[16:17]
	s_waitcnt vmcnt(1)
	v_pk_add_f32 v[26:27], v[56:57], 1.0 op_sel_hi:[1,0]
	v_pk_add_f32 v[28:29], v[54:55], 1.0 op_sel_hi:[1,0]
	s_waitcnt vmcnt(0)
	v_pk_fma_f32 v[16:17], v[26:27], v[16:17], v[60:61]
	v_pk_fma_f32 v[14:15], v[28:29], v[14:15], v[58:59]
	v_cvt_pk_bf16_f32 v14, v14, v15
	v_cvt_pk_bf16_f32 v15, v16, v17
	global_store_dwordx2 v[38:39], v[14:15], off offset:1024
	global_load_dwordx4 v[26:29], v[34:35], off offset:3072
	v_lshl_add_u64 v[14:15], v[70:71], 0, v[44:45]
	global_load_dwordx4 v[54:57], v[14:15], off
	global_load_dwordx4 v[58:61], v[72:73], off offset:3072
	v_mul_f32_e32 v14, v23, v23
	v_mul_f32_e32 v15, v19, v19
	v_mul_f32_e32 v16, v11, v11
	v_fmac_f32_e32 v14, v22, v22
	v_fmac_f32_e32 v15, v18, v18
	v_mul_f32_e32 v17, v3, v3
	v_fmac_f32_e32 v16, v10, v10
	v_fmac_f32_e32 v14, v24, v24
	v_fmac_f32_e32 v15, v20, v20
	v_fmac_f32_e32 v17, v2, v2
	v_fmac_f32_e32 v16, v12, v12
	v_fmac_f32_e32 v14, v25, v25
	v_fmac_f32_e32 v15, v21, v21
	v_fmac_f32_e32 v17, v4, v4
	v_fmac_f32_e32 v16, v13, v13
	v_add_f32_e32 v14, v14, v15
	v_fmac_f32_e32 v17, v5, v5
	v_add_f32_e32 v14, v14, v16
	v_add_f32_e32 v14, v14, v17
	ds_bpermute_b32 v15, v33, v14
	s_waitcnt lgkmcnt(0)
	v_add_f32_e32 v14, v14, v15
	ds_bpermute_b32 v15, v48, v14
	s_waitcnt lgkmcnt(0)
	v_add_f32_e32 v14, v14, v15
	ds_bpermute_b32 v15, v49, v14
	s_waitcnt lgkmcnt(0)
	v_add_f32_e32 v14, v14, v15
	ds_bpermute_b32 v15, v50, v14
	s_waitcnt lgkmcnt(0)
	v_add_f32_e32 v14, v14, v15
	ds_bpermute_b32 v15, v51, v14
	s_waitcnt lgkmcnt(0)
	v_add_f32_e32 v14, v14, v15
	ds_bpermute_b32 v15, v52, v14
	s_waitcnt vmcnt(2)
	v_pk_mul_f32 v[6:7], v[6:7], v[26:27]
	v_pk_mul_f32 v[8:9], v[8:9], v[28:29]
	s_waitcnt vmcnt(1)
	v_pk_add_f32 v[16:17], v[56:57], 1.0 op_sel_hi:[1,0]
	v_pk_add_f32 v[26:27], v[54:55], 1.0 op_sel_hi:[1,0]
	s_waitcnt vmcnt(0)
	v_pk_fma_f32 v[8:9], v[8:9], v[16:17], v[60:61]
	v_pk_fma_f32 v[6:7], v[6:7], v[26:27], v[58:59]
	v_cvt_pk_bf16_f32 v6, v6, v7
	v_cvt_pk_bf16_f32 v7, v8, v9
	global_store_dwordx2 v[38:39], v[6:7], off offset:1536
	s_and_saveexec_b64 s[4:5], vcc
	s_cbranch_execz .LBB0_758
; DI unsigned pk2(float lo, float hi) { return f2bf(lo) | (f2bf(hi) << 16); }
; DI const float* modp(const unsigned char* ws, int layer, int who, int idx) { return (const float*)(ws + WS_MOD) + ((size_t)(layer * 9 + who) * 6 + idx) * D; }
; DI void phase_norm(int layer, const float* g, int sidx, bf16_t* dst, bool first) {
;     ...
;         for (int r = 0; r < 2; ++r) {
;             if (r == 1 && !has1) break;
;             const int m = r ? m1 : m0; const int b = m / T, t = m - b * T; const int who = t < LC ? 8 : b;
;             const float* sh = modp(ws, layer, who, sidx); const float* sc = modp(ws, layer, who, sidx + 1);
;             const float rstd = rsqrtf((r ? ss1 : ss0) * (1.f / D) + 1e-6f);
; #pragma unroll
;             for (int j = 0; j < 4; ++j) { const int c = 4 * lane + 256 * j;
;                 const f32x4 gg = *(const f32x4*)(g + c), s1 = *(const f32x4*)(sc + c), s0 = *(const f32x4*)(sh + c);
;                 f32x4 y = (r ? v1[j] : v0[j]) * rstd * gg; y = y * (s1 + 1.f) + s0;
;                 u32x2 w; w.x = pk2(y[0], y[1]); w.y = pk2(y[2], y[3]);
;                 *(u32x2*)(dst + (size_t)m * D + c) = w; }
	s_mov_b32 s2, 0x78787879
	v_mul_hi_i32 v6, v46, s2
	v_lshrrev_b32_e32 v7, 31, v6
	v_ashrrev_i32_e32 v6, 11, v6
	v_add_u32_e32 v6, v6, v7
	v_mul_i32_i24_e32 v7, 0xffffef00, v6
	v_add3_u32 v7, s22, v7, v30
	s_movk_i32 s2, 0xff
	v_cmp_lt_i32_e32 vcc, s2, v7
	s_mov_b64 s[2:3], 0x1000
	v_ashrrev_i32_e32 v47, 31, v46
	v_cndmask_b32_e32 v6, 8, v6, vcc
	v_add_u32_e32 v6, s23, v6
	v_mul_i32_i24_e32 v6, 6, v6
	v_ashrrev_i32_e32 v7, 31, v6
	v_lshlrev_b64 v[6:7], 12, v[6:7]
	v_lshl_add_u64 v[16:17], s[14:15], 0, v[6:7]
	v_lshl_add_u64 v[58:59], v[16:17], 0, s[2:3]
	v_lshl_add_u64 v[26:27], v[58:59], 0, v[0:1]
	global_load_dwordx4 v[6:9], v[34:35], off
	v_lshl_add_u64 v[60:61], v[16:17], 0, v[0:1]
	global_load_dwordx4 v[26:29], v[26:27], off
	s_waitcnt lgkmcnt(0)
	v_add_f32_e32 v0, v14, v15
	global_load_dwordx4 v[54:57], v[60:61], off
	v_fmamk_f32 v0, v0, 0x3a800000, v183
	s_mov_b32 s2, 0x800000
	v_mul_f32_e32 v14, 0x4b800000, v0
	v_cmp_gt_f32_e32 vcc, s2, v0
	s_nop 1
	v_cndmask_b32_e32 v0, v0, v14, vcc
	v_rsq_f32_e32 v0, v0
	v_lshlrev_b64 v[14:15], 11, v[46:47]
	v_lshl_add_u64 v[46:47], v[36:37], 0, v[14:15]
	v_mul_f32_e32 v14, 0x45800000, v0
	v_cndmask_b32_e32 v0, v0, v14, vcc
	v_pk_mul_f32 v[14:15], v[24:25], v[0:1] op_sel_hi:[1,0]
	v_pk_mul_f32 v[16:17], v[22:23], v[0:1] op_sel_hi:[1,0]
	v_pk_mul_f32 v[20:21], v[20:21], v[0:1] op_sel_hi:[1,0]
	v_pk_mul_f32 v[18:19], v[18:19], v[0:1] op_sel_hi:[1,0]
	v_pk_mul_f32 v[12:13], v[12:13], v[0:1] op_sel_hi:[1,0]
	v_pk_mul_f32 v[10:11], v[10:11], v[0:1] op_sel_hi:[1,0]
	v_pk_mul_f32 v[4:5], v[4:5], v[0:1] op_sel_hi:[1,0]
	v_pk_mul_f32 v[2:3], v[2:3], v[0:1] op_sel_hi:[1,0]
	s_waitcnt vmcnt(2)
	v_pk_mul_f32 v[6:7], v[16:17], v[6:7]
	v_pk_mul_f32 v[8:9], v[14:15], v[8:9]
	s_waitcnt vmcnt(1)
	v_pk_add_f32 v[14:15], v[28:29], 1.0 op_sel_hi:[1,0]
	v_pk_add_f32 v[16:17], v[26:27], 1.0 op_sel_hi:[1,0]
	s_waitcnt vmcnt(0)
	v_pk_fma_f32 v[8:9], v[8:9], v[14:15], v[56:57]
	v_pk_fma_f32 v[6:7], v[6:7], v[16:17], v[54:55]
	v_cvt_pk_bf16_f32 v6, v6, v7
	v_cvt_pk_bf16_f32 v7, v8, v9
	global_store_dwordx2 v[46:47], v[6:7], off
	global_load_dwordx4 v[6:9], v[34:35], off offset:1024
	v_lshl_add_u64 v[14:15], v[58:59], 0, v[40:41]
	global_load_dwordx4 v[14:17], v[14:15], off
	s_nop 0
	global_load_dwordx4 v[22:25], v[60:61], off offset:1024
	s_waitcnt vmcnt(2)
	v_pk_mul_f32 v[6:7], v[18:19], v[6:7]
	v_pk_mul_f32 v[8:9], v[20:21], v[8:9]
	s_waitcnt vmcnt(1)
	v_pk_add_f32 v[16:17], v[16:17], 1.0 op_sel_hi:[1,0]
	v_pk_add_f32 v[14:15], v[14:15], 1.0 op_sel_hi:[1,0]
	s_waitcnt vmcnt(0)
	v_pk_fma_f32 v[8:9], v[8:9], v[16:17], v[24:25]
	v_pk_fma_f32 v[6:7], v[6:7], v[14:15], v[22:23]
	v_cvt_pk_bf16_f32 v6, v6, v7
	v_cvt_pk_bf16_f32 v7, v8, v9
	global_store_dwordx2 v[46:47], v[6:7], off offset:512
	global_load_dwordx4 v[6:9], v[34:35], off offset:2048
	v_lshl_add_u64 v[14:15], v[58:59], 0, v[42:43]
	global_load_dwordx4 v[14:17], v[14:15], off
	s_nop 0
	global_load_dwordx4 v[18:21], v[60:61], off offset:2048
	s_waitcnt vmcnt(2)
	v_pk_mul_f32 v[6:7], v[10:11], v[6:7]
	v_pk_mul_f32 v[8:9], v[12:13], v[8:9]
	s_waitcnt vmcnt(1)
	v_pk_add_f32 v[10:11], v[16:17], 1.0 op_sel_hi:[1,0]
	v_pk_add_f32 v[12:13], v[14:15], 1.0 op_sel_hi:[1,0]
	s_waitcnt vmcnt(0)
	v_pk_fma_f32 v[8:9], v[8:9], v[10:11], v[20:21]
	v_pk_fma_f32 v[6:7], v[6:7], v[12:13], v[18:19]
	v_cvt_pk_bf16_f32 v6, v6, v7
	v_cvt_pk_bf16_f32 v7, v8, v9
	global_store_dwordx2 v[46:47], v[6:7], off offset:1024
	global_load_dwordx4 v[6:9], v[34:35], off offset:3072
	v_lshl_add_u64 v[10:11], v[58:59], 0, v[44:45]
	global_load_dwordx4 v[10:13], v[10:11], off
	s_nop 0
	global_load_dwordx4 v[14:17], v[60:61], off offset:3072
	s_waitcnt vmcnt(2)
	v_pk_mul_f32 v[2:3], v[2:3], v[6:7]
	v_pk_mul_f32 v[4:5], v[4:5], v[8:9]
	s_waitcnt vmcnt(1)
	v_pk_add_f32 v[6:7], v[12:13], 1.0 op_sel_hi:[1,0]
	v_pk_add_f32 v[8:9], v[10:11], 1.0 op_sel_hi:[1,0]
	s_waitcnt vmcnt(0)
	v_pk_fma_f32 v[4:5], v[4:5], v[6:7], v[16:17]
	v_pk_fma_f32 v[2:3], v[2:3], v[8:9], v[14:15]
	v_bfe_u32 v0, v2, 16, 1
	v_bfe_u32 v6, v3, 16, 1
	v_add3_u32 v0, v2, v0, s31
	v_add3_u32 v2, v3, v6, s31
	v_lshrrev_b32_e32 v0, 16, v0
	v_and_or_b32 v2, v2, s0, v0
	v_cvt_pk_bf16_f32 v3, v4, v5
	global_store_dwordx2 v[46:47], v[2:3], off offset:1536
	s_branch .LBB0_758

; #define LAS __attribute__((address_space(3)))
; DI unsigned pk2(float lo, float hi) { return f2bf(lo) | (f2bf(hi) << 16); }
; #define BIDX() sgpr_opaque((int)__builtin_amdgcn_workgroup_id_x())
; #define GDIM() sgpr_opaque((int)__ockl_get_num_groups(0))
; DI void transpose_tiles(const float* src, int ldw, int Ks, bf16_t* dst, int Nn, int Kd, int kind, LAS float* tile) {
;     ...
;     for (int it = BIDX(); it < ntn * ntk; it += GDIM()) {
;         const int n0 = (it % ntn) * 64, k0 = (it / ntn) * 64;
;         { const int nn = tid & 63, kk = tid >> 6; const int off = colmap(kind, n0 + nn);
; #pragma unroll
;           for (int i = 0; i < 8; ++i) { const int k = k0 + kk + 8 * i; float v = 0.f; if (off >= 0 && k < Ks) v = src[(size_t)k * ldw + off]; tile[(kk + 8 * i) * 65 + nn] = v; } }
;         __syncthreads();
;         { const int nn = tid >> 3, kc = tid & 7; const LAS float* s = tile + (kc * 8) * 65 + nn;
;           u32x4 o; o.x = pk2(s[0], s[65]); o.y = pk2(s[2 * 65], s[3 * 65]); o.z = pk2(s[4 * 65], s[5 * 65]); o.w = pk2(s[6 * 65], s[7 * 65]);
;           *(u32x4*)(dst + (size_t)(n0 + nn) * Kd + k0 + kc * 8) = o; }
;         __syncthreads();
.LBB0_827:
	s_or_b64 exec, exec, s[2:3]
	s_waitcnt vmcnt(0)
	ds_write_b32 v10, v100
	ds_write_b32 v10, v101 offset:2080
	ds_write_b32 v10, v102 offset:4160
	ds_write_b32 v10, v103 offset:6240
	ds_write_b32 v10, v104 offset:8320
	ds_write_b32 v10, v105 offset:10400
	ds_write_b32 v10, v106 offset:12480
	ds_write_b32 v10, v107 offset:14560
	s_waitcnt lgkmcnt(0)
	s_barrier
	ds_read2_b32 v[4:5], v9 offset1:65
	ds_read2_b32 v[14:15], v9 offset0:130 offset1:195
	s_mov_b32 s2, s30
	s_waitcnt lgkmcnt(1)
	v_cvt_pk_bf16_f32 v12, v4, v5
	v_add_u32_e32 v3, 0x400, v9
	ds_read2_b32 v[4:5], v3 offset0:4 offset1:69
	s_waitcnt lgkmcnt(1)
	ds_read2_b32 v[16:17], v3 offset0:134 offset1:199
	v_cvt_pk_bf16_f32 v13, v14, v15
	s_waitcnt lgkmcnt(1)
	v_bfe_u32 v0, v4, 16, 1
	v_add3_u32 v0, v4, v0, s31
	v_bfe_u32 v3, v5, 16, 1
	v_lshrrev_b32_e32 v0, 16, v0
	v_add3_u32 v3, v5, v3, s31
	v_add_u32_e32 v4, s15, v8
	v_and_or_b32 v14, v3, s0, v0
	s_waitcnt lgkmcnt(0)
	v_ashrrev_i32_e32 v5, 31, v4
	v_lshlrev_b64 v[4:5], 11, v[4:5]
	v_lshl_add_u64 v[4:5], s[12:13], 0, v[4:5]
	s_ashr_i32 s15, s14, 31
	v_cvt_pk_bf16_f32 v15, v16, v17
	v_lshl_add_u64 v[4:5], s[14:15], 1, v[4:5]
	v_mov_b32_e32 v3, v1
	v_lshl_add_u64 v[4:5], v[4:5], 0, v[2:3]
	global_store_dwordx4 v[4:5], v[12:15], off
	s_barrier
	s_add_i32 s16, s2, s16
	s_cmpk_lt_i32 s16, 0x300
	s_cbranch_scc0 .LBB0_870

; #define LAS __attribute__((address_space(3)))
; DI unsigned pk2(float lo, float hi) { return f2bf(lo) | (f2bf(hi) << 16); }
; #define BIDX() sgpr_opaque((int)__builtin_amdgcn_workgroup_id_x())
; #define GDIM() sgpr_opaque((int)__ockl_get_num_groups(0))
; DI void transpose_tiles(const float* src, int ldw, int Ks, bf16_t* dst, int Nn, int Kd, int kind, LAS float* tile) {
;     ...
;     for (int it = BIDX(); it < ntn * ntk; it += GDIM()) {
;         const int n0 = (it % ntn) * 64, k0 = (it / ntn) * 64;
;         { const int nn = tid & 63, kk = tid >> 6; const int off = colmap(kind, n0 + nn);
; #pragma unroll
;           for (int i = 0; i < 8; ++i) { const int k = k0 + kk + 8 * i; float v = 0.f; if (off >= 0 && k < Ks) v = src[(size_t)k * ldw + off]; tile[(kk + 8 * i) * 65 + nn] = v; } }
;         __syncthreads();
;         { const int nn = tid >> 3, kc = tid & 7; const LAS float* s = tile + (kc * 8) * 65 + nn;
;           u32x4 o; o.x = pk2(s[0], s[65]); o.y = pk2(s[2 * 65], s[3 * 65]); o.z = pk2(s[4 * 65], s[5 * 65]); o.w = pk2(s[6 * 65], s[7 * 65]);
;           *(u32x4*)(dst + (size_t)(n0 + nn) * Kd + k0 + kc * 8) = o; }
;         __syncthreads();
.LBB0_872:
	s_or_b64 exec, exec, s[2:3]
	s_waitcnt vmcnt(0)
	ds_write_b32 v12, v100
	ds_write_b32 v12, v101 offset:2080
	ds_write_b32 v12, v102 offset:4160
	ds_write_b32 v12, v103 offset:6240
	ds_write_b32 v12, v104 offset:8320
	ds_write_b32 v12, v105 offset:10400
	ds_write_b32 v12, v106 offset:12480
	ds_write_b32 v12, v107 offset:14560
	s_waitcnt lgkmcnt(0)
	s_barrier
	ds_read2_b32 v[4:5], v11 offset1:65
	ds_read2_b32 v[6:7], v11 offset0:130 offset1:195
	s_mov_b32 s2, s30
	s_waitcnt lgkmcnt(1)
	v_cvt_pk_bf16_f32 v4, v4, v5
	v_add_u32_e32 v3, 0x400, v11
	ds_read2_b32 v[14:15], v3 offset0:4 offset1:69
	s_waitcnt lgkmcnt(1)
	ds_read2_b32 v[16:17], v3 offset0:134 offset1:199
	v_cvt_pk_bf16_f32 v5, v6, v7
	s_waitcnt lgkmcnt(1)
	v_bfe_u32 v0, v14, 16, 1
	v_add3_u32 v0, v14, v0, s31
	v_bfe_u32 v3, v15, 16, 1
	v_lshrrev_b32_e32 v0, 16, v0
	v_add3_u32 v3, v15, v3, s31
	v_add_u32_e32 v14, s15, v10
	v_and_or_b32 v6, v3, s0, v0
	s_waitcnt lgkmcnt(0)
	v_ashrrev_i32_e32 v15, 31, v14
	v_lshlrev_b64 v[14:15], 11, v[14:15]
	v_lshl_add_u64 v[14:15], s[12:13], 0, v[14:15]
	s_ashr_i32 s15, s14, 31
	v_cvt_pk_bf16_f32 v7, v16, v17
	v_lshl_add_u64 v[14:15], s[14:15], 1, v[14:15]
	v_mov_b32_e32 v3, v1
	v_lshl_add_u64 v[14:15], v[14:15], 0, v[2:3]
	global_store_dwordx4 v[14:15], v[4:7], off
	s_barrier
	s_add_i32 s18, s2, s18
	s_cmpk_lt_i32 s18, 0x100
	s_cbranch_scc0 .LBB0_889

; #define LAS __attribute__((address_space(3)))
; DI unsigned pk2(float lo, float hi) { return f2bf(lo) | (f2bf(hi) << 16); }
; #define BIDX() sgpr_opaque((int)__builtin_amdgcn_workgroup_id_x())
; #define GDIM() sgpr_opaque((int)__ockl_get_num_groups(0))
; DI void transpose_tiles(const float* src, int ldw, int Ks, bf16_t* dst, int Nn, int Kd, int kind, LAS float* tile) {
;     ...
;     for (int it = BIDX(); it < ntn * ntk; it += GDIM()) {
;         const int n0 = (it % ntn) * 64, k0 = (it / ntn) * 64;
;         { const int nn = tid & 63, kk = tid >> 6; const int off = colmap(kind, n0 + nn);
; #pragma unroll
;           for (int i = 0; i < 8; ++i) { const int k = k0 + kk + 8 * i; float v = 0.f; if (off >= 0 && k < Ks) v = src[(size_t)k * ldw + off]; tile[(kk + 8 * i) * 65 + nn] = v; } }
;         __syncthreads();
;         { const int nn = tid >> 3, kc = tid & 7; const LAS float* s = tile + (kc * 8) * 65 + nn;
;           u32x4 o; o.x = pk2(s[0], s[65]); o.y = pk2(s[2 * 65], s[3 * 65]); o.z = pk2(s[4 * 65], s[5 * 65]); o.w = pk2(s[6 * 65], s[7 * 65]);
;           *(u32x4*)(dst + (size_t)(n0 + nn) * Kd + k0 + kc * 8) = o; }
;         __syncthreads();
.LBB0_891:
	s_or_b64 exec, exec, s[2:3]
	s_waitcnt vmcnt(0)
	ds_write_b32 v12, v100
	ds_write_b32 v12, v101 offset:2080
	ds_write_b32 v12, v102 offset:4160
	ds_write_b32 v12, v103 offset:6240
	ds_write_b32 v12, v104 offset:8320
	ds_write_b32 v12, v105 offset:10400
	ds_write_b32 v12, v106 offset:12480
	ds_write_b32 v12, v107 offset:14560
	s_waitcnt lgkmcnt(0)
	s_barrier
	ds_read2_b32 v[4:5], v11 offset1:65
	ds_read2_b32 v[6:7], v11 offset0:130 offset1:195
	s_mov_b32 s2, s30
	s_waitcnt lgkmcnt(1)
	v_cvt_pk_bf16_f32 v4, v4, v5
	v_add_u32_e32 v3, 0x400, v11
	ds_read2_b32 v[14:15], v3 offset0:4 offset1:69
	s_waitcnt lgkmcnt(1)
	ds_read2_b32 v[16:17], v3 offset0:134 offset1:199
	v_cvt_pk_bf16_f32 v5, v6, v7
	s_waitcnt lgkmcnt(1)
	v_bfe_u32 v0, v14, 16, 1
	v_add3_u32 v0, v14, v0, s31
	v_bfe_u32 v3, v15, 16, 1
	v_lshrrev_b32_e32 v0, 16, v0
	v_add3_u32 v3, v15, v3, s31
	v_add_u32_e32 v14, s17, v10
	v_and_or_b32 v6, v3, s0, v0
	s_waitcnt lgkmcnt(0)
	v_ashrrev_i32_e32 v15, 31, v14
	v_lshlrev_b64 v[14:15], 11, v[14:15]
	v_lshl_add_u64 v[14:15], s[12:13], 0, v[14:15]
	s_ashr_i32 s17, s16, 31
	v_cvt_pk_bf16_f32 v7, v16, v17
	v_lshl_add_u64 v[14:15], s[16:17], 1, v[14:15]
	v_mov_b32_e32 v3, v1
	v_lshl_add_u64 v[14:15], v[14:15], 0, v[2:3]
	global_store_dwordx4 v[14:15], v[4:7], off
	s_barrier
	s_add_i32 s20, s2, s20
	s_cmpk_lt_i32 s20, 0x100
	s_cbranch_scc0 .LBB0_908

; #define LAS __attribute__((address_space(3)))
; DI unsigned pk2(float lo, float hi) { return f2bf(lo) | (f2bf(hi) << 16); }
; #define BIDX() sgpr_opaque((int)__builtin_amdgcn_workgroup_id_x())
; #define GDIM() sgpr_opaque((int)__ockl_get_num_groups(0))
; DI void transpose_tiles(const float* src, int ldw, int Ks, bf16_t* dst, int Nn, int Kd, int kind, LAS float* tile) {
;     ...
;     for (int it = BIDX(); it < ntn * ntk; it += GDIM()) {
;         const int n0 = (it % ntn) * 64, k0 = (it / ntn) * 64;
;         { const int nn = tid & 63, kk = tid >> 6; const int off = colmap(kind, n0 + nn);
; #pragma unroll
;           for (int i = 0; i < 8; ++i) { const int k = k0 + kk + 8 * i; float v = 0.f; if (off >= 0 && k < Ks) v = src[(size_t)k * ldw + off]; tile[(kk + 8 * i) * 65 + nn] = v; } }
;         __syncthreads();
;         { const int nn = tid >> 3, kc = tid & 7; const LAS float* s = tile + (kc * 8) * 65 + nn;
;           u32x4 o; o.x = pk2(s[0], s[65]); o.y = pk2(s[2 * 65], s[3 * 65]); o.z = pk2(s[4 * 65], s[5 * 65]); o.w = pk2(s[6 * 65], s[7 * 65]);
;           *(u32x4*)(dst + (size_t)(n0 + nn) * Kd + k0 + kc * 8) = o; }
;         __syncthreads();
.LBB0_910:
	s_or_b64 exec, exec, s[2:3]
	s_waitcnt vmcnt(0)
	ds_write_b32 v12, v100
	ds_write_b32 v12, v101 offset:2080
	ds_write_b32 v12, v102 offset:4160
	ds_write_b32 v12, v103 offset:6240
	ds_write_b32 v12, v104 offset:8320
	ds_write_b32 v12, v105 offset:10400
	ds_write_b32 v12, v106 offset:12480
	ds_write_b32 v12, v107 offset:14560
	s_waitcnt lgkmcnt(0)
	s_barrier
	ds_read2_b32 v[4:5], v11 offset1:65
	ds_read2_b32 v[6:7], v11 offset0:130 offset1:195
	s_mov_b32 s2, s30
	s_waitcnt lgkmcnt(1)
	v_cvt_pk_bf16_f32 v4, v4, v5
	v_add_u32_e32 v3, 0x400, v11
	ds_read2_b32 v[14:15], v3 offset0:4 offset1:69
	s_waitcnt lgkmcnt(1)
	ds_read2_b32 v[16:17], v3 offset0:134 offset1:199
	v_cvt_pk_bf16_f32 v5, v6, v7
	s_waitcnt lgkmcnt(1)
	v_bfe_u32 v0, v14, 16, 1
	v_add3_u32 v0, v14, v0, s31
	v_bfe_u32 v3, v15, 16, 1
	v_lshrrev_b32_e32 v0, 16, v0
	v_add3_u32 v3, v15, v3, s31
	v_add_u32_e32 v14, s19, v10
	v_and_or_b32 v6, v3, s0, v0
	s_waitcnt lgkmcnt(0)
	v_ashrrev_i32_e32 v15, 31, v14
	v_lshlrev_b64 v[14:15], 11, v[14:15]
	v_lshl_add_u64 v[14:15], s[16:17], 0, v[14:15]
	s_ashr_i32 s19, s18, 31
	v_cvt_pk_bf16_f32 v7, v16, v17
	v_lshl_add_u64 v[14:15], s[18:19], 1, v[14:15]
	v_mov_b32_e32 v3, v1
	v_lshl_add_u64 v[14:15], v[14:15], 0, v[2:3]
	global_store_dwordx4 v[14:15], v[4:7], off
	s_barrier
	s_add_i32 s42, s2, s42
	s_cmpk_lt_i32 s42, 0x100
	s_cbranch_scc0 .LBB0_927

; #define LAS __attribute__((address_space(3)))
; DI unsigned pk2(float lo, float hi) { return f2bf(lo) | (f2bf(hi) << 16); }
; #define BIDX() sgpr_opaque((int)__builtin_amdgcn_workgroup_id_x())
; #define GDIM() sgpr_opaque((int)__ockl_get_num_groups(0))
; DI void transpose_tiles(const float* src, int ldw, int Ks, bf16_t* dst, int Nn, int Kd, int kind, LAS float* tile) {
;     ...
;     for (int it = BIDX(); it < ntn * ntk; it += GDIM()) {
;         const int n0 = (it % ntn) * 64, k0 = (it / ntn) * 64;
;         { const int nn = tid & 63, kk = tid >> 6; const int off = colmap(kind, n0 + nn);
; #pragma unroll
;           for (int i = 0; i < 8; ++i) { const int k = k0 + kk + 8 * i; float v = 0.f; if (off >= 0 && k < Ks) v = src[(size_t)k * ldw + off]; tile[(kk + 8 * i) * 65 + nn] = v; } }
;         __syncthreads();
;         { const int nn = tid >> 3, kc = tid & 7; const LAS float* s = tile + (kc * 8) * 65 + nn;
;           u32x4 o; o.x = pk2(s[0], s[65]); o.y = pk2(s[2 * 65], s[3 * 65]); o.z = pk2(s[4 * 65], s[5 * 65]); o.w = pk2(s[6 * 65], s[7 * 65]);
;           *(u32x4*)(dst + (size_t)(n0 + nn) * Kd + k0 + kc * 8) = o; }
;         __syncthreads();
.LBB0_929:
	s_or_b64 exec, exec, s[2:3]
	s_waitcnt vmcnt(0)
	ds_write_b32 v12, v100
	ds_write_b32 v12, v101 offset:2080
	ds_write_b32 v12, v102 offset:4160
	ds_write_b32 v12, v103 offset:6240
	ds_write_b32 v12, v104 offset:8320
	ds_write_b32 v12, v105 offset:10400
	ds_write_b32 v12, v106 offset:12480
	ds_write_b32 v12, v107 offset:14560
	s_waitcnt lgkmcnt(0)
	s_barrier
	ds_read2_b32 v[4:5], v11 offset1:65
	ds_read2_b32 v[6:7], v11 offset0:130 offset1:195
	s_mov_b32 s2, s30
	s_waitcnt lgkmcnt(1)
	v_cvt_pk_bf16_f32 v4, v4, v5
	v_add_u32_e32 v3, 0x400, v11
	ds_read2_b32 v[14:15], v3 offset0:4 offset1:69
	s_waitcnt lgkmcnt(1)
	ds_read2_b32 v[16:17], v3 offset0:134 offset1:199
	v_cvt_pk_bf16_f32 v5, v6, v7
	s_waitcnt lgkmcnt(1)
	v_bfe_u32 v0, v14, 16, 1
	v_add3_u32 v0, v14, v0, s31
	v_bfe_u32 v3, v15, 16, 1
	v_lshrrev_b32_e32 v0, 16, v0
	v_add3_u32 v3, v15, v3, s31
	v_add_u32_e32 v14, s17, v10
	v_and_or_b32 v6, v3, s0, v0
	s_waitcnt lgkmcnt(0)
	v_ashrrev_i32_e32 v15, 31, v14
	v_lshlrev_b64 v[14:15], 11, v[14:15]
	v_lshl_add_u64 v[14:15], s[14:15], 0, v[14:15]
	s_ashr_i32 s17, s16, 31
	v_cvt_pk_bf16_f32 v7, v16, v17
	v_lshl_add_u64 v[14:15], s[16:17], 1, v[14:15]
	v_mov_b32_e32 v3, v1
	v_lshl_add_u64 v[14:15], v[14:15], 0, v[2:3]
	global_store_dwordx4 v[14:15], v[4:7], off
	s_barrier
	s_add_i32 s20, s2, s20
	s_cmpk_lt_i32 s20, 0x100
	s_cbranch_scc0 .LBB0_946

; #define LAS __attribute__((address_space(3)))
; DI unsigned pk2(float lo, float hi) { return f2bf(lo) | (f2bf(hi) << 16); }
; #define BIDX() sgpr_opaque((int)__builtin_amdgcn_workgroup_id_x())
; #define GDIM() sgpr_opaque((int)__ockl_get_num_groups(0))
; DI void transpose_tiles(const float* src, int ldw, int Ks, bf16_t* dst, int Nn, int Kd, int kind, LAS float* tile) {
;     ...
;     for (int it = BIDX(); it < ntn * ntk; it += GDIM()) {
;         const int n0 = (it % ntn) * 64, k0 = (it / ntn) * 64;
;         { const int nn = tid & 63, kk = tid >> 6; const int off = colmap(kind, n0 + nn);
; #pragma unroll
;           for (int i = 0; i < 8; ++i) { const int k = k0 + kk + 8 * i; float v = 0.f; if (off >= 0 && k < Ks) v = src[(size_t)k * ldw + off]; tile[(kk + 8 * i) * 65 + nn] = v; } }
;         __syncthreads();
;         { const int nn = tid >> 3, kc = tid & 7; const LAS float* s = tile + (kc * 8) * 65 + nn;
;           u32x4 o; o.x = pk2(s[0], s[65]); o.y = pk2(s[2 * 65], s[3 * 65]); o.z = pk2(s[4 * 65], s[5 * 65]); o.w = pk2(s[6 * 65], s[7 * 65]);
;           *(u32x4*)(dst + (size_t)(n0 + nn) * Kd + k0 + kc * 8) = o; }
;         __syncthreads();
.LBB0_948:
	s_or_b64 exec, exec, s[2:3]
	s_waitcnt vmcnt(0)
	ds_write_b32 v12, v100
	ds_write_b32 v12, v101 offset:2080
	ds_write_b32 v12, v102 offset:4160
	ds_write_b32 v12, v103 offset:6240
	ds_write_b32 v12, v104 offset:8320
	ds_write_b32 v12, v105 offset:10400
	ds_write_b32 v12, v106 offset:12480
	ds_write_b32 v12, v107 offset:14560
	s_waitcnt lgkmcnt(0)
	s_barrier
	ds_read2_b32 v[4:5], v11 offset1:65
	ds_read2_b32 v[6:7], v11 offset0:130 offset1:195
	s_mov_b32 s2, s30
	s_waitcnt lgkmcnt(1)
	v_cvt_pk_bf16_f32 v4, v4, v5
	v_add_u32_e32 v3, 0x400, v11
	ds_read2_b32 v[14:15], v3 offset0:4 offset1:69
	s_waitcnt lgkmcnt(1)
	ds_read2_b32 v[16:17], v3 offset0:134 offset1:199
	v_cvt_pk_bf16_f32 v5, v6, v7
	s_waitcnt lgkmcnt(1)
	v_bfe_u32 v0, v14, 16, 1
	v_add3_u32 v0, v14, v0, s31
	v_bfe_u32 v3, v15, 16, 1
	v_lshrrev_b32_e32 v0, 16, v0
	v_add3_u32 v3, v15, v3, s31
	v_add_u32_e32 v14, s21, v10
	v_and_or_b32 v6, v3, s0, v0
	s_waitcnt lgkmcnt(0)
	v_ashrrev_i32_e32 v15, 31, v14
	v_lshlrev_b64 v[14:15], 11, v[14:15]
	v_lshl_add_u64 v[14:15], s[18:19], 0, v[14:15]
	s_ashr_i32 s21, s20, 31
	v_cvt_pk_bf16_f32 v7, v16, v17
	v_lshl_add_u64 v[14:15], s[20:21], 1, v[14:15]
	v_mov_b32_e32 v3, v1
	v_lshl_add_u64 v[14:15], v[14:15], 0, v[2:3]
	global_store_dwordx4 v[14:15], v[4:7], off
	s_barrier
	s_add_i32 s42, s2, s42
	s_cmp_lt_i32 s42, 64
	s_cbranch_scc0 .LBB0_965

; #define LAS __attribute__((address_space(3)))
; DI unsigned pk2(float lo, float hi) { return f2bf(lo) | (f2bf(hi) << 16); }
; #define BIDX() sgpr_opaque((int)__builtin_amdgcn_workgroup_id_x())
; #define GDIM() sgpr_opaque((int)__ockl_get_num_groups(0))
; DI int tid_opaque() { int t = threadIdx.x; asm volatile("" : "+v"(t)); return t; }
; DI void transpose_tiles(const float* src, int ldw, int Ks, bf16_t* dst, int Nn, int Kd, int kind, LAS float* tile) {
;     const int tid = tid_opaque(), ntn = Nn / 64, ntk = Kd / 64;
;     for (int it = BIDX(); it < ntn * ntk; it += GDIM()) {
;         const int n0 = (it % ntn) * 64, k0 = (it / ntn) * 64;
;         { const int nn = tid & 63, kk = tid >> 6; const int off = colmap(kind, n0 + nn);
; #pragma unroll
;           for (int i = 0; i < 8; ++i) { const int k = k0 + kk + 8 * i; float v = 0.f; if (off >= 0 && k < Ks) v = src[(size_t)k * ldw + off]; tile[(kk + 8 * i) * 65 + nn] = v; } }
;         __syncthreads();
;         { const int nn = tid >> 3, kc = tid & 7; const LAS float* s = tile + (kc * 8) * 65 + nn;
;           u32x4 o; o.x = pk2(s[0], s[65]); o.y = pk2(s[2 * 65], s[3 * 65]); o.z = pk2(s[4 * 65], s[5 * 65]); o.w = pk2(s[6 * 65], s[7 * 65]);
;           *(u32x4*)(dst + (size_t)(n0 + nn) * Kd + k0 + kc * 8) = o; }
;         __syncthreads();
.LBB0_967:
	s_or_b64 exec, exec, s[2:3]
	s_waitcnt vmcnt(0)
	ds_write_b32 v12, v100
	ds_write_b32 v12, v101 offset:2080
	ds_write_b32 v12, v102 offset:4160
	ds_write_b32 v12, v103 offset:6240
	ds_write_b32 v12, v104 offset:8320
	ds_write_b32 v12, v105 offset:10400
	ds_write_b32 v12, v106 offset:12480
	ds_write_b32 v12, v107 offset:14560
	s_waitcnt lgkmcnt(0)
	s_barrier
	ds_read2_b32 v[4:5], v11 offset1:65
	ds_read2_b32 v[6:7], v11 offset0:130 offset1:195
	s_mov_b32 s2, s30
	s_waitcnt lgkmcnt(1)
	v_cvt_pk_bf16_f32 v4, v4, v5
	v_add_u32_e32 v3, 0x400, v11
	ds_read2_b32 v[14:15], v3 offset0:4 offset1:69
	s_waitcnt lgkmcnt(1)
	ds_read2_b32 v[16:17], v3 offset0:134 offset1:199
	v_cvt_pk_bf16_f32 v5, v6, v7
	s_waitcnt lgkmcnt(1)
	v_bfe_u32 v0, v14, 16, 1
	v_add3_u32 v0, v14, v0, s31
	v_bfe_u32 v3, v15, 16, 1
	v_lshrrev_b32_e32 v0, 16, v0
	v_add3_u32 v3, v15, v3, s31
	v_add_u32_e32 v14, s19, v10
	v_and_or_b32 v6, v3, s0, v0
	s_waitcnt lgkmcnt(0)
	v_ashrrev_i32_e32 v15, 31, v14
	v_lshlrev_b64 v[14:15], 11, v[14:15]
	v_lshl_add_u64 v[14:15], s[16:17], 0, v[14:15]
	s_ashr_i32 s19, s18, 31
	v_cvt_pk_bf16_f32 v7, v16, v17
	v_lshl_add_u64 v[14:15], s[18:19], 1, v[14:15]
	v_mov_b32_e32 v3, v1
	v_lshl_add_u64 v[14:15], v[14:15], 0, v[2:3]
	global_store_dwordx4 v[14:15], v[4:7], off
	s_barrier
	s_add_i32 s20, s2, s20
	s_cmp_lt_i32 s20, 64
	s_cbranch_scc0 .LBB0_984

; #define LAS __attribute__((address_space(3)))
; DI unsigned pk2(float lo, float hi) { return f2bf(lo) | (f2bf(hi) << 16); }
; #define BIDX() sgpr_opaque((int)__builtin_amdgcn_workgroup_id_x())
; #define GDIM() sgpr_opaque((int)__ockl_get_num_groups(0))
; DI int tid_opaque() { int t = threadIdx.x; asm volatile("" : "+v"(t)); return t; }
; DI void transpose_tiles(const float* src, int ldw, int Ks, bf16_t* dst, int Nn, int Kd, int kind, LAS float* tile) {
;     const int tid = tid_opaque(), ntn = Nn / 64, ntk = Kd / 64;
;     for (int it = BIDX(); it < ntn * ntk; it += GDIM()) {
;         const int n0 = (it % ntn) * 64, k0 = (it / ntn) * 64;
;         { const int nn = tid & 63, kk = tid >> 6; const int off = colmap(kind, n0 + nn);
; #pragma unroll
;           for (int i = 0; i < 8; ++i) { const int k = k0 + kk + 8 * i; float v = 0.f; if (off >= 0 && k < Ks) v = src[(size_t)k * ldw + off]; tile[(kk + 8 * i) * 65 + nn] = v; } }
;         __syncthreads();
;         { const int nn = tid >> 3, kc = tid & 7; const LAS float* s = tile + (kc * 8) * 65 + nn;
;           u32x4 o; o.x = pk2(s[0], s[65]); o.y = pk2(s[2 * 65], s[3 * 65]); o.z = pk2(s[4 * 65], s[5 * 65]); o.w = pk2(s[6 * 65], s[7 * 65]);
;           *(u32x4*)(dst + (size_t)(n0 + nn) * Kd + k0 + kc * 8) = o; }
;         __syncthreads();
.LBB0_986:
	s_or_b64 exec, exec, s[2:3]
	s_waitcnt vmcnt(0)
	ds_write_b32 v10, v100
	ds_write_b32 v10, v101 offset:2080
	ds_write_b32 v10, v102 offset:4160
	ds_write_b32 v10, v103 offset:6240
	ds_write_b32 v10, v104 offset:8320
	ds_write_b32 v10, v105 offset:10400
	ds_write_b32 v10, v106 offset:12480
	ds_write_b32 v10, v107 offset:14560
	s_waitcnt lgkmcnt(0)
	s_barrier
	ds_read2_b32 v[4:5], v9 offset1:65
	ds_read2_b32 v[14:15], v9 offset0:130 offset1:195
	s_mov_b32 s2, s30
	s_waitcnt lgkmcnt(1)
	v_cvt_pk_bf16_f32 v12, v4, v5
	v_add_u32_e32 v3, 0x400, v9
	ds_read2_b32 v[4:5], v3 offset0:4 offset1:69
	s_waitcnt lgkmcnt(1)
	ds_read2_b32 v[16:17], v3 offset0:134 offset1:199
	v_cvt_pk_bf16_f32 v13, v14, v15
	s_waitcnt lgkmcnt(1)
	v_bfe_u32 v0, v4, 16, 1
	v_add3_u32 v0, v4, v0, s31
	v_bfe_u32 v3, v5, 16, 1
	v_lshrrev_b32_e32 v0, 16, v0
	v_add3_u32 v3, v5, v3, s31
	v_add_u32_e32 v4, s17, v8
	v_and_or_b32 v14, v3, s0, v0
	s_waitcnt lgkmcnt(0)
	v_ashrrev_i32_e32 v5, 31, v4
	v_lshlrev_b64 v[4:5], 11, v[4:5]
	v_lshl_add_u64 v[4:5], s[12:13], 0, v[4:5]
	s_ashr_i32 s17, s16, 31
	v_cvt_pk_bf16_f32 v15, v16, v17
	v_lshl_add_u64 v[4:5], s[16:17], 1, v[4:5]
	v_mov_b32_e32 v3, v1
	v_lshl_add_u64 v[4:5], v[4:5], 0, v[2:3]
	global_store_dwordx4 v[4:5], v[12:15], off
	s_barrier
	s_add_i32 s18, s2, s18
	s_cmp_lt_i32 s18, 64
	s_cbranch_scc0 .LBB0_1003

; #define LAS __attribute__((address_space(3)))
; DI unsigned pk2(float lo, float hi) { return f2bf(lo) | (f2bf(hi) << 16); }
; #define BIDX() sgpr_opaque((int)__builtin_amdgcn_workgroup_id_x())
; #define GDIM() sgpr_opaque((int)__ockl_get_num_groups(0))
; DI int tid_opaque() { int t = threadIdx.x; asm volatile("" : "+v"(t)); return t; }
; DI void transpose_tiles(const float* src, int ldw, int Ks, bf16_t* dst, int Nn, int Kd, int kind, LAS float* tile) {
;     const int tid = tid_opaque(), ntn = Nn / 64, ntk = Kd / 64;
;     for (int it = BIDX(); it < ntn * ntk; it += GDIM()) {
;         const int n0 = (it % ntn) * 64, k0 = (it / ntn) * 64;
;         { const int nn = tid & 63, kk = tid >> 6; const int off = colmap(kind, n0 + nn);
; #pragma unroll
;           for (int i = 0; i < 8; ++i) { const int k = k0 + kk + 8 * i; float v = 0.f; if (off >= 0 && k < Ks) v = src[(size_t)k * ldw + off]; tile[(kk + 8 * i) * 65 + nn] = v; } }
;         __syncthreads();
;         { const int nn = tid >> 3, kc = tid & 7; const LAS float* s = tile + (kc * 8) * 65 + nn;
;           u32x4 o; o.x = pk2(s[0], s[65]); o.y = pk2(s[2 * 65], s[3 * 65]); o.z = pk2(s[4 * 65], s[5 * 65]); o.w = pk2(s[6 * 65], s[7 * 65]);
;           *(u32x4*)(dst + (size_t)(n0 + nn) * Kd + k0 + kc * 8) = o; }
;         __syncthreads();
.LBB0_1005:
	s_or_b64 exec, exec, s[2:3]
	s_waitcnt vmcnt(0)
	ds_write_b32 v12, v100
	ds_write_b32 v12, v101 offset:2080
	ds_write_b32 v12, v102 offset:4160
	ds_write_b32 v12, v103 offset:6240
	ds_write_b32 v12, v104 offset:8320
	ds_write_b32 v12, v105 offset:10400
	ds_write_b32 v12, v106 offset:12480
	ds_write_b32 v12, v107 offset:14560
	s_waitcnt lgkmcnt(0)
	s_barrier
	ds_read2_b32 v[4:5], v11 offset1:65
	ds_read2_b32 v[6:7], v11 offset0:130 offset1:195
	s_mov_b32 s2, s30
	s_waitcnt lgkmcnt(1)
	v_cvt_pk_bf16_f32 v4, v4, v5
	v_add_u32_e32 v3, 0x400, v11
	ds_read2_b32 v[14:15], v3 offset0:4 offset1:69
	s_waitcnt lgkmcnt(1)
	ds_read2_b32 v[16:17], v3 offset0:134 offset1:199
	v_cvt_pk_bf16_f32 v5, v6, v7
	s_waitcnt lgkmcnt(1)
	v_bfe_u32 v0, v14, 16, 1
	v_add3_u32 v0, v14, v0, s31
	v_bfe_u32 v3, v15, 16, 1
	v_lshrrev_b32_e32 v0, 16, v0
	v_add3_u32 v3, v15, v3, s31
	v_add_u32_e32 v14, s17, v10
	v_and_or_b32 v6, v3, s0, v0
	s_waitcnt lgkmcnt(0)
	v_ashrrev_i32_e32 v15, 31, v14
	v_lshlrev_b64 v[14:15], 7, v[14:15]
	v_lshl_add_u64 v[14:15], s[14:15], 0, v[14:15]
	s_ashr_i32 s17, s16, 31
	v_cvt_pk_bf16_f32 v7, v16, v17
	v_lshl_add_u64 v[14:15], s[16:17], 1, v[14:15]
	v_mov_b32_e32 v3, v1
	v_lshl_add_u64 v[14:15], v[14:15], 0, v[2:3]
	global_store_dwordx4 v[14:15], v[4:7], off
	s_barrier
	s_add_i32 s21, s2, s21
	s_cmp_lt_i32 s21, 16
	s_cbranch_scc0 .LBB0_1022

; #define LAS __attribute__((address_space(3)))
; DI unsigned pk2(float lo, float hi) { return f2bf(lo) | (f2bf(hi) << 16); }
; #define BIDX() sgpr_opaque((int)__builtin_amdgcn_workgroup_id_x())
; #define GDIM() sgpr_opaque((int)__ockl_get_num_groups(0))
; DI int tid_opaque() { int t = threadIdx.x; asm volatile("" : "+v"(t)); return t; }
; DI void transpose_tiles(const float* src, int ldw, int Ks, bf16_t* dst, int Nn, int Kd, int kind, LAS float* tile) {
;     const int tid = tid_opaque(), ntn = Nn / 64, ntk = Kd / 64;
;     for (int it = BIDX(); it < ntn * ntk; it += GDIM()) {
;         const int n0 = (it % ntn) * 64, k0 = (it / ntn) * 64;
;         { const int nn = tid & 63, kk = tid >> 6; const int off = colmap(kind, n0 + nn);
; #pragma unroll
;           for (int i = 0; i < 8; ++i) { const int k = k0 + kk + 8 * i; float v = 0.f; if (off >= 0 && k < Ks) v = src[(size_t)k * ldw + off]; tile[(kk + 8 * i) * 65 + nn] = v; } }
;         __syncthreads();
;         { const int nn = tid >> 3, kc = tid & 7; const LAS float* s = tile + (kc * 8) * 65 + nn;
;           u32x4 o; o.x = pk2(s[0], s[65]); o.y = pk2(s[2 * 65], s[3 * 65]); o.z = pk2(s[4 * 65], s[5 * 65]); o.w = pk2(s[6 * 65], s[7 * 65]);
;           *(u32x4*)(dst + (size_t)(n0 + nn) * Kd + k0 + kc * 8) = o; }
;         __syncthreads();
.LBB0_1024:
	s_or_b64 exec, exec, s[2:3]
	s_waitcnt vmcnt(0)
	ds_write_b32 v12, v100
	ds_write_b32 v12, v101 offset:2080
	ds_write_b32 v12, v102 offset:4160
	ds_write_b32 v12, v103 offset:6240
	ds_write_b32 v12, v104 offset:8320
	ds_write_b32 v12, v105 offset:10400
	ds_write_b32 v12, v106 offset:12480
	ds_write_b32 v12, v107 offset:14560
	s_waitcnt lgkmcnt(0)
	s_barrier
	ds_read2_b32 v[4:5], v11 offset1:65
	ds_read2_b32 v[6:7], v11 offset0:130 offset1:195
	s_ashr_i32 s17, s16, 31
	s_mov_b32 s2, s30
	s_waitcnt lgkmcnt(1)
	v_cvt_pk_bf16_f32 v4, v4, v5
	v_add_u32_e32 v3, 0x400, v11
	ds_read2_b32 v[14:15], v3 offset0:4 offset1:69
	s_waitcnt lgkmcnt(1)
	ds_read2_b32 v[16:17], v3 offset0:134 offset1:199
	v_cvt_pk_bf16_f32 v5, v6, v7
	s_waitcnt lgkmcnt(1)
	v_bfe_u32 v0, v14, 16, 1
	v_add3_u32 v0, v14, v0, s31
	v_bfe_u32 v3, v15, 16, 1
	v_lshrrev_b32_e32 v0, 16, v0
	v_add3_u32 v3, v15, v3, s31
	v_add_u32_e32 v14, s5, v10
	v_and_or_b32 v6, v3, s0, v0
	s_waitcnt lgkmcnt(0)
	v_ashrrev_i32_e32 v15, 31, v14
	v_lshlrev_b64 v[14:15], 7, v[14:15]
	v_lshl_add_u64 v[14:15], s[14:15], 0, v[14:15]
	v_cvt_pk_bf16_f32 v7, v16, v17
	v_lshl_add_u64 v[14:15], s[16:17], 1, v[14:15]
	v_mov_b32_e32 v3, v1
	v_lshl_add_u64 v[14:15], v[14:15], 0, v[2:3]
	global_store_dwordx4 v[14:15], v[4:7], off
	s_barrier
	s_add_i32 s21, s2, s21
	s_cmp_lt_i32 s21, 16
	s_cbranch_scc0 .LBB0_1041

; #define LAS __attribute__((address_space(3)))
; DI unsigned pk2(float lo, float hi) { return f2bf(lo) | (f2bf(hi) << 16); }
; #define BIDX() sgpr_opaque((int)__builtin_amdgcn_workgroup_id_x())
; #define GDIM() sgpr_opaque((int)__ockl_get_num_groups(0))
; DI int tid_opaque() { int t = threadIdx.x; asm volatile("" : "+v"(t)); return t; }
; DI void transpose_tiles(const float* src, int ldw, int Ks, bf16_t* dst, int Nn, int Kd, int kind, LAS float* tile) {
;     const int tid = tid_opaque(), ntn = Nn / 64, ntk = Kd / 64;
;     for (int it = BIDX(); it < ntn * ntk; it += GDIM()) {
;         const int n0 = (it % ntn) * 64, k0 = (it / ntn) * 64;
;         { const int nn = tid & 63, kk = tid >> 6; const int off = colmap(kind, n0 + nn);
; #pragma unroll
;           for (int i = 0; i < 8; ++i) { const int k = k0 + kk + 8 * i; float v = 0.f; if (off >= 0 && k < Ks) v = src[(size_t)k * ldw + off]; tile[(kk + 8 * i) * 65 + nn] = v; } }
;         __syncthreads();
;         { const int nn = tid >> 3, kc = tid & 7; const LAS float* s = tile + (kc * 8) * 65 + nn;
;           u32x4 o; o.x = pk2(s[0], s[65]); o.y = pk2(s[2 * 65], s[3 * 65]); o.z = pk2(s[4 * 65], s[5 * 65]); o.w = pk2(s[6 * 65], s[7 * 65]);
;           *(u32x4*)(dst + (size_t)(n0 + nn) * Kd + k0 + kc * 8) = o; }
;         __syncthreads();
.LBB0_1062:
	s_or_b64 exec, exec, s[2:3]
	s_waitcnt vmcnt(0)
	ds_write_b32 v12, v100
	ds_write_b32 v12, v101 offset:2080
	ds_write_b32 v12, v102 offset:4160
	ds_write_b32 v12, v103 offset:6240
	ds_write_b32 v12, v104 offset:8320
	ds_write_b32 v12, v105 offset:10400
	ds_write_b32 v12, v106 offset:12480
	ds_write_b32 v12, v107 offset:14560
	s_waitcnt lgkmcnt(0)
	s_barrier
	ds_read2_b32 v[4:5], v11 offset1:65
	ds_read2_b32 v[6:7], v11 offset0:130 offset1:195
	s_mov_b32 s2, s30
	s_waitcnt lgkmcnt(1)
	v_cvt_pk_bf16_f32 v4, v4, v5
	v_add_u32_e32 v3, 0x400, v11
	ds_read2_b32 v[14:15], v3 offset0:4 offset1:69
	s_waitcnt lgkmcnt(1)
	ds_read2_b32 v[16:17], v3 offset0:134 offset1:199
	v_cvt_pk_bf16_f32 v5, v6, v7
	s_waitcnt lgkmcnt(1)
	v_bfe_u32 v0, v14, 16, 1
	v_add3_u32 v0, v14, v0, s31
	v_bfe_u32 v3, v15, 16, 1
	v_lshrrev_b32_e32 v0, 16, v0
	v_add3_u32 v3, v15, v3, s31
	v_add_u32_e32 v14, s15, v10
	v_and_or_b32 v6, v3, s0, v0
	s_waitcnt lgkmcnt(0)
	v_ashrrev_i32_e32 v15, 31, v14
	v_lshlrev_b64 v[14:15], 7, v[14:15]
	v_lshl_add_u64 v[14:15], s[4:5], 0, v[14:15]
	s_ashr_i32 s15, s14, 31
	v_cvt_pk_bf16_f32 v7, v16, v17
	v_lshl_add_u64 v[14:15], s[14:15], 1, v[14:15]
	v_mov_b32_e32 v3, v1
	v_lshl_add_u64 v[14:15], v[14:15], 0, v[2:3]
	global_store_dwordx4 v[14:15], v[4:7], off
	s_barrier
	s_add_i32 s18, s2, s18
	s_cmp_lt_i32 s18, 16
	s_cbranch_scc0 .LBB0_1079

; #define LAS __attribute__((address_space(3)))
; DI unsigned pk2(float lo, float hi) { return f2bf(lo) | (f2bf(hi) << 16); }
; #define BIDX() sgpr_opaque((int)__builtin_amdgcn_workgroup_id_x())
; #define GDIM() sgpr_opaque((int)__ockl_get_num_groups(0))
; DI int tid_opaque() { int t = threadIdx.x; asm volatile("" : "+v"(t)); return t; }
; DI void transpose_tiles(const float* src, int ldw, int Ks, bf16_t* dst, int Nn, int Kd, int kind, LAS float* tile) {
;     const int tid = tid_opaque(), ntn = Nn / 64, ntk = Kd / 64;
;     for (int it = BIDX(); it < ntn * ntk; it += GDIM()) {
;         const int n0 = (it % ntn) * 64, k0 = (it / ntn) * 64;
;         { const int nn = tid & 63, kk = tid >> 6; const int off = colmap(kind, n0 + nn);
; #pragma unroll
;           for (int i = 0; i < 8; ++i) { const int k = k0 + kk + 8 * i; float v = 0.f; if (off >= 0 && k < Ks) v = src[(size_t)k * ldw + off]; tile[(kk + 8 * i) * 65 + nn] = v; } }
;         __syncthreads();
;         { const int nn = tid >> 3, kc = tid & 7; const LAS float* s = tile + (kc * 8) * 65 + nn;
;           u32x4 o; o.x = pk2(s[0], s[65]); o.y = pk2(s[2 * 65], s[3 * 65]); o.z = pk2(s[4 * 65], s[5 * 65]); o.w = pk2(s[6 * 65], s[7 * 65]);
;           *(u32x4*)(dst + (size_t)(n0 + nn) * Kd + k0 + kc * 8) = o; }
;         __syncthreads();
.LBB0_1081:
	s_or_b64 exec, exec, s[2:3]
	s_waitcnt vmcnt(0)
	ds_write_b32 v12, v100
	ds_write_b32 v12, v101 offset:2080
	ds_write_b32 v12, v102 offset:4160
	ds_write_b32 v12, v103 offset:6240
	ds_write_b32 v12, v104 offset:8320
	ds_write_b32 v12, v105 offset:10400
	ds_write_b32 v12, v106 offset:12480
	ds_write_b32 v12, v107 offset:14560
	s_waitcnt lgkmcnt(0)
	s_barrier
	ds_read2_b32 v[4:5], v11 offset1:65
	ds_read2_b32 v[6:7], v11 offset0:130 offset1:195
	s_movk_i32 s2, 0x180
	s_waitcnt lgkmcnt(1)
	v_cvt_pk_bf16_f32 v4, v4, v5
	v_add_u32_e32 v3, 0x400, v11
	ds_read2_b32 v[14:15], v3 offset0:4 offset1:69
	s_waitcnt lgkmcnt(1)
	ds_read2_b32 v[16:17], v3 offset0:134 offset1:199
	v_cvt_pk_bf16_f32 v5, v6, v7
	s_waitcnt lgkmcnt(1)
	v_cvt_pk_bf16_f32 v6, v14, v15
	s_waitcnt lgkmcnt(0)
	v_cvt_pk_bf16_f32 v7, v16, v17
	v_add_u32_e32 v0, s15, v10
	v_mov_b64_e32 v[14:15], s[12:13]
	v_mad_i64_i32 v[14:15], s[2:3], v0, s2, v[14:15]
	s_ashr_i32 s15, s14, 31
	v_lshl_add_u64 v[14:15], s[14:15], 1, v[14:15]
	v_mov_b32_e32 v3, v1
	v_lshl_add_u64 v[14:15], v[14:15], 0, v[2:3]
	s_mov_b32 s2, s30
	global_store_dwordx4 v[14:15], v[4:7], off
	s_barrier
	s_add_i32 s18, s2, s18
	s_cmp_lt_i32 s18, 48
	s_cbranch_scc0 .LBB0_1098

; #define LAS __attribute__((address_space(3)))
; DI unsigned pk2(float lo, float hi) { return f2bf(lo) | (f2bf(hi) << 16); }
; #define BIDX() sgpr_opaque((int)__builtin_amdgcn_workgroup_id_x())
; #define GDIM() sgpr_opaque((int)__ockl_get_num_groups(0))
; DI int tid_opaque() { int t = threadIdx.x; asm volatile("" : "+v"(t)); return t; }
; DI void transpose_tiles(const float* src, int ldw, int Ks, bf16_t* dst, int Nn, int Kd, int kind, LAS float* tile) {
;     const int tid = tid_opaque(), ntn = Nn / 64, ntk = Kd / 64;
;     for (int it = BIDX(); it < ntn * ntk; it += GDIM()) {
;         const int n0 = (it % ntn) * 64, k0 = (it / ntn) * 64;
;         { const int nn = tid & 63, kk = tid >> 6; const int off = colmap(kind, n0 + nn);
; #pragma unroll
;           for (int i = 0; i < 8; ++i) { const int k = k0 + kk + 8 * i; float v = 0.f; if (off >= 0 && k < Ks) v = src[(size_t)k * ldw + off]; tile[(kk + 8 * i) * 65 + nn] = v; } }
;         __syncthreads();
;         { const int nn = tid >> 3, kc = tid & 7; const LAS float* s = tile + (kc * 8) * 65 + nn;
;           u32x4 o; o.x = pk2(s[0], s[65]); o.y = pk2(s[2 * 65], s[3 * 65]); o.z = pk2(s[4 * 65], s[5 * 65]); o.w = pk2(s[6 * 65], s[7 * 65]);
;           *(u32x4*)(dst + (size_t)(n0 + nn) * Kd + k0 + kc * 8) = o; }
;         __syncthreads();
.LBB0_1100:
	s_or_b64 exec, exec, s[2:3]
	s_waitcnt vmcnt(0)
	ds_write_b32 v12, v100
	ds_write_b32 v12, v101 offset:2080
	ds_write_b32 v12, v102 offset:4160
	ds_write_b32 v12, v103 offset:6240
	ds_write_b32 v12, v104 offset:8320
	ds_write_b32 v12, v105 offset:10400
	ds_write_b32 v12, v106 offset:12480
	ds_write_b32 v12, v107 offset:14560
	s_waitcnt lgkmcnt(0)
	s_barrier
	ds_read2_b32 v[4:5], v11 offset1:65
	ds_read2_b32 v[6:7], v11 offset0:130 offset1:195
	s_mov_b32 s2, s30
	s_waitcnt lgkmcnt(1)
	v_cvt_pk_bf16_f32 v4, v4, v5
	v_add_u32_e32 v3, 0x400, v11
	ds_read2_b32 v[14:15], v3 offset0:4 offset1:69
	s_waitcnt lgkmcnt(1)
	ds_read2_b32 v[16:17], v3 offset0:134 offset1:199
	v_cvt_pk_bf16_f32 v5, v6, v7
	s_waitcnt lgkmcnt(1)
	v_bfe_u32 v0, v14, 16, 1
	v_add3_u32 v0, v14, v0, s31
	v_bfe_u32 v3, v15, 16, 1
	v_lshrrev_b32_e32 v0, 16, v0
	v_add3_u32 v3, v15, v3, s31
	v_add_u32_e32 v14, s13, v10
	v_and_or_b32 v6, v3, s0, v0
	s_waitcnt lgkmcnt(0)
	v_ashrrev_i32_e32 v15, 31, v14
	v_lshlrev_b64 v[14:15], 11, v[14:15]
	v_lshl_add_u64 v[14:15], s[10:11], 0, v[14:15]
	s_ashr_i32 s13, s12, 31
	v_cvt_pk_bf16_f32 v7, v16, v17
	v_lshl_add_u64 v[14:15], s[12:13], 1, v[14:15]
	v_mov_b32_e32 v3, v1
	v_lshl_add_u64 v[14:15], v[14:15], 0, v[2:3]
	global_store_dwordx4 v[14:15], v[4:7], off
	s_barrier
	s_add_i32 s16, s2, s16
	s_cmpk_lt_i32 s16, 0x100
	s_cbranch_scc0 .LBB0_824

; #define LAS __attribute__((address_space(3)))
; #define IN(k) ((const float*)kload(8 * (k)))
; DI unsigned pk2(float lo, float hi) { return f2bf(lo) | (f2bf(hi) << 16); }
; #define BIDX() sgpr_opaque((int)__builtin_amdgcn_workgroup_id_x())
; #define GDIM() sgpr_opaque((int)__ockl_get_num_groups(0))
; DI int tid_opaque() { int t = threadIdx.x; asm volatile("" : "+v"(t)); return t; }
; DI void transpose_tiles(const float* src, int ldw, int Ks, bf16_t* dst, int Nn, int Kd, int kind, LAS float* tile) {
;     const int tid = tid_opaque(), ntn = Nn / 64, ntk = Kd / 64;
;     for (int it = BIDX(); it < ntn * ntk; it += GDIM()) {
;         const int n0 = (it % ntn) * 64, k0 = (it / ntn) * 64;
;         { const int nn = tid & 63, kk = tid >> 6; const int off = colmap(kind, n0 + nn);
; #pragma unroll
;           for (int i = 0; i < 8; ++i) { const int k = k0 + kk + 8 * i; float v = 0.f; if (off >= 0 && k < Ks) v = src[(size_t)k * ldw + off]; tile[(kk + 8 * i) * 65 + nn] = v; } }
;         __syncthreads();
;         { const int nn = tid >> 3, kc = tid & 7; const LAS float* s = tile + (kc * 8) * 65 + nn;
;           u32x4 o; o.x = pk2(s[0], s[65]); o.y = pk2(s[2 * 65], s[3 * 65]); o.z = pk2(s[4 * 65], s[5 * 65]); o.w = pk2(s[6 * 65], s[7 * 65]);
;           *(u32x4*)(dst + (size_t)(n0 + nn) * Kd + k0 + kc * 8) = o; }
;         __syncthreads();
; DI void phase_setup(LAS unsigned char* lds) {
;     ...
;     for (int l = 0; l < 4; ++l) {
;         transpose_tiles(IN(8) + (size_t)l * D * FF, FF, D, (bf16_t*)(ws + W_M1_T) + (size_t)l * FF * D, FF, D, 0, tile);
;         transpose_tiles(IN(9) + (size_t)l * FF * D, D, FF, (bf16_t*)(ws + W_M2_T) + (size_t)l * D * FF, D, FF, 0, tile);
.LBB0_1121:
	s_or_b64 exec, exec, s[2:3]
	s_waitcnt vmcnt(0)
	ds_write_b32 v12, v100
	ds_write_b32 v12, v101 offset:2080
	ds_write_b32 v12, v102 offset:4160
	ds_write_b32 v12, v103 offset:6240
	ds_write_b32 v12, v104 offset:8320
	ds_write_b32 v12, v105 offset:10400
	ds_write_b32 v12, v106 offset:12480
	ds_write_b32 v12, v107 offset:14560
	s_waitcnt lgkmcnt(0)
	s_barrier
	ds_read2_b32 v[4:5], v11 offset1:65
	ds_read2_b32 v[6:7], v11 offset0:130 offset1:195
	s_mov_b32 s2, s30
	s_waitcnt lgkmcnt(1)
	v_cvt_pk_bf16_f32 v4, v4, v5
	v_add_u32_e32 v3, 0x400, v11
	ds_read2_b32 v[14:15], v3 offset0:4 offset1:69
	s_waitcnt lgkmcnt(1)
	ds_read2_b32 v[16:17], v3 offset0:134 offset1:199
	v_cvt_pk_bf16_f32 v5, v6, v7
	s_waitcnt lgkmcnt(1)
	v_bfe_u32 v0, v14, 16, 1
	v_add3_u32 v0, v14, v0, s31
	v_bfe_u32 v3, v15, 16, 1
	v_lshrrev_b32_e32 v0, 16, v0
	v_add3_u32 v3, v15, v3, s31
	v_add_u32_e32 v14, s9, v10
	v_and_or_b32 v6, v3, s0, v0
	s_waitcnt lgkmcnt(0)
	v_ashrrev_i32_e32 v15, 31, v14
	v_lshlrev_b64 v[14:15], 11, v[14:15]
	v_lshl_add_u64 v[14:15], s[6:7], 0, v[14:15]
	s_ashr_i32 s9, s8, 31
	v_cvt_pk_bf16_f32 v7, v16, v17
	v_lshl_add_u64 v[14:15], s[8:9], 1, v[14:15]
	v_mov_b32_e32 v3, v1
	v_lshl_add_u64 v[14:15], v[14:15], 0, v[2:3]
	global_store_dwordx4 v[14:15], v[4:7], off
	s_barrier
	s_add_i32 s17, s2, s17
	s_cmpk_lt_i32 s17, 0x400
	s_cbranch_scc0 .LBB0_1138

; #define LAS __attribute__((address_space(3)))
; #define IN(k) ((const float*)kload(8 * (k)))
; DI unsigned pk2(float lo, float hi) { return f2bf(lo) | (f2bf(hi) << 16); }
; #define BIDX() sgpr_opaque((int)__builtin_amdgcn_workgroup_id_x())
; #define GDIM() sgpr_opaque((int)__ockl_get_num_groups(0))
; DI int tid_opaque() { int t = threadIdx.x; asm volatile("" : "+v"(t)); return t; }
; DI void transpose_tiles(const float* src, int ldw, int Ks, bf16_t* dst, int Nn, int Kd, int kind, LAS float* tile) {
;     const int tid = tid_opaque(), ntn = Nn / 64, ntk = Kd / 64;
;     for (int it = BIDX(); it < ntn * ntk; it += GDIM()) {
;         const int n0 = (it % ntn) * 64, k0 = (it / ntn) * 64;
;         { const int nn = tid & 63, kk = tid >> 6; const int off = colmap(kind, n0 + nn);
; #pragma unroll
;           for (int i = 0; i < 8; ++i) { const int k = k0 + kk + 8 * i; float v = 0.f; if (off >= 0 && k < Ks) v = src[(size_t)k * ldw + off]; tile[(kk + 8 * i) * 65 + nn] = v; } }
;         __syncthreads();
;         { const int nn = tid >> 3, kc = tid & 7; const LAS float* s = tile + (kc * 8) * 65 + nn;
;           u32x4 o; o.x = pk2(s[0], s[65]); o.y = pk2(s[2 * 65], s[3 * 65]); o.z = pk2(s[4 * 65], s[5 * 65]); o.w = pk2(s[6 * 65], s[7 * 65]);
;           *(u32x4*)(dst + (size_t)(n0 + nn) * Kd + k0 + kc * 8) = o; }
;         __syncthreads();
; DI void phase_setup(LAS unsigned char* lds) {
;     ...
;     for (int l = 0; l < 4; ++l) {
;         transpose_tiles(IN(8) + (size_t)l * D * FF, FF, D, (bf16_t*)(ws + W_M1_T) + (size_t)l * FF * D, FF, D, 0, tile);
;         transpose_tiles(IN(9) + (size_t)l * FF * D, D, FF, (bf16_t*)(ws + W_M2_T) + (size_t)l * D * FF, D, FF, 0, tile);
.LBB0_1140:
	s_or_b64 exec, exec, s[2:3]
	s_waitcnt vmcnt(0)
	ds_write_b32 v12, v100
	ds_write_b32 v12, v101 offset:2080
	ds_write_b32 v12, v102 offset:4160
	ds_write_b32 v12, v103 offset:6240
	ds_write_b32 v12, v104 offset:8320
	ds_write_b32 v12, v105 offset:10400
	ds_write_b32 v12, v106 offset:12480
	ds_write_b32 v12, v107 offset:14560
	s_waitcnt lgkmcnt(0)
	s_barrier
	ds_read2_b32 v[4:5], v11 offset1:65
	ds_read2_b32 v[6:7], v11 offset0:130 offset1:195
	s_mov_b32 s2, s30
	s_waitcnt lgkmcnt(1)
	v_cvt_pk_bf16_f32 v4, v4, v5
	v_add_u32_e32 v3, 0x400, v11
	ds_read2_b32 v[14:15], v3 offset0:4 offset1:69
	s_waitcnt lgkmcnt(1)
	ds_read2_b32 v[16:17], v3 offset0:134 offset1:199
	v_cvt_pk_bf16_f32 v5, v6, v7
	s_waitcnt lgkmcnt(1)
	v_bfe_u32 v0, v14, 16, 1
	v_add3_u32 v0, v14, v0, s31
	v_bfe_u32 v3, v15, 16, 1
	v_lshrrev_b32_e32 v0, 16, v0
	v_add3_u32 v3, v15, v3, s31
	v_add_u32_e32 v14, s9, v10
	v_and_or_b32 v6, v3, s0, v0
	s_waitcnt lgkmcnt(0)
	v_ashrrev_i32_e32 v15, 31, v14
	v_lshlrev_b64 v[14:15], 13, v[14:15]
	v_lshl_add_u64 v[14:15], s[6:7], 0, v[14:15]
	s_ashr_i32 s9, s8, 31
	v_cvt_pk_bf16_f32 v7, v16, v17
	v_lshl_add_u64 v[14:15], s[8:9], 1, v[14:15]
	v_mov_b32_e32 v3, v1
	v_lshl_add_u64 v[14:15], v[14:15], 0, v[2:3]
	global_store_dwordx4 v[14:15], v[4:7], off
	s_barrier
	s_add_i32 s17, s2, s17
	s_cmpk_lt_i32 s17, 0x400
	s_cbranch_scc0 .LBB0_1118
